# pipelined norm rows + hyena LDS-read hoisting (on top of batched epilogues, supertile gu)
# speedup vs baseline: 1.0651x; 1.0142x over previous
; #define TIDX opaque_tid()
; DI void phase_norm(const Params& p, char* wsb, int layer, int which, int mrows, bool do_convert, char* lds) {
;   const int tid = TIDX, lane = tid & 63, wid = tid >> 6;
;   const float* xs = (const float*)(wsb + OFF_XS);
;   u16* H = (u16*)(wsb + OFF_H);
;   const float* mods = (const float*)(wsb + OFF_MODS) + (size_t)layer * 9 * 9216;
;   const float* g = p.norm_g + (layer * 3 + which) * 1024;
;   const int nw = gridDim.x * 4;
; #pragma unroll 2
;   for (int row = blockIdx.x * 4 + wid; row < mrows; row += nw) {
;     const float4* xr = (const float4*)(xs + (size_t)row * 1024);
;     float4 v[4];
;     float ss = 0.f;
; #pragma unroll
;     for (int i = 0; i < 4; ++i) { v[i] = xr[lane + 64 * i]; ss += v[i].x * v[i].x + v[i].y * v[i].y + v[i].z * v[i].z + v[i].w * v[i].w; }
; #pragma unroll
;     for (int o = 32; o; o >>= 1) ss += __shfl_xor(ss, o);
;     const float r = rsqrtf(ss * (1.f / 1024.f) + 1e-6f);
.LBB0_342:
	s_mov_b32 s10, s19
	v_mov_b32_e32 v0, v178
	s_mov_b32 s9, s19
	s_mov_b64 s[54:55], s[26:27]
	s_add_u32 s12, s54, s10
	v_ashrrev_i32_e32 v2, 6, v0
	v_readlane_b32 s34, v243, 61
	v_add_u32_e32 v6, s87, v2
	s_movk_i32 s6, 0x4800
	v_writelane_b32 v242, s8, 0
	s_mov_b64 s[48:49], s[20:21]
	s_addc_u32 s13, s55, 0
	v_readlane_b32 s35, v243, 62
	v_cmp_gt_i32_e32 vcc, s6, v6
	v_writelane_b32 v242, s9, 1
	s_mul_i32 s6, s8, 0x51000
	s_mov_b64 s[52:53], s[24:25]
	s_mov_b64 s[50:51], s[22:23]
	v_writelane_b32 v242, s6, 2
	s_and_saveexec_b64 s[6:7], vcc
	s_movk_i32 s41, 0x47ff
	s_mov_b64 s[48:49], 0x1000
	s_cbranch_execz .LBB0_345
	v_readlane_b32 s8, v242, 0
	v_readlane_b32 s9, v242, 1
	s_mul_i32 s18, s8, 0xc00
	s_mul_hi_u32 s11, s8, 0x51000
	s_lshl_b64 s[8:9], s[18:19], 2
	v_readlane_b32 s64, v243, 37
	v_readlane_b32 s65, v243, 38
	s_add_u32 s14, s64, s8
	s_addc_u32 s15, s65, s9
	v_readlane_b32 s8, v242, 2
	s_add_u32 s8, s12, s8
	v_cmp_lt_i32_e32 vcc, v187, v186
	s_addc_u32 s9, s13, s11
	v_and_b32_e32 v3, 63, v0
	v_cndmask_b32_e32 v4, v185, v187, vcc
	v_cmp_lt_i32_e32 vcc, v188, v186
	s_add_u32 s8, s8, 0x4000
	v_lshlrev_b32_e32 v26, 2, v4
	v_cndmask_b32_e32 v4, v185, v188, vcc
	v_cmp_lt_i32_e32 vcc, v189, v186
	s_addc_u32 s9, s9, 0
	v_lshlrev_b32_e32 v0, 4, v3
	v_lshlrev_b32_e32 v27, 2, v4
	v_cndmask_b32_e32 v4, v185, v189, vcc
	v_cmp_lt_i32_e32 vcc, v190, v186
	v_readlane_b32 s11, v243, 1
	v_lshl_add_u64 v[8:9], s[14:15], 0, v[0:1]
	v_lshlrev_b32_e32 v28, 2, v4
	v_cndmask_b32_e32 v4, v185, v190, vcc
	v_cmp_lt_i32_e32 vcc, v191, v186
	s_add_u32 s14, s11, s10
	v_readlane_b32 s11, v243, 2
	v_lshlrev_b32_e32 v29, 2, v4
	v_cndmask_b32_e32 v4, v185, v191, vcc
	v_cmp_lt_i32_e32 vcc, v192, v186
	v_ashrrev_i32_e32 v7, 31, v6
	s_addc_u32 s15, s11, 0
	v_readlane_b32 s11, v243, 3
	v_lshlrev_b32_e32 v2, 2, v3
	v_lshlrev_b32_e32 v30, 2, v4
	v_cndmask_b32_e32 v4, v185, v192, vcc
	v_lshlrev_b64 v[10:11], 12, v[6:7]
	v_lshlrev_b64 v[12:13], 11, v[6:7]
	s_add_u32 s10, s11, s10
	v_readlane_b32 s11, v243, 4
	v_lshlrev_b32_e32 v31, 2, v4
	v_or_b32_e32 v4, 0x100, v2
	v_or_b32_e32 v16, 0x200, v2
	v_or_b32_e32 v18, 0x300, v2
	v_or_b32_e32 v10, v10, v0
	v_lshl_or_b32 v12, v3, 3, v12
	s_addc_u32 s11, s11, 0
	v_lshl_add_u64 v[10:11], s[14:15], 0, v[10:11]
	v_lshl_add_u64 v[12:13], s[10:11], 0, v[12:13]
	s_mov_b64 s[10:11], 0
	v_lshlrev_b32_e32 v0, 2, v2
	v_lshlrev_b32_e32 v14, 2, v4
	v_mov_b32_e32 v15, v1
	v_lshlrev_b32_e32 v16, 2, v16
	v_mov_b32_e32 v17, v1
	v_lshlrev_b32_e32 v18, 2, v18
	v_mov_b32_e32 v19, v1
	v_readlane_b32 s66, v243, 39
	v_readlane_b32 s67, v243, 40
	v_readlane_b32 s68, v243, 41
	v_readlane_b32 s69, v243, 42
	v_readlane_b32 s70, v243, 43
	v_readlane_b32 s71, v243, 44
	s_cmpk_lg_u32 s92, 0x200
	s_cbranch_scc1 .LBB0_344
	global_load_dwordx4 v[138:141], v[8:9], off
	global_load_dwordx4 v[142:145], v[8:9], off offset:1024
	global_load_dwordx4 v[246:249], v[8:9], off offset:2048
	global_load_dwordx4 v[250:253], v[8:9], off offset:3072
	s_mov_b64 s[64:65], s[8:9]
	s_add_u32 s66, s8, 0x1000
	s_addc_u32 s67, s9, 0
	global_load_dwordx4 v[64:67], v[10:11], off offset:-2048
	global_load_dwordx4 v[68:71], v[10:11], off offset:-1024
	global_load_dwordx4 v[72:75], v[10:11], off
	global_load_dwordx4 v[76:79], v[10:11], off offset:1024
	v_lshl_add_u64 v[10:11], v[10:11], 0, s[34:35]
	global_load_dwordx4 v[80:83], v0, s[64:65]
	global_load_dwordx4 v[84:87], v0, s[64:65] offset:1024
	global_load_dwordx4 v[88:91], v0, s[64:65] offset:2048
	global_load_dwordx4 v[92:95], v0, s[64:65] offset:3072
	global_load_dwordx4 v[96:99], v0, s[66:67]
	global_load_dwordx4 v[100:103], v0, s[66:67] offset:1024
	global_load_dwordx4 v[104:107], v0, s[66:67] offset:2048
	global_load_dwordx4 v[108:111], v0, s[66:67] offset:3072
	s_add_u32 s64, s64, 0x9000
	s_addc_u32 s65, s65, 0
	s_add_u32 s66, s66, 0x9000
	s_addc_u32 s67, s67, 0
	global_load_dwordx4 v[214:217], v[10:11], off offset:-2048
	global_load_dwordx4 v[218:221], v[10:11], off offset:-1024
	global_load_dwordx4 v[222:225], v[10:11], off
	global_load_dwordx4 v[226:229], v[10:11], off offset:1024
	v_lshl_add_u64 v[10:11], v[10:11], 0, s[34:35]
	global_load_dwordx4 v[112:115], v0, s[64:65]
	global_load_dwordx4 v[116:119], v0, s[64:65] offset:1024
	global_load_dwordx4 v[120:123], v0, s[64:65] offset:2048
	global_load_dwordx4 v[126:129], v0, s[64:65] offset:3072
	global_load_dwordx4 v[230:233], v0, s[66:67]
	global_load_dwordx4 v[234:237], v0, s[66:67] offset:1024
	global_load_dwordx4 v[238:241], v0, s[66:67] offset:2048
	global_load_dwordx4 v[134:137], v0, s[66:67] offset:3072
	s_add_u32 s64, s64, 0x9000
	s_addc_u32 s65, s65, 0
	s_add_u32 s66, s66, 0x9000
	s_addc_u32 s67, s67, 0
	s_waitcnt vmcnt(12)
	v_mul_f32_e32 v37, v65, v65
	v_fmac_f32_e32 v37, v64, v64
	v_fmac_f32_e32 v37, v66, v66
	v_fmac_f32_e32 v37, v67, v67
	v_mul_f32_e32 v38, v69, v69
	v_fmac_f32_e32 v38, v68, v68
	v_fmac_f32_e32 v38, v70, v70
	v_fmac_f32_e32 v38, v71, v71
	v_mul_f32_e32 v39, v73, v73
	v_fmac_f32_e32 v39, v72, v72
	v_fmac_f32_e32 v39, v74, v74
	v_fmac_f32_e32 v39, v75, v75
	v_mul_f32_e32 v40, v77, v77
	v_fmac_f32_e32 v40, v76, v76
	v_fmac_f32_e32 v40, v78, v78
	v_fmac_f32_e32 v40, v79, v79
	v_add_f32_e32 v255, v37, v38
	v_add_f32_e32 v255, v255, v39
	v_add_f32_e32 v255, v255, v40
	ds_bpermute_b32 v254, v26, v255
	s_waitcnt lgkmcnt(0)
	v_add_f32_e32 v255, v255, v254
	ds_bpermute_b32 v254, v27, v255
	s_waitcnt lgkmcnt(0)
	v_add_f32_e32 v255, v255, v254
	ds_bpermute_b32 v254, v28, v255
	s_waitcnt lgkmcnt(0)
	v_add_f32_e32 v255, v255, v254
	ds_bpermute_b32 v254, v29, v255
	s_waitcnt lgkmcnt(0)
	v_add_f32_e32 v255, v255, v254
	ds_bpermute_b32 v254, v30, v255
	s_waitcnt lgkmcnt(0)
; DI void phase_norm(const Params& p, char* wsb, int layer, int which, int mrows, bool do_convert, char* lds) {
;     ...
;   for (int row = blockIdx.x * 4 + wid; row < mrows; row += nw) {
;     const float4* xr = (const float4*)(xs + (size_t)row * 1024);
;     float4 v[4];
;     float ss = 0.f;
; #pragma unroll
;     for (int i = 0; i < 4; ++i) { v[i] = xr[lane + 64 * i]; ss += v[i].x * v[i].x + v[i].y * v[i].y + v[i].z * v[i].z + v[i].w * v[i].w; }
; #pragma unroll
;     for (int o = 32; o; o >>= 1) ss += __shfl_xor(ss, o);
;     const float r = rsqrtf(ss * (1.f / 1024.f) + 1e-6f);
;     const int mr = row < TL ? (row >> 11) : 8;
;     const float* sh = mods + (size_t)mr * 9216 + (3 * which) * 1024;
;     const float* sc = sh + 1024;
; #pragma unroll
;     for (int i = 0; i < 4; ++i) {
;       int col = (lane + 64 * i) * 4;
;       float4 gg = *(const float4*)(g + col), s4 = *(const float4*)(sh + col), c4 = *(const float4*)(sc + col);
;       float o0 = v[i].x * r * gg.x * (1.f + c4.x) + s4.x;
;       float o1 = v[i].y * r * gg.y * (1.f + c4.y) + s4.y;
;       float o2 = v[i].z * r * gg.z * (1.f + c4.z) + s4.z;
;       float o3 = v[i].w * r * gg.w * (1.f + c4.w) + s4.w;
;       *(uint2*)(H + (size_t)row * 1024 + col) = make_uint2(pack2(o0, o1), pack2(o2, o3));
;     }
	v_add_f32_e32 v255, v255, v254
	ds_bpermute_b32 v254, v31, v255
	s_waitcnt lgkmcnt(0)
	v_add_f32_e32 v255, v255, v254
	v_fmamk_f32 v255, v255, 0x3a800000, v179
	v_cmp_gt_f32_e32 vcc, s40, v255
	v_mul_f32_e32 v254, 0x4b800000, v255
	s_nop 0
	v_cndmask_b32_e32 v255, v255, v254, vcc
	v_rsq_f32_e32 v255, v255
	s_nop 0
	v_mul_f32_e32 v254, 0x45800000, v255
	v_cndmask_b32_e32 v56, v255, v254, vcc
	s_nop 0
	v_pk_mul_f32 v[64:65], v[64:65], v[56:57] op_sel_hi:[1,0]
	v_pk_mul_f32 v[66:67], v[66:67], v[56:57] op_sel_hi:[1,0]
	v_pk_add_f32 v[96:97], v[96:97], 1.0 op_sel_hi:[1,0]
	v_pk_add_f32 v[98:99], v[98:99], 1.0 op_sel_hi:[1,0]
	v_pk_mul_f32 v[64:65], v[138:139], v[64:65]
	v_pk_mul_f32 v[66:67], v[140:141], v[66:67]
	v_pk_fma_f32 v[64:65], v[96:97], v[64:65], v[80:81]
	v_pk_fma_f32 v[66:67], v[98:99], v[66:67], v[82:83]
	v_cvt_pk_bf16_f32 v58, v64, v65
	v_cvt_pk_bf16_f32 v59, v66, v67
	global_store_dwordx2 v[12:13], v[58:59], off offset:-1024
	v_pk_mul_f32 v[68:69], v[68:69], v[56:57] op_sel_hi:[1,0]
	v_pk_mul_f32 v[70:71], v[70:71], v[56:57] op_sel_hi:[1,0]
	v_pk_add_f32 v[100:101], v[100:101], 1.0 op_sel_hi:[1,0]
	v_pk_add_f32 v[102:103], v[102:103], 1.0 op_sel_hi:[1,0]
	v_pk_mul_f32 v[68:69], v[142:143], v[68:69]
	v_pk_mul_f32 v[70:71], v[144:145], v[70:71]
	v_pk_fma_f32 v[68:69], v[100:101], v[68:69], v[84:85]
	v_pk_fma_f32 v[70:71], v[102:103], v[70:71], v[86:87]
	v_cvt_pk_bf16_f32 v60, v68, v69
	v_cvt_pk_bf16_f32 v61, v70, v71
	global_store_dwordx2 v[12:13], v[60:61], off offset:-512
	v_pk_mul_f32 v[72:73], v[72:73], v[56:57] op_sel_hi:[1,0]
	v_pk_mul_f32 v[74:75], v[74:75], v[56:57] op_sel_hi:[1,0]
	v_pk_add_f32 v[104:105], v[104:105], 1.0 op_sel_hi:[1,0]
	v_pk_add_f32 v[106:107], v[106:107], 1.0 op_sel_hi:[1,0]
	v_pk_mul_f32 v[72:73], v[246:247], v[72:73]
	v_pk_mul_f32 v[74:75], v[248:249], v[74:75]
	v_pk_fma_f32 v[72:73], v[104:105], v[72:73], v[88:89]
	v_pk_fma_f32 v[74:75], v[106:107], v[74:75], v[90:91]
	v_cvt_pk_bf16_f32 v58, v72, v73
	v_cvt_pk_bf16_f32 v59, v74, v75
	global_store_dwordx2 v[12:13], v[58:59], off
	v_pk_mul_f32 v[76:77], v[76:77], v[56:57] op_sel_hi:[1,0]
	v_pk_mul_f32 v[78:79], v[78:79], v[56:57] op_sel_hi:[1,0]
	v_pk_add_f32 v[108:109], v[108:109], 1.0 op_sel_hi:[1,0]
	v_pk_add_f32 v[110:111], v[110:111], 1.0 op_sel_hi:[1,0]
	v_pk_mul_f32 v[76:77], v[250:251], v[76:77]
	v_pk_mul_f32 v[78:79], v[252:253], v[78:79]
	v_pk_fma_f32 v[76:77], v[108:109], v[76:77], v[92:93]
	v_pk_fma_f32 v[78:79], v[110:111], v[78:79], v[94:95]
	v_cvt_pk_bf16_f32 v60, v76, v77
	v_cvt_pk_bf16_f32 v61, v78, v79
	global_store_dwordx2 v[12:13], v[60:61], off offset:512
	v_lshl_add_u64 v[12:13], v[12:13], 0, s[36:37]
	global_load_dwordx4 v[64:67], v[10:11], off offset:-2048
	global_load_dwordx4 v[68:71], v[10:11], off offset:-1024
	global_load_dwordx4 v[72:75], v[10:11], off
	global_load_dwordx4 v[76:79], v[10:11], off offset:1024
	v_lshl_add_u64 v[10:11], v[10:11], 0, s[34:35]
	global_load_dwordx4 v[80:83], v0, s[64:65]
	global_load_dwordx4 v[84:87], v0, s[64:65] offset:1024
	global_load_dwordx4 v[88:91], v0, s[64:65] offset:2048
	global_load_dwordx4 v[92:95], v0, s[64:65] offset:3072
	global_load_dwordx4 v[96:99], v0, s[66:67]
	global_load_dwordx4 v[100:103], v0, s[66:67] offset:1024
	global_load_dwordx4 v[104:107], v0, s[66:67] offset:2048
	global_load_dwordx4 v[108:111], v0, s[66:67] offset:3072
	s_add_u32 s64, s64, 0x9000
	s_addc_u32 s65, s65, 0
	s_add_u32 s66, s66, 0x9000
	s_addc_u32 s67, s67, 0
	s_waitcnt vmcnt(16)
	v_mul_f32_e32 v37, v215, v215
	v_fmac_f32_e32 v37, v214, v214
	v_fmac_f32_e32 v37, v216, v216
	v_fmac_f32_e32 v37, v217, v217
	v_mul_f32_e32 v38, v219, v219
	v_fmac_f32_e32 v38, v218, v218
	v_fmac_f32_e32 v38, v220, v220
	v_fmac_f32_e32 v38, v221, v221
	v_mul_f32_e32 v39, v223, v223
	v_fmac_f32_e32 v39, v222, v222
	v_fmac_f32_e32 v39, v224, v224
	v_fmac_f32_e32 v39, v225, v225
	v_mul_f32_e32 v40, v227, v227
	v_fmac_f32_e32 v40, v226, v226
	v_fmac_f32_e32 v40, v228, v228
	v_fmac_f32_e32 v40, v229, v229
	v_add_f32_e32 v255, v37, v38
	v_add_f32_e32 v255, v255, v39
	v_add_f32_e32 v255, v255, v40
	ds_bpermute_b32 v254, v26, v255
	s_waitcnt lgkmcnt(0)
	v_add_f32_e32 v255, v255, v254
	ds_bpermute_b32 v254, v27, v255
	s_waitcnt lgkmcnt(0)
	v_add_f32_e32 v255, v255, v254
	ds_bpermute_b32 v254, v28, v255
	s_waitcnt lgkmcnt(0)
	v_add_f32_e32 v255, v255, v254
	ds_bpermute_b32 v254, v29, v255
	s_waitcnt lgkmcnt(0)
	v_add_f32_e32 v255, v255, v254
	ds_bpermute_b32 v254, v30, v255
	s_waitcnt lgkmcnt(0)
	v_add_f32_e32 v255, v255, v254
	ds_bpermute_b32 v254, v31, v255
	s_waitcnt lgkmcnt(0)
; DI void phase_norm(const Params& p, char* wsb, int layer, int which, int mrows, bool do_convert, char* lds) {
;     ...
;   for (int row = blockIdx.x * 4 + wid; row < mrows; row += nw) {
;     const float4* xr = (const float4*)(xs + (size_t)row * 1024);
;     float4 v[4];
;     float ss = 0.f;
; #pragma unroll
;     for (int i = 0; i < 4; ++i) { v[i] = xr[lane + 64 * i]; ss += v[i].x * v[i].x + v[i].y * v[i].y + v[i].z * v[i].z + v[i].w * v[i].w; }
; #pragma unroll
;     for (int o = 32; o; o >>= 1) ss += __shfl_xor(ss, o);
;     const float r = rsqrtf(ss * (1.f / 1024.f) + 1e-6f);
;     const int mr = row < TL ? (row >> 11) : 8;
;     const float* sh = mods + (size_t)mr * 9216 + (3 * which) * 1024;
;     const float* sc = sh + 1024;
; #pragma unroll
;     for (int i = 0; i < 4; ++i) {
;       int col = (lane + 64 * i) * 4;
;       float4 gg = *(const float4*)(g + col), s4 = *(const float4*)(sh + col), c4 = *(const float4*)(sc + col);
;       float o0 = v[i].x * r * gg.x * (1.f + c4.x) + s4.x;
;       float o1 = v[i].y * r * gg.y * (1.f + c4.y) + s4.y;
;       float o2 = v[i].z * r * gg.z * (1.f + c4.z) + s4.z;
;       float o3 = v[i].w * r * gg.w * (1.f + c4.w) + s4.w;
;       *(uint2*)(H + (size_t)row * 1024 + col) = make_uint2(pack2(o0, o1), pack2(o2, o3));
;     }
	v_add_f32_e32 v255, v255, v254
	v_fmamk_f32 v255, v255, 0x3a800000, v179
	v_cmp_gt_f32_e32 vcc, s40, v255
	v_mul_f32_e32 v254, 0x4b800000, v255
	s_nop 0
	v_cndmask_b32_e32 v255, v255, v254, vcc
	v_rsq_f32_e32 v255, v255
	s_nop 0
	v_mul_f32_e32 v254, 0x45800000, v255
	v_cndmask_b32_e32 v56, v255, v254, vcc
	s_nop 0
	v_pk_mul_f32 v[214:215], v[214:215], v[56:57] op_sel_hi:[1,0]
	v_pk_mul_f32 v[216:217], v[216:217], v[56:57] op_sel_hi:[1,0]
	v_pk_add_f32 v[230:231], v[230:231], 1.0 op_sel_hi:[1,0]
	v_pk_add_f32 v[232:233], v[232:233], 1.0 op_sel_hi:[1,0]
	v_pk_mul_f32 v[214:215], v[138:139], v[214:215]
	v_pk_mul_f32 v[216:217], v[140:141], v[216:217]
	v_pk_fma_f32 v[214:215], v[230:231], v[214:215], v[112:113]
	v_pk_fma_f32 v[216:217], v[232:233], v[216:217], v[114:115]
	v_cvt_pk_bf16_f32 v58, v214, v215
	v_cvt_pk_bf16_f32 v59, v216, v217
	global_store_dwordx2 v[12:13], v[58:59], off offset:-1024
	v_pk_mul_f32 v[218:219], v[218:219], v[56:57] op_sel_hi:[1,0]
	v_pk_mul_f32 v[220:221], v[220:221], v[56:57] op_sel_hi:[1,0]
	v_pk_add_f32 v[234:235], v[234:235], 1.0 op_sel_hi:[1,0]
	v_pk_add_f32 v[236:237], v[236:237], 1.0 op_sel_hi:[1,0]
	v_pk_mul_f32 v[218:219], v[142:143], v[218:219]
	v_pk_mul_f32 v[220:221], v[144:145], v[220:221]
	v_pk_fma_f32 v[218:219], v[234:235], v[218:219], v[116:117]
	v_pk_fma_f32 v[220:221], v[236:237], v[220:221], v[118:119]
	v_cvt_pk_bf16_f32 v60, v218, v219
	v_cvt_pk_bf16_f32 v61, v220, v221
	global_store_dwordx2 v[12:13], v[60:61], off offset:-512
	v_pk_mul_f32 v[222:223], v[222:223], v[56:57] op_sel_hi:[1,0]
	v_pk_mul_f32 v[224:225], v[224:225], v[56:57] op_sel_hi:[1,0]
	v_pk_add_f32 v[238:239], v[238:239], 1.0 op_sel_hi:[1,0]
	v_pk_add_f32 v[240:241], v[240:241], 1.0 op_sel_hi:[1,0]
	v_pk_mul_f32 v[222:223], v[246:247], v[222:223]
	v_pk_mul_f32 v[224:225], v[248:249], v[224:225]
	v_pk_fma_f32 v[222:223], v[238:239], v[222:223], v[120:121]
	v_pk_fma_f32 v[224:225], v[240:241], v[224:225], v[122:123]
	v_cvt_pk_bf16_f32 v58, v222, v223
	v_cvt_pk_bf16_f32 v59, v224, v225
	global_store_dwordx2 v[12:13], v[58:59], off
	v_pk_mul_f32 v[226:227], v[226:227], v[56:57] op_sel_hi:[1,0]
	v_pk_mul_f32 v[228:229], v[228:229], v[56:57] op_sel_hi:[1,0]
	v_pk_add_f32 v[134:135], v[134:135], 1.0 op_sel_hi:[1,0]
	v_pk_add_f32 v[136:137], v[136:137], 1.0 op_sel_hi:[1,0]
	v_pk_mul_f32 v[226:227], v[250:251], v[226:227]
	v_pk_mul_f32 v[228:229], v[252:253], v[228:229]
	v_pk_fma_f32 v[226:227], v[134:135], v[226:227], v[126:127]
	v_pk_fma_f32 v[228:229], v[136:137], v[228:229], v[128:129]
	v_cvt_pk_bf16_f32 v60, v226, v227
	v_cvt_pk_bf16_f32 v61, v228, v229
	global_store_dwordx2 v[12:13], v[60:61], off offset:512
	v_lshl_add_u64 v[12:13], v[12:13], 0, s[36:37]
	global_load_dwordx4 v[214:217], v[10:11], off offset:-2048
	global_load_dwordx4 v[218:221], v[10:11], off offset:-1024
	global_load_dwordx4 v[222:225], v[10:11], off
	global_load_dwordx4 v[226:229], v[10:11], off offset:1024
	v_lshl_add_u64 v[10:11], v[10:11], 0, s[34:35]
	global_load_dwordx4 v[112:115], v0, s[64:65]
	global_load_dwordx4 v[116:119], v0, s[64:65] offset:1024
	global_load_dwordx4 v[120:123], v0, s[64:65] offset:2048
	global_load_dwordx4 v[126:129], v0, s[64:65] offset:3072
	global_load_dwordx4 v[230:233], v0, s[66:67]
	global_load_dwordx4 v[234:237], v0, s[66:67] offset:1024
	global_load_dwordx4 v[238:241], v0, s[66:67] offset:2048
	global_load_dwordx4 v[134:137], v0, s[66:67] offset:3072
	s_add_u32 s64, s64, 0x9000
	s_addc_u32 s65, s65, 0
	s_add_u32 s66, s66, 0x9000
	s_addc_u32 s67, s67, 0
	s_waitcnt vmcnt(16)
	v_mul_f32_e32 v37, v65, v65
	v_fmac_f32_e32 v37, v64, v64
	v_fmac_f32_e32 v37, v66, v66
	v_fmac_f32_e32 v37, v67, v67
	v_mul_f32_e32 v38, v69, v69
	v_fmac_f32_e32 v38, v68, v68
	v_fmac_f32_e32 v38, v70, v70
	v_fmac_f32_e32 v38, v71, v71
	v_mul_f32_e32 v39, v73, v73
	v_fmac_f32_e32 v39, v72, v72
	v_fmac_f32_e32 v39, v74, v74
	v_fmac_f32_e32 v39, v75, v75
	v_mul_f32_e32 v40, v77, v77
	v_fmac_f32_e32 v40, v76, v76
	v_fmac_f32_e32 v40, v78, v78
	v_fmac_f32_e32 v40, v79, v79
	v_add_f32_e32 v255, v37, v38
	v_add_f32_e32 v255, v255, v39
	v_add_f32_e32 v255, v255, v40
	ds_bpermute_b32 v254, v26, v255
	s_waitcnt lgkmcnt(0)
	v_add_f32_e32 v255, v255, v254
	ds_bpermute_b32 v254, v27, v255
	s_waitcnt lgkmcnt(0)
	v_add_f32_e32 v255, v255, v254
	ds_bpermute_b32 v254, v28, v255
	s_waitcnt lgkmcnt(0)
	v_add_f32_e32 v255, v255, v254
	ds_bpermute_b32 v254, v29, v255
	s_waitcnt lgkmcnt(0)
	v_add_f32_e32 v255, v255, v254
	ds_bpermute_b32 v254, v30, v255
	s_waitcnt lgkmcnt(0)
	v_add_f32_e32 v255, v255, v254
	ds_bpermute_b32 v254, v31, v255
	s_waitcnt lgkmcnt(0)
; DI void phase_norm(const Params& p, char* wsb, int layer, int which, int mrows, bool do_convert, char* lds) {
;     ...
;   for (int row = blockIdx.x * 4 + wid; row < mrows; row += nw) {
;     const float4* xr = (const float4*)(xs + (size_t)row * 1024);
;     float4 v[4];
;     float ss = 0.f;
; #pragma unroll
;     for (int i = 0; i < 4; ++i) { v[i] = xr[lane + 64 * i]; ss += v[i].x * v[i].x + v[i].y * v[i].y + v[i].z * v[i].z + v[i].w * v[i].w; }
; #pragma unroll
;     for (int o = 32; o; o >>= 1) ss += __shfl_xor(ss, o);
;     const float r = rsqrtf(ss * (1.f / 1024.f) + 1e-6f);
;     const int mr = row < TL ? (row >> 11) : 8;
;     const float* sh = mods + (size_t)mr * 9216 + (3 * which) * 1024;
;     const float* sc = sh + 1024;
; #pragma unroll
;     for (int i = 0; i < 4; ++i) {
;       int col = (lane + 64 * i) * 4;
;       float4 gg = *(const float4*)(g + col), s4 = *(const float4*)(sh + col), c4 = *(const float4*)(sc + col);
;       float o0 = v[i].x * r * gg.x * (1.f + c4.x) + s4.x;
;       float o1 = v[i].y * r * gg.y * (1.f + c4.y) + s4.y;
;       float o2 = v[i].z * r * gg.z * (1.f + c4.z) + s4.z;
;       float o3 = v[i].w * r * gg.w * (1.f + c4.w) + s4.w;
;       *(uint2*)(H + (size_t)row * 1024 + col) = make_uint2(pack2(o0, o1), pack2(o2, o3));
;     }
	v_add_f32_e32 v255, v255, v254
	v_fmamk_f32 v255, v255, 0x3a800000, v179
	v_cmp_gt_f32_e32 vcc, s40, v255
	v_mul_f32_e32 v254, 0x4b800000, v255
	s_nop 0
	v_cndmask_b32_e32 v255, v255, v254, vcc
	v_rsq_f32_e32 v255, v255
	s_nop 0
	v_mul_f32_e32 v254, 0x45800000, v255
	v_cndmask_b32_e32 v56, v255, v254, vcc
	s_nop 0
	v_pk_mul_f32 v[64:65], v[64:65], v[56:57] op_sel_hi:[1,0]
	v_pk_mul_f32 v[66:67], v[66:67], v[56:57] op_sel_hi:[1,0]
	v_pk_add_f32 v[96:97], v[96:97], 1.0 op_sel_hi:[1,0]
	v_pk_add_f32 v[98:99], v[98:99], 1.0 op_sel_hi:[1,0]
	v_pk_mul_f32 v[64:65], v[138:139], v[64:65]
	v_pk_mul_f32 v[66:67], v[140:141], v[66:67]
	v_pk_fma_f32 v[64:65], v[96:97], v[64:65], v[80:81]
	v_pk_fma_f32 v[66:67], v[98:99], v[66:67], v[82:83]
	v_cvt_pk_bf16_f32 v58, v64, v65
	v_cvt_pk_bf16_f32 v59, v66, v67
	global_store_dwordx2 v[12:13], v[58:59], off offset:-1024
	v_pk_mul_f32 v[68:69], v[68:69], v[56:57] op_sel_hi:[1,0]
	v_pk_mul_f32 v[70:71], v[70:71], v[56:57] op_sel_hi:[1,0]
	v_pk_add_f32 v[100:101], v[100:101], 1.0 op_sel_hi:[1,0]
	v_pk_add_f32 v[102:103], v[102:103], 1.0 op_sel_hi:[1,0]
	v_pk_mul_f32 v[68:69], v[142:143], v[68:69]
	v_pk_mul_f32 v[70:71], v[144:145], v[70:71]
	v_pk_fma_f32 v[68:69], v[100:101], v[68:69], v[84:85]
	v_pk_fma_f32 v[70:71], v[102:103], v[70:71], v[86:87]
	v_cvt_pk_bf16_f32 v60, v68, v69
	v_cvt_pk_bf16_f32 v61, v70, v71
	global_store_dwordx2 v[12:13], v[60:61], off offset:-512
	v_pk_mul_f32 v[72:73], v[72:73], v[56:57] op_sel_hi:[1,0]
	v_pk_mul_f32 v[74:75], v[74:75], v[56:57] op_sel_hi:[1,0]
	v_pk_add_f32 v[104:105], v[104:105], 1.0 op_sel_hi:[1,0]
	v_pk_add_f32 v[106:107], v[106:107], 1.0 op_sel_hi:[1,0]
	v_pk_mul_f32 v[72:73], v[246:247], v[72:73]
	v_pk_mul_f32 v[74:75], v[248:249], v[74:75]
	v_pk_fma_f32 v[72:73], v[104:105], v[72:73], v[88:89]
	v_pk_fma_f32 v[74:75], v[106:107], v[74:75], v[90:91]
	v_cvt_pk_bf16_f32 v58, v72, v73
	v_cvt_pk_bf16_f32 v59, v74, v75
	global_store_dwordx2 v[12:13], v[58:59], off
	v_pk_mul_f32 v[76:77], v[76:77], v[56:57] op_sel_hi:[1,0]
	v_pk_mul_f32 v[78:79], v[78:79], v[56:57] op_sel_hi:[1,0]
	v_pk_add_f32 v[108:109], v[108:109], 1.0 op_sel_hi:[1,0]
	v_pk_add_f32 v[110:111], v[110:111], 1.0 op_sel_hi:[1,0]
	v_pk_mul_f32 v[76:77], v[250:251], v[76:77]
	v_pk_mul_f32 v[78:79], v[252:253], v[78:79]
	v_pk_fma_f32 v[76:77], v[108:109], v[76:77], v[92:93]
	v_pk_fma_f32 v[78:79], v[110:111], v[78:79], v[94:95]
	v_cvt_pk_bf16_f32 v60, v76, v77
	v_cvt_pk_bf16_f32 v61, v78, v79
	global_store_dwordx2 v[12:13], v[60:61], off offset:512
	v_lshl_add_u64 v[12:13], v[12:13], 0, s[36:37]
	global_load_dwordx4 v[64:67], v[10:11], off offset:-2048
	global_load_dwordx4 v[68:71], v[10:11], off offset:-1024
	global_load_dwordx4 v[72:75], v[10:11], off
	global_load_dwordx4 v[76:79], v[10:11], off offset:1024
	v_lshl_add_u64 v[10:11], v[10:11], 0, s[34:35]
	global_load_dwordx4 v[80:83], v0, s[64:65]
	global_load_dwordx4 v[84:87], v0, s[64:65] offset:1024
	global_load_dwordx4 v[88:91], v0, s[64:65] offset:2048
	global_load_dwordx4 v[92:95], v0, s[64:65] offset:3072
	global_load_dwordx4 v[96:99], v0, s[66:67]
	global_load_dwordx4 v[100:103], v0, s[66:67] offset:1024
	global_load_dwordx4 v[104:107], v0, s[66:67] offset:2048
	global_load_dwordx4 v[108:111], v0, s[66:67] offset:3072
	s_add_u32 s64, s64, 0x9000
	s_addc_u32 s65, s65, 0
	s_add_u32 s66, s66, 0x9000
	s_addc_u32 s67, s67, 0
	s_waitcnt vmcnt(16)
	v_mul_f32_e32 v37, v215, v215
	v_fmac_f32_e32 v37, v214, v214
	v_fmac_f32_e32 v37, v216, v216
	v_fmac_f32_e32 v37, v217, v217
	v_mul_f32_e32 v38, v219, v219
	v_fmac_f32_e32 v38, v218, v218
	v_fmac_f32_e32 v38, v220, v220
	v_fmac_f32_e32 v38, v221, v221
	v_mul_f32_e32 v39, v223, v223
	v_fmac_f32_e32 v39, v222, v222
	v_fmac_f32_e32 v39, v224, v224
	v_fmac_f32_e32 v39, v225, v225
	v_mul_f32_e32 v40, v227, v227
	v_fmac_f32_e32 v40, v226, v226
	v_fmac_f32_e32 v40, v228, v228
	v_fmac_f32_e32 v40, v229, v229
	v_add_f32_e32 v255, v37, v38
	v_add_f32_e32 v255, v255, v39
	v_add_f32_e32 v255, v255, v40
	ds_bpermute_b32 v254, v26, v255
	s_waitcnt lgkmcnt(0)
	v_add_f32_e32 v255, v255, v254
	ds_bpermute_b32 v254, v27, v255
	s_waitcnt lgkmcnt(0)
	v_add_f32_e32 v255, v255, v254
	ds_bpermute_b32 v254, v28, v255
	s_waitcnt lgkmcnt(0)
	v_add_f32_e32 v255, v255, v254
	ds_bpermute_b32 v254, v29, v255
	s_waitcnt lgkmcnt(0)
	v_add_f32_e32 v255, v255, v254
	ds_bpermute_b32 v254, v30, v255
	s_waitcnt lgkmcnt(0)
	v_add_f32_e32 v255, v255, v254
	ds_bpermute_b32 v254, v31, v255
	s_waitcnt lgkmcnt(0)
; DI void phase_norm(const Params& p, char* wsb, int layer, int which, int mrows, bool do_convert, char* lds) {
;     ...
;   for (int row = blockIdx.x * 4 + wid; row < mrows; row += nw) {
;     const float4* xr = (const float4*)(xs + (size_t)row * 1024);
;     float4 v[4];
;     float ss = 0.f;
; #pragma unroll
;     for (int i = 0; i < 4; ++i) { v[i] = xr[lane + 64 * i]; ss += v[i].x * v[i].x + v[i].y * v[i].y + v[i].z * v[i].z + v[i].w * v[i].w; }
; #pragma unroll
;     for (int o = 32; o; o >>= 1) ss += __shfl_xor(ss, o);
;     const float r = rsqrtf(ss * (1.f / 1024.f) + 1e-6f);
;     const int mr = row < TL ? (row >> 11) : 8;
;     const float* sh = mods + (size_t)mr * 9216 + (3 * which) * 1024;
;     const float* sc = sh + 1024;
; #pragma unroll
;     for (int i = 0; i < 4; ++i) {
;       int col = (lane + 64 * i) * 4;
;       float4 gg = *(const float4*)(g + col), s4 = *(const float4*)(sh + col), c4 = *(const float4*)(sc + col);
;       float o0 = v[i].x * r * gg.x * (1.f + c4.x) + s4.x;
;       float o1 = v[i].y * r * gg.y * (1.f + c4.y) + s4.y;
;       float o2 = v[i].z * r * gg.z * (1.f + c4.z) + s4.z;
;       float o3 = v[i].w * r * gg.w * (1.f + c4.w) + s4.w;
;       *(uint2*)(H + (size_t)row * 1024 + col) = make_uint2(pack2(o0, o1), pack2(o2, o3));
;     }
	v_add_f32_e32 v255, v255, v254
	v_fmamk_f32 v255, v255, 0x3a800000, v179
	v_cmp_gt_f32_e32 vcc, s40, v255
	v_mul_f32_e32 v254, 0x4b800000, v255
	s_nop 0
	v_cndmask_b32_e32 v255, v255, v254, vcc
	v_rsq_f32_e32 v255, v255
	s_nop 0
	v_mul_f32_e32 v254, 0x45800000, v255
	v_cndmask_b32_e32 v56, v255, v254, vcc
	s_nop 0
	v_pk_mul_f32 v[214:215], v[214:215], v[56:57] op_sel_hi:[1,0]
	v_pk_mul_f32 v[216:217], v[216:217], v[56:57] op_sel_hi:[1,0]
	v_pk_add_f32 v[230:231], v[230:231], 1.0 op_sel_hi:[1,0]
	v_pk_add_f32 v[232:233], v[232:233], 1.0 op_sel_hi:[1,0]
	v_pk_mul_f32 v[214:215], v[138:139], v[214:215]
	v_pk_mul_f32 v[216:217], v[140:141], v[216:217]
	v_pk_fma_f32 v[214:215], v[230:231], v[214:215], v[112:113]
	v_pk_fma_f32 v[216:217], v[232:233], v[216:217], v[114:115]
	v_cvt_pk_bf16_f32 v58, v214, v215
	v_cvt_pk_bf16_f32 v59, v216, v217
	global_store_dwordx2 v[12:13], v[58:59], off offset:-1024
	v_pk_mul_f32 v[218:219], v[218:219], v[56:57] op_sel_hi:[1,0]
	v_pk_mul_f32 v[220:221], v[220:221], v[56:57] op_sel_hi:[1,0]
	v_pk_add_f32 v[234:235], v[234:235], 1.0 op_sel_hi:[1,0]
	v_pk_add_f32 v[236:237], v[236:237], 1.0 op_sel_hi:[1,0]
	v_pk_mul_f32 v[218:219], v[142:143], v[218:219]
	v_pk_mul_f32 v[220:221], v[144:145], v[220:221]
	v_pk_fma_f32 v[218:219], v[234:235], v[218:219], v[116:117]
	v_pk_fma_f32 v[220:221], v[236:237], v[220:221], v[118:119]
	v_cvt_pk_bf16_f32 v60, v218, v219
	v_cvt_pk_bf16_f32 v61, v220, v221
	global_store_dwordx2 v[12:13], v[60:61], off offset:-512
	v_pk_mul_f32 v[222:223], v[222:223], v[56:57] op_sel_hi:[1,0]
	v_pk_mul_f32 v[224:225], v[224:225], v[56:57] op_sel_hi:[1,0]
	v_pk_add_f32 v[238:239], v[238:239], 1.0 op_sel_hi:[1,0]
	v_pk_add_f32 v[240:241], v[240:241], 1.0 op_sel_hi:[1,0]
	v_pk_mul_f32 v[222:223], v[246:247], v[222:223]
	v_pk_mul_f32 v[224:225], v[248:249], v[224:225]
	v_pk_fma_f32 v[222:223], v[238:239], v[222:223], v[120:121]
	v_pk_fma_f32 v[224:225], v[240:241], v[224:225], v[122:123]
	v_cvt_pk_bf16_f32 v58, v222, v223
	v_cvt_pk_bf16_f32 v59, v224, v225
	global_store_dwordx2 v[12:13], v[58:59], off
	v_pk_mul_f32 v[226:227], v[226:227], v[56:57] op_sel_hi:[1,0]
	v_pk_mul_f32 v[228:229], v[228:229], v[56:57] op_sel_hi:[1,0]
	v_pk_add_f32 v[134:135], v[134:135], 1.0 op_sel_hi:[1,0]
	v_pk_add_f32 v[136:137], v[136:137], 1.0 op_sel_hi:[1,0]
	v_pk_mul_f32 v[226:227], v[250:251], v[226:227]
	v_pk_mul_f32 v[228:229], v[252:253], v[228:229]
	v_pk_fma_f32 v[226:227], v[134:135], v[226:227], v[126:127]
	v_pk_fma_f32 v[228:229], v[136:137], v[228:229], v[128:129]
	v_cvt_pk_bf16_f32 v60, v226, v227
	v_cvt_pk_bf16_f32 v61, v228, v229
	global_store_dwordx2 v[12:13], v[60:61], off offset:512
	v_lshl_add_u64 v[12:13], v[12:13], 0, s[36:37]
	global_load_dwordx4 v[214:217], v[10:11], off offset:-2048
	global_load_dwordx4 v[218:221], v[10:11], off offset:-1024
	global_load_dwordx4 v[222:225], v[10:11], off
	global_load_dwordx4 v[226:229], v[10:11], off offset:1024
	v_lshl_add_u64 v[10:11], v[10:11], 0, s[34:35]
	global_load_dwordx4 v[112:115], v0, s[64:65]
	global_load_dwordx4 v[116:119], v0, s[64:65] offset:1024
	global_load_dwordx4 v[120:123], v0, s[64:65] offset:2048
	global_load_dwordx4 v[126:129], v0, s[64:65] offset:3072
	global_load_dwordx4 v[230:233], v0, s[66:67]
	global_load_dwordx4 v[234:237], v0, s[66:67] offset:1024
	global_load_dwordx4 v[238:241], v0, s[66:67] offset:2048
	global_load_dwordx4 v[134:137], v0, s[66:67] offset:3072
	s_add_u32 s64, s64, 0x9000
	s_addc_u32 s65, s65, 0
	s_add_u32 s66, s66, 0x9000
	s_addc_u32 s67, s67, 0
	s_waitcnt vmcnt(16)
	v_mul_f32_e32 v37, v65, v65
	v_fmac_f32_e32 v37, v64, v64
	v_fmac_f32_e32 v37, v66, v66
	v_fmac_f32_e32 v37, v67, v67
	v_mul_f32_e32 v38, v69, v69
	v_fmac_f32_e32 v38, v68, v68
	v_fmac_f32_e32 v38, v70, v70
	v_fmac_f32_e32 v38, v71, v71
	v_mul_f32_e32 v39, v73, v73
	v_fmac_f32_e32 v39, v72, v72
	v_fmac_f32_e32 v39, v74, v74
	v_fmac_f32_e32 v39, v75, v75
	v_mul_f32_e32 v40, v77, v77
	v_fmac_f32_e32 v40, v76, v76
	v_fmac_f32_e32 v40, v78, v78
	v_fmac_f32_e32 v40, v79, v79
	v_add_f32_e32 v255, v37, v38
	v_add_f32_e32 v255, v255, v39
	v_add_f32_e32 v255, v255, v40
	ds_bpermute_b32 v254, v26, v255
	s_waitcnt lgkmcnt(0)
	v_add_f32_e32 v255, v255, v254
	ds_bpermute_b32 v254, v27, v255
	s_waitcnt lgkmcnt(0)
	v_add_f32_e32 v255, v255, v254
	ds_bpermute_b32 v254, v28, v255
	s_waitcnt lgkmcnt(0)
	v_add_f32_e32 v255, v255, v254
	ds_bpermute_b32 v254, v29, v255
	s_waitcnt lgkmcnt(0)
	v_add_f32_e32 v255, v255, v254
	ds_bpermute_b32 v254, v30, v255
	s_waitcnt lgkmcnt(0)
	v_add_f32_e32 v255, v255, v254
	ds_bpermute_b32 v254, v31, v255
	s_waitcnt lgkmcnt(0)
; DI void phase_norm(const Params& p, char* wsb, int layer, int which, int mrows, bool do_convert, char* lds) {
;     ...
;   for (int row = blockIdx.x * 4 + wid; row < mrows; row += nw) {
;     const float4* xr = (const float4*)(xs + (size_t)row * 1024);
;     float4 v[4];
;     float ss = 0.f;
; #pragma unroll
;     for (int i = 0; i < 4; ++i) { v[i] = xr[lane + 64 * i]; ss += v[i].x * v[i].x + v[i].y * v[i].y + v[i].z * v[i].z + v[i].w * v[i].w; }
; #pragma unroll
;     for (int o = 32; o; o >>= 1) ss += __shfl_xor(ss, o);
;     const float r = rsqrtf(ss * (1.f / 1024.f) + 1e-6f);
;     const int mr = row < TL ? (row >> 11) : 8;
;     const float* sh = mods + (size_t)mr * 9216 + (3 * which) * 1024;
;     const float* sc = sh + 1024;
; #pragma unroll
;     for (int i = 0; i < 4; ++i) {
;       int col = (lane + 64 * i) * 4;
;       float4 gg = *(const float4*)(g + col), s4 = *(const float4*)(sh + col), c4 = *(const float4*)(sc + col);
;       float o0 = v[i].x * r * gg.x * (1.f + c4.x) + s4.x;
;       float o1 = v[i].y * r * gg.y * (1.f + c4.y) + s4.y;
;       float o2 = v[i].z * r * gg.z * (1.f + c4.z) + s4.z;
;       float o3 = v[i].w * r * gg.w * (1.f + c4.w) + s4.w;
;       *(uint2*)(H + (size_t)row * 1024 + col) = make_uint2(pack2(o0, o1), pack2(o2, o3));
;     }
	v_add_f32_e32 v255, v255, v254
	v_fmamk_f32 v255, v255, 0x3a800000, v179
	v_cmp_gt_f32_e32 vcc, s40, v255
	v_mul_f32_e32 v254, 0x4b800000, v255
	s_nop 0
	v_cndmask_b32_e32 v255, v255, v254, vcc
	v_rsq_f32_e32 v255, v255
	s_nop 0
	v_mul_f32_e32 v254, 0x45800000, v255
	v_cndmask_b32_e32 v56, v255, v254, vcc
	s_nop 0
	v_pk_mul_f32 v[64:65], v[64:65], v[56:57] op_sel_hi:[1,0]
	v_pk_mul_f32 v[66:67], v[66:67], v[56:57] op_sel_hi:[1,0]
	v_pk_add_f32 v[96:97], v[96:97], 1.0 op_sel_hi:[1,0]
	v_pk_add_f32 v[98:99], v[98:99], 1.0 op_sel_hi:[1,0]
	v_pk_mul_f32 v[64:65], v[138:139], v[64:65]
	v_pk_mul_f32 v[66:67], v[140:141], v[66:67]
	v_pk_fma_f32 v[64:65], v[96:97], v[64:65], v[80:81]
	v_pk_fma_f32 v[66:67], v[98:99], v[66:67], v[82:83]
	v_cvt_pk_bf16_f32 v58, v64, v65
	v_cvt_pk_bf16_f32 v59, v66, v67
	global_store_dwordx2 v[12:13], v[58:59], off offset:-1024
	v_pk_mul_f32 v[68:69], v[68:69], v[56:57] op_sel_hi:[1,0]
	v_pk_mul_f32 v[70:71], v[70:71], v[56:57] op_sel_hi:[1,0]
	v_pk_add_f32 v[100:101], v[100:101], 1.0 op_sel_hi:[1,0]
	v_pk_add_f32 v[102:103], v[102:103], 1.0 op_sel_hi:[1,0]
	v_pk_mul_f32 v[68:69], v[142:143], v[68:69]
	v_pk_mul_f32 v[70:71], v[144:145], v[70:71]
	v_pk_fma_f32 v[68:69], v[100:101], v[68:69], v[84:85]
	v_pk_fma_f32 v[70:71], v[102:103], v[70:71], v[86:87]
	v_cvt_pk_bf16_f32 v60, v68, v69
	v_cvt_pk_bf16_f32 v61, v70, v71
	global_store_dwordx2 v[12:13], v[60:61], off offset:-512
	v_pk_mul_f32 v[72:73], v[72:73], v[56:57] op_sel_hi:[1,0]
	v_pk_mul_f32 v[74:75], v[74:75], v[56:57] op_sel_hi:[1,0]
	v_pk_add_f32 v[104:105], v[104:105], 1.0 op_sel_hi:[1,0]
	v_pk_add_f32 v[106:107], v[106:107], 1.0 op_sel_hi:[1,0]
	v_pk_mul_f32 v[72:73], v[246:247], v[72:73]
	v_pk_mul_f32 v[74:75], v[248:249], v[74:75]
	v_pk_fma_f32 v[72:73], v[104:105], v[72:73], v[88:89]
	v_pk_fma_f32 v[74:75], v[106:107], v[74:75], v[90:91]
	v_cvt_pk_bf16_f32 v58, v72, v73
	v_cvt_pk_bf16_f32 v59, v74, v75
	global_store_dwordx2 v[12:13], v[58:59], off
	v_pk_mul_f32 v[76:77], v[76:77], v[56:57] op_sel_hi:[1,0]
	v_pk_mul_f32 v[78:79], v[78:79], v[56:57] op_sel_hi:[1,0]
	v_pk_add_f32 v[108:109], v[108:109], 1.0 op_sel_hi:[1,0]
	v_pk_add_f32 v[110:111], v[110:111], 1.0 op_sel_hi:[1,0]
	v_pk_mul_f32 v[76:77], v[250:251], v[76:77]
	v_pk_mul_f32 v[78:79], v[252:253], v[78:79]
	v_pk_fma_f32 v[76:77], v[108:109], v[76:77], v[92:93]
	v_pk_fma_f32 v[78:79], v[110:111], v[78:79], v[94:95]
	v_cvt_pk_bf16_f32 v60, v76, v77
	v_cvt_pk_bf16_f32 v61, v78, v79
	global_store_dwordx2 v[12:13], v[60:61], off offset:512
	v_lshl_add_u64 v[12:13], v[12:13], 0, s[36:37]
	global_load_dwordx4 v[64:67], v[10:11], off offset:-2048
	global_load_dwordx4 v[68:71], v[10:11], off offset:-1024
	global_load_dwordx4 v[72:75], v[10:11], off
	global_load_dwordx4 v[76:79], v[10:11], off offset:1024
	v_lshl_add_u64 v[10:11], v[10:11], 0, s[34:35]
	global_load_dwordx4 v[80:83], v0, s[64:65]
	global_load_dwordx4 v[84:87], v0, s[64:65] offset:1024
	global_load_dwordx4 v[88:91], v0, s[64:65] offset:2048
	global_load_dwordx4 v[92:95], v0, s[64:65] offset:3072
	global_load_dwordx4 v[96:99], v0, s[66:67]
	global_load_dwordx4 v[100:103], v0, s[66:67] offset:1024
	global_load_dwordx4 v[104:107], v0, s[66:67] offset:2048
	global_load_dwordx4 v[108:111], v0, s[66:67] offset:3072
	s_add_u32 s64, s64, 0x9000
	s_addc_u32 s65, s65, 0
	s_add_u32 s66, s66, 0x9000
	s_addc_u32 s67, s67, 0
	s_waitcnt vmcnt(16)
	v_mul_f32_e32 v37, v215, v215
	v_fmac_f32_e32 v37, v214, v214
	v_fmac_f32_e32 v37, v216, v216
	v_fmac_f32_e32 v37, v217, v217
	v_mul_f32_e32 v38, v219, v219
	v_fmac_f32_e32 v38, v218, v218
	v_fmac_f32_e32 v38, v220, v220
	v_fmac_f32_e32 v38, v221, v221
	v_mul_f32_e32 v39, v223, v223
	v_fmac_f32_e32 v39, v222, v222
	v_fmac_f32_e32 v39, v224, v224
	v_fmac_f32_e32 v39, v225, v225
	v_mul_f32_e32 v40, v227, v227
	v_fmac_f32_e32 v40, v226, v226
	v_fmac_f32_e32 v40, v228, v228
	v_fmac_f32_e32 v40, v229, v229
	v_add_f32_e32 v255, v37, v38
	v_add_f32_e32 v255, v255, v39
	v_add_f32_e32 v255, v255, v40
	ds_bpermute_b32 v254, v26, v255
	s_waitcnt lgkmcnt(0)
	v_add_f32_e32 v255, v255, v254
	ds_bpermute_b32 v254, v27, v255
	s_waitcnt lgkmcnt(0)
	v_add_f32_e32 v255, v255, v254
	ds_bpermute_b32 v254, v28, v255
	s_waitcnt lgkmcnt(0)
	v_add_f32_e32 v255, v255, v254
	ds_bpermute_b32 v254, v29, v255
	s_waitcnt lgkmcnt(0)
	v_add_f32_e32 v255, v255, v254
	ds_bpermute_b32 v254, v30, v255
	s_waitcnt lgkmcnt(0)
	v_add_f32_e32 v255, v255, v254
	ds_bpermute_b32 v254, v31, v255
	s_waitcnt lgkmcnt(0)
; DI void phase_norm(const Params& p, char* wsb, int layer, int which, int mrows, bool do_convert, char* lds) {
;     ...
;   for (int row = blockIdx.x * 4 + wid; row < mrows; row += nw) {
;     const float4* xr = (const float4*)(xs + (size_t)row * 1024);
;     float4 v[4];
;     float ss = 0.f;
; #pragma unroll
;     for (int i = 0; i < 4; ++i) { v[i] = xr[lane + 64 * i]; ss += v[i].x * v[i].x + v[i].y * v[i].y + v[i].z * v[i].z + v[i].w * v[i].w; }
; #pragma unroll
;     for (int o = 32; o; o >>= 1) ss += __shfl_xor(ss, o);
;     const float r = rsqrtf(ss * (1.f / 1024.f) + 1e-6f);
;     const int mr = row < TL ? (row >> 11) : 8;
;     const float* sh = mods + (size_t)mr * 9216 + (3 * which) * 1024;
;     const float* sc = sh + 1024;
; #pragma unroll
;     for (int i = 0; i < 4; ++i) {
;       int col = (lane + 64 * i) * 4;
;       float4 gg = *(const float4*)(g + col), s4 = *(const float4*)(sh + col), c4 = *(const float4*)(sc + col);
;       float o0 = v[i].x * r * gg.x * (1.f + c4.x) + s4.x;
;       float o1 = v[i].y * r * gg.y * (1.f + c4.y) + s4.y;
;       float o2 = v[i].z * r * gg.z * (1.f + c4.z) + s4.z;
;       float o3 = v[i].w * r * gg.w * (1.f + c4.w) + s4.w;
;       *(uint2*)(H + (size_t)row * 1024 + col) = make_uint2(pack2(o0, o1), pack2(o2, o3));
;     }
	v_add_f32_e32 v255, v255, v254
	v_fmamk_f32 v255, v255, 0x3a800000, v179
	v_cmp_gt_f32_e32 vcc, s40, v255
	v_mul_f32_e32 v254, 0x4b800000, v255
	s_nop 0
	v_cndmask_b32_e32 v255, v255, v254, vcc
	v_rsq_f32_e32 v255, v255
	s_nop 0
	v_mul_f32_e32 v254, 0x45800000, v255
	v_cndmask_b32_e32 v56, v255, v254, vcc
	s_nop 0
	v_pk_mul_f32 v[214:215], v[214:215], v[56:57] op_sel_hi:[1,0]
	v_pk_mul_f32 v[216:217], v[216:217], v[56:57] op_sel_hi:[1,0]
	v_pk_add_f32 v[230:231], v[230:231], 1.0 op_sel_hi:[1,0]
	v_pk_add_f32 v[232:233], v[232:233], 1.0 op_sel_hi:[1,0]
	v_pk_mul_f32 v[214:215], v[138:139], v[214:215]
	v_pk_mul_f32 v[216:217], v[140:141], v[216:217]
	v_pk_fma_f32 v[214:215], v[230:231], v[214:215], v[112:113]
	v_pk_fma_f32 v[216:217], v[232:233], v[216:217], v[114:115]
	v_cvt_pk_bf16_f32 v58, v214, v215
	v_cvt_pk_bf16_f32 v59, v216, v217
	global_store_dwordx2 v[12:13], v[58:59], off offset:-1024
	v_pk_mul_f32 v[218:219], v[218:219], v[56:57] op_sel_hi:[1,0]
	v_pk_mul_f32 v[220:221], v[220:221], v[56:57] op_sel_hi:[1,0]
	v_pk_add_f32 v[234:235], v[234:235], 1.0 op_sel_hi:[1,0]
	v_pk_add_f32 v[236:237], v[236:237], 1.0 op_sel_hi:[1,0]
	v_pk_mul_f32 v[218:219], v[142:143], v[218:219]
	v_pk_mul_f32 v[220:221], v[144:145], v[220:221]
	v_pk_fma_f32 v[218:219], v[234:235], v[218:219], v[116:117]
	v_pk_fma_f32 v[220:221], v[236:237], v[220:221], v[118:119]
	v_cvt_pk_bf16_f32 v60, v218, v219
	v_cvt_pk_bf16_f32 v61, v220, v221
	global_store_dwordx2 v[12:13], v[60:61], off offset:-512
	v_pk_mul_f32 v[222:223], v[222:223], v[56:57] op_sel_hi:[1,0]
	v_pk_mul_f32 v[224:225], v[224:225], v[56:57] op_sel_hi:[1,0]
	v_pk_add_f32 v[238:239], v[238:239], 1.0 op_sel_hi:[1,0]
	v_pk_add_f32 v[240:241], v[240:241], 1.0 op_sel_hi:[1,0]
	v_pk_mul_f32 v[222:223], v[246:247], v[222:223]
	v_pk_mul_f32 v[224:225], v[248:249], v[224:225]
	v_pk_fma_f32 v[222:223], v[238:239], v[222:223], v[120:121]
	v_pk_fma_f32 v[224:225], v[240:241], v[224:225], v[122:123]
	v_cvt_pk_bf16_f32 v58, v222, v223
	v_cvt_pk_bf16_f32 v59, v224, v225
	global_store_dwordx2 v[12:13], v[58:59], off
	v_pk_mul_f32 v[226:227], v[226:227], v[56:57] op_sel_hi:[1,0]
	v_pk_mul_f32 v[228:229], v[228:229], v[56:57] op_sel_hi:[1,0]
	v_pk_add_f32 v[134:135], v[134:135], 1.0 op_sel_hi:[1,0]
	v_pk_add_f32 v[136:137], v[136:137], 1.0 op_sel_hi:[1,0]
	v_pk_mul_f32 v[226:227], v[250:251], v[226:227]
	v_pk_mul_f32 v[228:229], v[252:253], v[228:229]
	v_pk_fma_f32 v[226:227], v[134:135], v[226:227], v[126:127]
	v_pk_fma_f32 v[228:229], v[136:137], v[228:229], v[128:129]
	v_cvt_pk_bf16_f32 v60, v226, v227
	v_cvt_pk_bf16_f32 v61, v228, v229
	global_store_dwordx2 v[12:13], v[60:61], off offset:512
	v_lshl_add_u64 v[12:13], v[12:13], 0, s[36:37]
	global_load_dwordx4 v[214:217], v[10:11], off offset:-2048
	global_load_dwordx4 v[218:221], v[10:11], off offset:-1024
	global_load_dwordx4 v[222:225], v[10:11], off
	global_load_dwordx4 v[226:229], v[10:11], off offset:1024
	v_lshl_add_u64 v[10:11], v[10:11], 0, s[34:35]
	global_load_dwordx4 v[112:115], v0, s[64:65]
	global_load_dwordx4 v[116:119], v0, s[64:65] offset:1024
	global_load_dwordx4 v[120:123], v0, s[64:65] offset:2048
	global_load_dwordx4 v[126:129], v0, s[64:65] offset:3072
	global_load_dwordx4 v[230:233], v0, s[66:67]
	global_load_dwordx4 v[234:237], v0, s[66:67] offset:1024
	global_load_dwordx4 v[238:241], v0, s[66:67] offset:2048
	global_load_dwordx4 v[134:137], v0, s[66:67] offset:3072
	s_add_u32 s64, s64, 0x9000
	s_addc_u32 s65, s65, 0
	s_add_u32 s66, s66, 0x9000
	s_addc_u32 s67, s67, 0
	s_waitcnt vmcnt(16)
	v_mul_f32_e32 v37, v65, v65
	v_fmac_f32_e32 v37, v64, v64
	v_fmac_f32_e32 v37, v66, v66
	v_fmac_f32_e32 v37, v67, v67
	v_mul_f32_e32 v38, v69, v69
	v_fmac_f32_e32 v38, v68, v68
	v_fmac_f32_e32 v38, v70, v70
	v_fmac_f32_e32 v38, v71, v71
	v_mul_f32_e32 v39, v73, v73
	v_fmac_f32_e32 v39, v72, v72
	v_fmac_f32_e32 v39, v74, v74
	v_fmac_f32_e32 v39, v75, v75
	v_mul_f32_e32 v40, v77, v77
	v_fmac_f32_e32 v40, v76, v76
	v_fmac_f32_e32 v40, v78, v78
	v_fmac_f32_e32 v40, v79, v79
	v_add_f32_e32 v255, v37, v38
	v_add_f32_e32 v255, v255, v39
	v_add_f32_e32 v255, v255, v40
	ds_bpermute_b32 v254, v26, v255
	s_waitcnt lgkmcnt(0)
	v_add_f32_e32 v255, v255, v254
	ds_bpermute_b32 v254, v27, v255
	s_waitcnt lgkmcnt(0)
	v_add_f32_e32 v255, v255, v254
	ds_bpermute_b32 v254, v28, v255
	s_waitcnt lgkmcnt(0)
	v_add_f32_e32 v255, v255, v254
	ds_bpermute_b32 v254, v29, v255
	s_waitcnt lgkmcnt(0)
	v_add_f32_e32 v255, v255, v254
	ds_bpermute_b32 v254, v30, v255
	s_waitcnt lgkmcnt(0)
	v_add_f32_e32 v255, v255, v254
	ds_bpermute_b32 v254, v31, v255
	s_waitcnt lgkmcnt(0)
; DI void phase_norm(const Params& p, char* wsb, int layer, int which, int mrows, bool do_convert, char* lds) {
;     ...
;   for (int row = blockIdx.x * 4 + wid; row < mrows; row += nw) {
;     const float4* xr = (const float4*)(xs + (size_t)row * 1024);
;     float4 v[4];
;     float ss = 0.f;
; #pragma unroll
;     for (int i = 0; i < 4; ++i) { v[i] = xr[lane + 64 * i]; ss += v[i].x * v[i].x + v[i].y * v[i].y + v[i].z * v[i].z + v[i].w * v[i].w; }
; #pragma unroll
;     for (int o = 32; o; o >>= 1) ss += __shfl_xor(ss, o);
;     const float r = rsqrtf(ss * (1.f / 1024.f) + 1e-6f);
;     const int mr = row < TL ? (row >> 11) : 8;
;     const float* sh = mods + (size_t)mr * 9216 + (3 * which) * 1024;
;     const float* sc = sh + 1024;
; #pragma unroll
;     for (int i = 0; i < 4; ++i) {
;       int col = (lane + 64 * i) * 4;
;       float4 gg = *(const float4*)(g + col), s4 = *(const float4*)(sh + col), c4 = *(const float4*)(sc + col);
;       float o0 = v[i].x * r * gg.x * (1.f + c4.x) + s4.x;
;       float o1 = v[i].y * r * gg.y * (1.f + c4.y) + s4.y;
;       float o2 = v[i].z * r * gg.z * (1.f + c4.z) + s4.z;
;       float o3 = v[i].w * r * gg.w * (1.f + c4.w) + s4.w;
;       *(uint2*)(H + (size_t)row * 1024 + col) = make_uint2(pack2(o0, o1), pack2(o2, o3));
;     }
	v_add_f32_e32 v255, v255, v254
	v_fmamk_f32 v255, v255, 0x3a800000, v179
	v_cmp_gt_f32_e32 vcc, s40, v255
	v_mul_f32_e32 v254, 0x4b800000, v255
	s_nop 0
	v_cndmask_b32_e32 v255, v255, v254, vcc
	v_rsq_f32_e32 v255, v255
	s_nop 0
	v_mul_f32_e32 v254, 0x45800000, v255
	v_cndmask_b32_e32 v56, v255, v254, vcc
	s_nop 0
	v_pk_mul_f32 v[64:65], v[64:65], v[56:57] op_sel_hi:[1,0]
	v_pk_mul_f32 v[66:67], v[66:67], v[56:57] op_sel_hi:[1,0]
	v_pk_add_f32 v[96:97], v[96:97], 1.0 op_sel_hi:[1,0]
	v_pk_add_f32 v[98:99], v[98:99], 1.0 op_sel_hi:[1,0]
	v_pk_mul_f32 v[64:65], v[138:139], v[64:65]
	v_pk_mul_f32 v[66:67], v[140:141], v[66:67]
	v_pk_fma_f32 v[64:65], v[96:97], v[64:65], v[80:81]
	v_pk_fma_f32 v[66:67], v[98:99], v[66:67], v[82:83]
	v_cvt_pk_bf16_f32 v58, v64, v65
	v_cvt_pk_bf16_f32 v59, v66, v67
	global_store_dwordx2 v[12:13], v[58:59], off offset:-1024
	v_pk_mul_f32 v[68:69], v[68:69], v[56:57] op_sel_hi:[1,0]
	v_pk_mul_f32 v[70:71], v[70:71], v[56:57] op_sel_hi:[1,0]
	v_pk_add_f32 v[100:101], v[100:101], 1.0 op_sel_hi:[1,0]
	v_pk_add_f32 v[102:103], v[102:103], 1.0 op_sel_hi:[1,0]
	v_pk_mul_f32 v[68:69], v[142:143], v[68:69]
	v_pk_mul_f32 v[70:71], v[144:145], v[70:71]
	v_pk_fma_f32 v[68:69], v[100:101], v[68:69], v[84:85]
	v_pk_fma_f32 v[70:71], v[102:103], v[70:71], v[86:87]
	v_cvt_pk_bf16_f32 v60, v68, v69
	v_cvt_pk_bf16_f32 v61, v70, v71
	global_store_dwordx2 v[12:13], v[60:61], off offset:-512
	v_pk_mul_f32 v[72:73], v[72:73], v[56:57] op_sel_hi:[1,0]
	v_pk_mul_f32 v[74:75], v[74:75], v[56:57] op_sel_hi:[1,0]
	v_pk_add_f32 v[104:105], v[104:105], 1.0 op_sel_hi:[1,0]
	v_pk_add_f32 v[106:107], v[106:107], 1.0 op_sel_hi:[1,0]
	v_pk_mul_f32 v[72:73], v[246:247], v[72:73]
	v_pk_mul_f32 v[74:75], v[248:249], v[74:75]
	v_pk_fma_f32 v[72:73], v[104:105], v[72:73], v[88:89]
	v_pk_fma_f32 v[74:75], v[106:107], v[74:75], v[90:91]
	v_cvt_pk_bf16_f32 v58, v72, v73
	v_cvt_pk_bf16_f32 v59, v74, v75
	global_store_dwordx2 v[12:13], v[58:59], off
	v_pk_mul_f32 v[76:77], v[76:77], v[56:57] op_sel_hi:[1,0]
	v_pk_mul_f32 v[78:79], v[78:79], v[56:57] op_sel_hi:[1,0]
	v_pk_add_f32 v[108:109], v[108:109], 1.0 op_sel_hi:[1,0]
	v_pk_add_f32 v[110:111], v[110:111], 1.0 op_sel_hi:[1,0]
	v_pk_mul_f32 v[76:77], v[250:251], v[76:77]
	v_pk_mul_f32 v[78:79], v[252:253], v[78:79]
	v_pk_fma_f32 v[76:77], v[108:109], v[76:77], v[92:93]
	v_pk_fma_f32 v[78:79], v[110:111], v[78:79], v[94:95]
	v_cvt_pk_bf16_f32 v60, v76, v77
	v_cvt_pk_bf16_f32 v61, v78, v79
	global_store_dwordx2 v[12:13], v[60:61], off offset:512
	v_lshl_add_u64 v[12:13], v[12:13], 0, s[36:37]
	global_load_dwordx4 v[64:67], v[10:11], off offset:-2048
	global_load_dwordx4 v[68:71], v[10:11], off offset:-1024
	global_load_dwordx4 v[72:75], v[10:11], off
	global_load_dwordx4 v[76:79], v[10:11], off offset:1024
	v_lshl_add_u64 v[10:11], v[10:11], 0, s[34:35]
	global_load_dwordx4 v[80:83], v0, s[64:65]
	global_load_dwordx4 v[84:87], v0, s[64:65] offset:1024
	global_load_dwordx4 v[88:91], v0, s[64:65] offset:2048
	global_load_dwordx4 v[92:95], v0, s[64:65] offset:3072
	global_load_dwordx4 v[96:99], v0, s[66:67]
	global_load_dwordx4 v[100:103], v0, s[66:67] offset:1024
	global_load_dwordx4 v[104:107], v0, s[66:67] offset:2048
	global_load_dwordx4 v[108:111], v0, s[66:67] offset:3072
	s_add_u32 s64, s64, 0x9000
	s_addc_u32 s65, s65, 0
	s_add_u32 s66, s66, 0x9000
	s_addc_u32 s67, s67, 0
	s_waitcnt vmcnt(16)
	v_mul_f32_e32 v37, v215, v215
	v_fmac_f32_e32 v37, v214, v214
	v_fmac_f32_e32 v37, v216, v216
	v_fmac_f32_e32 v37, v217, v217
	v_mul_f32_e32 v38, v219, v219
	v_fmac_f32_e32 v38, v218, v218
	v_fmac_f32_e32 v38, v220, v220
	v_fmac_f32_e32 v38, v221, v221
	v_mul_f32_e32 v39, v223, v223
	v_fmac_f32_e32 v39, v222, v222
	v_fmac_f32_e32 v39, v224, v224
	v_fmac_f32_e32 v39, v225, v225
	v_mul_f32_e32 v40, v227, v227
	v_fmac_f32_e32 v40, v226, v226
	v_fmac_f32_e32 v40, v228, v228
	v_fmac_f32_e32 v40, v229, v229
	v_add_f32_e32 v255, v37, v38
	v_add_f32_e32 v255, v255, v39
	v_add_f32_e32 v255, v255, v40
	ds_bpermute_b32 v254, v26, v255
	s_waitcnt lgkmcnt(0)
	v_add_f32_e32 v255, v255, v254
	ds_bpermute_b32 v254, v27, v255
	s_waitcnt lgkmcnt(0)
	v_add_f32_e32 v255, v255, v254
	ds_bpermute_b32 v254, v28, v255
	s_waitcnt lgkmcnt(0)
	v_add_f32_e32 v255, v255, v254
	ds_bpermute_b32 v254, v29, v255
	s_waitcnt lgkmcnt(0)
	v_add_f32_e32 v255, v255, v254
	ds_bpermute_b32 v254, v30, v255
	s_waitcnt lgkmcnt(0)
	v_add_f32_e32 v255, v255, v254
	ds_bpermute_b32 v254, v31, v255
	s_waitcnt lgkmcnt(0)
; DI void phase_norm(const Params& p, char* wsb, int layer, int which, int mrows, bool do_convert, char* lds) {
;     ...
;   for (int row = blockIdx.x * 4 + wid; row < mrows; row += nw) {
;     const float4* xr = (const float4*)(xs + (size_t)row * 1024);
;     float4 v[4];
;     float ss = 0.f;
; #pragma unroll
;     for (int i = 0; i < 4; ++i) { v[i] = xr[lane + 64 * i]; ss += v[i].x * v[i].x + v[i].y * v[i].y + v[i].z * v[i].z + v[i].w * v[i].w; }
; #pragma unroll
;     for (int o = 32; o; o >>= 1) ss += __shfl_xor(ss, o);
;     const float r = rsqrtf(ss * (1.f / 1024.f) + 1e-6f);
;     const int mr = row < TL ? (row >> 11) : 8;
;     const float* sh = mods + (size_t)mr * 9216 + (3 * which) * 1024;
;     const float* sc = sh + 1024;
; #pragma unroll
;     for (int i = 0; i < 4; ++i) {
;       int col = (lane + 64 * i) * 4;
;       float4 gg = *(const float4*)(g + col), s4 = *(const float4*)(sh + col), c4 = *(const float4*)(sc + col);
;       float o0 = v[i].x * r * gg.x * (1.f + c4.x) + s4.x;
;       float o1 = v[i].y * r * gg.y * (1.f + c4.y) + s4.y;
;       float o2 = v[i].z * r * gg.z * (1.f + c4.z) + s4.z;
;       float o3 = v[i].w * r * gg.w * (1.f + c4.w) + s4.w;
;       *(uint2*)(H + (size_t)row * 1024 + col) = make_uint2(pack2(o0, o1), pack2(o2, o3));
;     }
	v_add_f32_e32 v255, v255, v254
	v_fmamk_f32 v255, v255, 0x3a800000, v179
	v_cmp_gt_f32_e32 vcc, s40, v255
	v_mul_f32_e32 v254, 0x4b800000, v255
	s_nop 0
	v_cndmask_b32_e32 v255, v255, v254, vcc
	v_rsq_f32_e32 v255, v255
	s_nop 0
	v_mul_f32_e32 v254, 0x45800000, v255
	v_cndmask_b32_e32 v56, v255, v254, vcc
	s_nop 0
	v_pk_mul_f32 v[214:215], v[214:215], v[56:57] op_sel_hi:[1,0]
	v_pk_mul_f32 v[216:217], v[216:217], v[56:57] op_sel_hi:[1,0]
	v_pk_add_f32 v[230:231], v[230:231], 1.0 op_sel_hi:[1,0]
	v_pk_add_f32 v[232:233], v[232:233], 1.0 op_sel_hi:[1,0]
	v_pk_mul_f32 v[214:215], v[138:139], v[214:215]
	v_pk_mul_f32 v[216:217], v[140:141], v[216:217]
	v_pk_fma_f32 v[214:215], v[230:231], v[214:215], v[112:113]
	v_pk_fma_f32 v[216:217], v[232:233], v[216:217], v[114:115]
	v_cvt_pk_bf16_f32 v58, v214, v215
	v_cvt_pk_bf16_f32 v59, v216, v217
	global_store_dwordx2 v[12:13], v[58:59], off offset:-1024
	v_pk_mul_f32 v[218:219], v[218:219], v[56:57] op_sel_hi:[1,0]
	v_pk_mul_f32 v[220:221], v[220:221], v[56:57] op_sel_hi:[1,0]
	v_pk_add_f32 v[234:235], v[234:235], 1.0 op_sel_hi:[1,0]
	v_pk_add_f32 v[236:237], v[236:237], 1.0 op_sel_hi:[1,0]
	v_pk_mul_f32 v[218:219], v[142:143], v[218:219]
	v_pk_mul_f32 v[220:221], v[144:145], v[220:221]
	v_pk_fma_f32 v[218:219], v[234:235], v[218:219], v[116:117]
	v_pk_fma_f32 v[220:221], v[236:237], v[220:221], v[118:119]
	v_cvt_pk_bf16_f32 v60, v218, v219
	v_cvt_pk_bf16_f32 v61, v220, v221
	global_store_dwordx2 v[12:13], v[60:61], off offset:-512
	v_pk_mul_f32 v[222:223], v[222:223], v[56:57] op_sel_hi:[1,0]
	v_pk_mul_f32 v[224:225], v[224:225], v[56:57] op_sel_hi:[1,0]
	v_pk_add_f32 v[238:239], v[238:239], 1.0 op_sel_hi:[1,0]
	v_pk_add_f32 v[240:241], v[240:241], 1.0 op_sel_hi:[1,0]
	v_pk_mul_f32 v[222:223], v[246:247], v[222:223]
	v_pk_mul_f32 v[224:225], v[248:249], v[224:225]
	v_pk_fma_f32 v[222:223], v[238:239], v[222:223], v[120:121]
	v_pk_fma_f32 v[224:225], v[240:241], v[224:225], v[122:123]
	v_cvt_pk_bf16_f32 v58, v222, v223
	v_cvt_pk_bf16_f32 v59, v224, v225
	global_store_dwordx2 v[12:13], v[58:59], off
	v_pk_mul_f32 v[226:227], v[226:227], v[56:57] op_sel_hi:[1,0]
	v_pk_mul_f32 v[228:229], v[228:229], v[56:57] op_sel_hi:[1,0]
	v_pk_add_f32 v[134:135], v[134:135], 1.0 op_sel_hi:[1,0]
	v_pk_add_f32 v[136:137], v[136:137], 1.0 op_sel_hi:[1,0]
	v_pk_mul_f32 v[226:227], v[250:251], v[226:227]
	v_pk_mul_f32 v[228:229], v[252:253], v[228:229]
	v_pk_fma_f32 v[226:227], v[134:135], v[226:227], v[126:127]
	v_pk_fma_f32 v[228:229], v[136:137], v[228:229], v[128:129]
	v_cvt_pk_bf16_f32 v60, v226, v227
	v_cvt_pk_bf16_f32 v61, v228, v229
	global_store_dwordx2 v[12:13], v[60:61], off offset:512
	v_lshl_add_u64 v[12:13], v[12:13], 0, s[36:37]
	s_waitcnt vmcnt(4)
	v_mul_f32_e32 v37, v65, v65
	v_fmac_f32_e32 v37, v64, v64
	v_fmac_f32_e32 v37, v66, v66
	v_fmac_f32_e32 v37, v67, v67
	v_mul_f32_e32 v38, v69, v69
	v_fmac_f32_e32 v38, v68, v68
	v_fmac_f32_e32 v38, v70, v70
	v_fmac_f32_e32 v38, v71, v71
	v_mul_f32_e32 v39, v73, v73
	v_fmac_f32_e32 v39, v72, v72
	v_fmac_f32_e32 v39, v74, v74
	v_fmac_f32_e32 v39, v75, v75
	v_mul_f32_e32 v40, v77, v77
	v_fmac_f32_e32 v40, v76, v76
	v_fmac_f32_e32 v40, v78, v78
	v_fmac_f32_e32 v40, v79, v79
	v_add_f32_e32 v255, v37, v38
	v_add_f32_e32 v255, v255, v39
	v_add_f32_e32 v255, v255, v40
	ds_bpermute_b32 v254, v26, v255
	s_waitcnt lgkmcnt(0)
	v_add_f32_e32 v255, v255, v254
	ds_bpermute_b32 v254, v27, v255
	s_waitcnt lgkmcnt(0)
	v_add_f32_e32 v255, v255, v254
	ds_bpermute_b32 v254, v28, v255
	s_waitcnt lgkmcnt(0)
	v_add_f32_e32 v255, v255, v254
	ds_bpermute_b32 v254, v29, v255
	s_waitcnt lgkmcnt(0)
	v_add_f32_e32 v255, v255, v254
	ds_bpermute_b32 v254, v30, v255
	s_waitcnt lgkmcnt(0)
	v_add_f32_e32 v255, v255, v254
	ds_bpermute_b32 v254, v31, v255
	s_waitcnt lgkmcnt(0)
	v_add_f32_e32 v255, v255, v254
	v_fmamk_f32 v255, v255, 0x3a800000, v179
	v_cmp_gt_f32_e32 vcc, s40, v255
	v_mul_f32_e32 v254, 0x4b800000, v255
	s_nop 0
	v_cndmask_b32_e32 v255, v255, v254, vcc
	v_rsq_f32_e32 v255, v255
	s_nop 0
	v_mul_f32_e32 v254, 0x45800000, v255
	v_cndmask_b32_e32 v56, v255, v254, vcc
	s_nop 0
	v_pk_mul_f32 v[64:65], v[64:65], v[56:57] op_sel_hi:[1,0]
	v_pk_mul_f32 v[66:67], v[66:67], v[56:57] op_sel_hi:[1,0]
	v_pk_add_f32 v[96:97], v[96:97], 1.0 op_sel_hi:[1,0]
	v_pk_add_f32 v[98:99], v[98:99], 1.0 op_sel_hi:[1,0]
	v_pk_mul_f32 v[64:65], v[138:139], v[64:65]
	v_pk_mul_f32 v[66:67], v[140:141], v[66:67]
	v_pk_fma_f32 v[64:65], v[96:97], v[64:65], v[80:81]
	v_pk_fma_f32 v[66:67], v[98:99], v[66:67], v[82:83]
	v_cvt_pk_bf16_f32 v58, v64, v65
	v_cvt_pk_bf16_f32 v59, v66, v67
	global_store_dwordx2 v[12:13], v[58:59], off offset:-1024
	v_pk_mul_f32 v[68:69], v[68:69], v[56:57] op_sel_hi:[1,0]
	v_pk_mul_f32 v[70:71], v[70:71], v[56:57] op_sel_hi:[1,0]
	v_pk_add_f32 v[100:101], v[100:101], 1.0 op_sel_hi:[1,0]
	v_pk_add_f32 v[102:103], v[102:103], 1.0 op_sel_hi:[1,0]
	v_pk_mul_f32 v[68:69], v[142:143], v[68:69]
	v_pk_mul_f32 v[70:71], v[144:145], v[70:71]
	v_pk_fma_f32 v[68:69], v[100:101], v[68:69], v[84:85]
	v_pk_fma_f32 v[70:71], v[102:103], v[70:71], v[86:87]
	v_cvt_pk_bf16_f32 v60, v68, v69
	v_cvt_pk_bf16_f32 v61, v70, v71
	global_store_dwordx2 v[12:13], v[60:61], off offset:-512
	v_pk_mul_f32 v[72:73], v[72:73], v[56:57] op_sel_hi:[1,0]
	v_pk_mul_f32 v[74:75], v[74:75], v[56:57] op_sel_hi:[1,0]
	v_pk_add_f32 v[104:105], v[104:105], 1.0 op_sel_hi:[1,0]
	v_pk_add_f32 v[106:107], v[106:107], 1.0 op_sel_hi:[1,0]
	v_pk_mul_f32 v[72:73], v[246:247], v[72:73]
	v_pk_mul_f32 v[74:75], v[248:249], v[74:75]
	v_pk_fma_f32 v[72:73], v[104:105], v[72:73], v[88:89]
	v_pk_fma_f32 v[74:75], v[106:107], v[74:75], v[90:91]
	v_cvt_pk_bf16_f32 v58, v72, v73
	v_cvt_pk_bf16_f32 v59, v74, v75
	global_store_dwordx2 v[12:13], v[58:59], off
	v_pk_mul_f32 v[76:77], v[76:77], v[56:57] op_sel_hi:[1,0]
	v_pk_mul_f32 v[78:79], v[78:79], v[56:57] op_sel_hi:[1,0]
	v_pk_add_f32 v[108:109], v[108:109], 1.0 op_sel_hi:[1,0]
	v_pk_add_f32 v[110:111], v[110:111], 1.0 op_sel_hi:[1,0]
	v_pk_mul_f32 v[76:77], v[250:251], v[76:77]
	v_pk_mul_f32 v[78:79], v[252:253], v[78:79]
	v_pk_fma_f32 v[76:77], v[108:109], v[76:77], v[92:93]
	v_pk_fma_f32 v[78:79], v[110:111], v[78:79], v[94:95]
	v_cvt_pk_bf16_f32 v60, v76, v77
	v_cvt_pk_bf16_f32 v61, v78, v79
	global_store_dwordx2 v[12:13], v[60:61], off offset:512
	v_lshl_add_u64 v[12:13], v[12:13], 0, s[36:37]
; DI void phase_norm(const Params& p, char* wsb, int layer, int which, int mrows, bool do_convert, char* lds) {
;     ...
;   for (int row = blockIdx.x * 4 + wid; row < mrows; row += nw) {
;     const float4* xr = (const float4*)(xs + (size_t)row * 1024);
;     float4 v[4];
;     float ss = 0.f;
; #pragma unroll
;     for (int i = 0; i < 4; ++i) { v[i] = xr[lane + 64 * i]; ss += v[i].x * v[i].x + v[i].y * v[i].y + v[i].z * v[i].z + v[i].w * v[i].w; }
; #pragma unroll
;     for (int o = 32; o; o >>= 1) ss += __shfl_xor(ss, o);
;     const float r = rsqrtf(ss * (1.f / 1024.f) + 1e-6f);
;     const int mr = row < TL ? (row >> 11) : 8;
;     const float* sh = mods + (size_t)mr * 9216 + (3 * which) * 1024;
;     const float* sc = sh + 1024;
; #pragma unroll
;     for (int i = 0; i < 4; ++i) {
;       int col = (lane + 64 * i) * 4;
;       float4 gg = *(const float4*)(g + col), s4 = *(const float4*)(sh + col), c4 = *(const float4*)(sc + col);
;       float o0 = v[i].x * r * gg.x * (1.f + c4.x) + s4.x;
;       float o1 = v[i].y * r * gg.y * (1.f + c4.y) + s4.y;
;       float o2 = v[i].z * r * gg.z * (1.f + c4.z) + s4.z;
;       float o3 = v[i].w * r * gg.w * (1.f + c4.w) + s4.w;
;       *(uint2*)(H + (size_t)row * 1024 + col) = make_uint2(pack2(o0, o1), pack2(o2, o3));
;     }
.Lnrm0_done:
	s_branch .LBB0_345
.LBB0_344:
	v_min_i32_e32 v2, 0x4000, v6
	v_ashrrev_i32_e32 v2, 11, v2
	v_mul_hi_i32_i24_e32 v3, 0x9000, v2
	v_mul_i32_i24_e32 v2, 0x9000, v2
	v_lshl_add_u64 v[2:3], s[8:9], 0, v[2:3]
	v_lshl_add_u64 v[22:23], v[2:3], 0, s[48:49]
	v_lshl_add_u64 v[20:21], v[2:3], 0, v[0:1]
	v_lshl_add_u64 v[2:3], v[22:23], 0, v[0:1]
	global_load_dwordx4 v[32:35], v[10:11], off offset:-2048
	global_load_dwordx4 v[36:39], v[8:9], off
	global_load_dwordx4 v[40:43], v[20:21], off
	s_nop 0
	global_load_dwordx4 v[2:5], v[2:3], off
	v_lshl_add_u64 v[56:57], v[22:23], 0, v[14:15]
	global_load_dwordx4 v[44:47], v[10:11], off offset:-1024
	v_add_u32_e32 v6, s94, v6
	s_waitcnt vmcnt(4)
	v_mov_b32_e32 v48, v33
	v_mov_b32_e32 v24, v32
	s_waitcnt vmcnt(1)
	v_pk_add_f32 v[54:55], v[2:3], 1.0 op_sel_hi:[1,0]
	v_mov_b32_e32 v2, v34
	s_waitcnt vmcnt(0)
	v_mov_b32_e32 v49, v45
	v_mov_b32_e32 v25, v44
	v_pk_mul_f32 v[48:49], v[48:49], v[48:49]
	v_mov_b32_e32 v3, v46
	v_pk_fma_f32 v[24:25], v[24:25], v[24:25], v[48:49]
	v_pk_add_f32 v[52:53], v[4:5], 1.0 op_sel_hi:[1,0]
	v_mov_b32_e32 v4, v35
	v_mov_b32_e32 v5, v47
	v_pk_fma_f32 v[2:3], v[2:3], v[2:3], v[24:25]
	global_load_dwordx4 v[48:51], v[10:11], off
	v_pk_fma_f32 v[58:59], v[4:5], v[4:5], v[2:3]
	global_load_dwordx4 v[2:5], v[10:11], off offset:1024
	v_add_f32_e32 v7, v58, v59
	v_lshl_add_u64 v[24:25], v[22:23], 0, v[16:17]
	v_lshl_add_u64 v[22:23], v[22:23], 0, v[18:19]
	v_lshl_add_u64 v[10:11], v[10:11], 0, s[34:35]
	s_waitcnt vmcnt(1)
	v_mov_b32_e32 v66, v49
	v_mov_b32_e32 v64, v48
	s_waitcnt vmcnt(0)
	v_mov_b32_e32 v67, v3
	v_mov_b32_e32 v65, v2
	v_pk_mul_f32 v[66:67], v[66:67], v[66:67]
	v_mov_b32_e32 v60, v50
	v_mov_b32_e32 v61, v4
	v_pk_fma_f32 v[64:65], v[64:65], v[64:65], v[66:67]
	v_mov_b32_e32 v62, v51
	v_mov_b32_e32 v63, v5
	v_pk_fma_f32 v[60:61], v[60:61], v[60:61], v[64:65]
	s_nop 0
	v_pk_fma_f32 v[60:61], v[62:63], v[62:63], v[60:61]
	s_nop 0
	v_add_f32_e32 v7, v7, v60
	v_add_f32_e32 v7, v7, v61
	ds_bpermute_b32 v58, v26, v7
	s_waitcnt lgkmcnt(0)
	v_add_f32_e32 v7, v7, v58
	ds_bpermute_b32 v58, v27, v7
	s_waitcnt lgkmcnt(0)
	v_add_f32_e32 v7, v7, v58
	ds_bpermute_b32 v58, v28, v7
	s_waitcnt lgkmcnt(0)
	v_add_f32_e32 v7, v7, v58
	ds_bpermute_b32 v58, v29, v7
	s_waitcnt lgkmcnt(0)
	v_add_f32_e32 v7, v7, v58
	ds_bpermute_b32 v58, v30, v7
	s_waitcnt lgkmcnt(0)
	v_add_f32_e32 v7, v7, v58
	ds_bpermute_b32 v58, v31, v7
	s_waitcnt lgkmcnt(0)
	v_add_f32_e32 v7, v7, v58
	v_fmamk_f32 v7, v7, 0x3a800000, v179
	v_cmp_gt_f32_e32 vcc, s40, v7
	v_mul_f32_e32 v58, 0x4b800000, v7
	s_nop 0
	v_cndmask_b32_e32 v7, v7, v58, vcc
	v_rsq_f32_e32 v7, v7
	s_nop 0
	v_mul_f32_e32 v58, 0x45800000, v7
	v_cndmask_b32_e32 v58, v7, v58, vcc
	v_pk_mul_f32 v[32:33], v[32:33], v[58:59] op_sel_hi:[1,0]
	v_pk_mul_f32 v[34:35], v[34:35], v[58:59] op_sel_hi:[1,0]
	v_pk_mul_f32 v[32:33], v[36:37], v[32:33]
	v_pk_mul_f32 v[34:35], v[38:39], v[34:35]
	v_pk_fma_f32 v[32:33], v[54:55], v[32:33], v[40:41]
	v_pk_fma_f32 v[34:35], v[52:53], v[34:35], v[42:43]
	v_cvt_pk_bf16_f32 v32, v32, v33
	v_cvt_pk_bf16_f32 v33, v34, v35
	global_store_dwordx2 v[12:13], v[32:33], off offset:-1024
	global_load_dwordx4 v[32:35], v[8:9], off offset:1024
	s_nop 0
	global_load_dwordx4 v[36:39], v[20:21], off offset:1024
	global_load_dwordx4 v[40:43], v[56:57], off
	v_pk_mul_f32 v[44:45], v[44:45], v[58:59] op_sel_hi:[1,0]
	v_pk_mul_f32 v[2:3], v[2:3], v[58:59] op_sel_hi:[1,0]
	v_pk_mul_f32 v[4:5], v[4:5], v[58:59] op_sel_hi:[1,0]
	v_cmp_lt_i32_e32 vcc, s41, v6
	s_or_b64 s[10:11], vcc, s[10:11]
	s_waitcnt vmcnt(2)
	v_pk_mul_f32 v[32:33], v[44:45], v[32:33]
	s_waitcnt vmcnt(0)
	v_pk_add_f32 v[40:41], v[40:41], 1.0 op_sel_hi:[1,0]
	s_nop 0
	v_pk_fma_f32 v[32:33], v[32:33], v[40:41], v[36:37]
	v_pk_mul_f32 v[36:37], v[46:47], v[58:59] op_sel_hi:[1,0]
	v_cvt_pk_bf16_f32 v32, v32, v33
	v_pk_mul_f32 v[34:35], v[36:37], v[34:35]
	v_pk_add_f32 v[36:37], v[42:43], 1.0 op_sel_hi:[1,0]
	s_nop 0
	v_pk_fma_f32 v[34:35], v[34:35], v[36:37], v[38:39]
	s_nop 0
	v_cvt_pk_bf16_f32 v33, v34, v35
	global_store_dwordx2 v[12:13], v[32:33], off offset:-512
	global_load_dwordx4 v[32:35], v[8:9], off offset:2048
	s_nop 0
	global_load_dwordx4 v[36:39], v[20:21], off offset:2048
	global_load_dwordx4 v[40:43], v[24:25], off
	v_pk_mul_f32 v[24:25], v[48:49], v[58:59] op_sel_hi:[1,0]
	s_waitcnt vmcnt(2)
	v_pk_mul_f32 v[24:25], v[24:25], v[32:33]
	s_waitcnt vmcnt(0)
	v_pk_add_f32 v[32:33], v[40:41], 1.0 op_sel_hi:[1,0]
	s_nop 0
	v_pk_fma_f32 v[24:25], v[24:25], v[32:33], v[36:37]
	v_pk_mul_f32 v[32:33], v[50:51], v[58:59] op_sel_hi:[1,0]
	v_cvt_pk_bf16_f32 v24, v24, v25
	v_pk_mul_f32 v[32:33], v[32:33], v[34:35]
	v_pk_add_f32 v[34:35], v[42:43], 1.0 op_sel_hi:[1,0]
	s_nop 0
	v_pk_fma_f32 v[32:33], v[32:33], v[34:35], v[38:39]
	s_nop 0
	v_cvt_pk_bf16_f32 v25, v32, v33
	global_store_dwordx2 v[12:13], v[24:25], off
	global_load_dwordx4 v[32:35], v[8:9], off offset:3072
	global_load_dwordx4 v[36:39], v[20:21], off offset:3072
	s_nop 0
	global_load_dwordx4 v[20:23], v[22:23], off
	s_waitcnt vmcnt(2)
	v_pk_mul_f32 v[2:3], v[2:3], v[32:33]
	v_pk_mul_f32 v[4:5], v[4:5], v[34:35]
	s_waitcnt vmcnt(0)
	v_pk_add_f32 v[20:21], v[20:21], 1.0 op_sel_hi:[1,0]
	s_nop 0
	v_pk_fma_f32 v[2:3], v[2:3], v[20:21], v[36:37]
	v_pk_add_f32 v[20:21], v[22:23], 1.0 op_sel_hi:[1,0]
	v_cvt_pk_bf16_f32 v2, v2, v3
	v_pk_fma_f32 v[4:5], v[4:5], v[20:21], v[38:39]
	s_nop 0
	v_cvt_pk_bf16_f32 v3, v4, v5
	global_store_dwordx2 v[12:13], v[2:3], off offset:512
	v_lshl_add_u64 v[12:13], v[12:13], 0, s[36:37]
	s_andn2_b64 exec, exec, s[10:11]
	s_cbranch_execnz .LBB0_344

; #define TIDX opaque_tid()
; DI void phase_norm(const Params& p, char* wsb, int layer, int which, int mrows, bool do_convert, char* lds) {
;   const int tid = TIDX, lane = tid & 63, wid = tid >> 6;
;   const float* xs = (const float*)(wsb + OFF_XS);
;   u16* H = (u16*)(wsb + OFF_H);
;   const float* mods = (const float*)(wsb + OFF_MODS) + (size_t)layer * 9 * 9216;
;   const float* g = p.norm_g + (layer * 3 + which) * 1024;
;   const int nw = gridDim.x * 4;
; #pragma unroll 2
;   for (int row = blockIdx.x * 4 + wid; row < mrows; row += nw) {
;     const float4* xr = (const float4*)(xs + (size_t)row * 1024);
;     float4 v[4];
;     float ss = 0.f;
; #pragma unroll
;     for (int i = 0; i < 4; ++i) { v[i] = xr[lane + 64 * i]; ss += v[i].x * v[i].x + v[i].y * v[i].y + v[i].z * v[i].z + v[i].w * v[i].w; }
; #pragma unroll
;     for (int o = 32; o; o >>= 1) ss += __shfl_xor(ss, o);
;     const float r = rsqrtf(ss * (1.f / 1024.f) + 1e-6f);
.LBB0_531:
	s_or_b64 exec, exec, s[6:7]
	s_mov_b32 s10, s19
	v_mov_b32_e32 v0, v178
	s_waitcnt lgkmcnt(0)
	s_barrier
	s_movk_i32 s6, 0x4800
	v_ashrrev_i32_e32 v2, 6, v0
	v_add_u32_e32 v18, s87, v2
	v_cmp_gt_i32_e32 vcc, s6, v18
	s_and_saveexec_b64 s[6:7], vcc
	s_mov_b64 s[56:57], 0x1000
	s_cbranch_execz .LBB0_534
	v_cmp_lt_i32_e32 vcc, v187, v186
	s_mov_b64 s[54:55], s[26:27]
	v_readlane_b32 s8, v242, 0
	v_cndmask_b32_e32 v4, v185, v187, vcc
	v_cmp_lt_i32_e32 vcc, v188, v186
	v_lshlrev_b32_e32 v48, 2, v4
	s_mov_b64 s[52:53], s[24:25]
	v_cndmask_b32_e32 v4, v185, v188, vcc
	v_cmp_lt_i32_e32 vcc, v189, v186
	s_mov_b64 s[50:51], s[22:23]
	s_mov_b64 s[48:49], s[20:21]
	s_add_u32 s11, s54, s10
	v_readlane_b32 s9, v242, 1
	s_mul_i32 s18, s8, 0xc00
	v_lshlrev_b32_e32 v49, 2, v4
	v_cndmask_b32_e32 v4, v185, v189, vcc
	v_cmp_lt_i32_e32 vcc, v190, v186
	s_addc_u32 s14, s55, 0
	s_lshl_b64 s[8:9], s[18:19], 2
	v_readlane_b32 s48, v243, 37
	v_lshlrev_b32_e32 v50, 2, v4
	v_cndmask_b32_e32 v4, v185, v190, vcc
	v_cmp_lt_i32_e32 vcc, v191, v186
	v_readlane_b32 s49, v243, 38
	s_add_u32 s8, s48, s8
	v_and_b32_e32 v3, 63, v0
	v_lshlrev_b32_e32 v51, 2, v4
	v_cndmask_b32_e32 v4, v185, v191, vcc
	v_cmp_lt_i32_e32 vcc, v192, v186
	s_addc_u32 s9, s49, s9
	v_lshlrev_b32_e32 v2, 2, v3
	v_lshlrev_b32_e32 v52, 2, v4
	v_cndmask_b32_e32 v4, v185, v192, vcc
	s_add_u32 s12, s8, 0x1000
	v_lshlrev_b32_e32 v53, 2, v4
	v_or_b32_e32 v4, 0x100, v2
	s_addc_u32 s13, s9, 0
	v_readlane_b32 s8, v242, 2
	v_lshlrev_b32_e32 v6, 2, v4
	v_mov_b32_e32 v7, v1
	s_add_u32 s8, s11, s8
	v_lshl_add_u64 v[22:23], s[12:13], 0, v[6:7]
	v_or_b32_e32 v6, 0x200, v2
	s_addc_u32 s9, s14, 0
	v_lshlrev_b32_e32 v8, 2, v6
	v_mov_b32_e32 v9, v1
	s_add_u32 s8, s8, 0x7000
	v_lshl_add_u64 v[24:25], s[12:13], 0, v[8:9]
	v_or_b32_e32 v8, 0x300, v2
	s_addc_u32 s9, s9, 0
	v_lshlrev_b32_e32 v0, 4, v3
	v_lshlrev_b32_e32 v10, 2, v8
	v_mov_b32_e32 v11, v1
	v_ashrrev_i32_e32 v19, 31, v18
	v_readlane_b32 s11, v243, 1
	v_lshl_add_u64 v[20:21], s[12:13], 0, v[0:1]
	v_lshl_add_u64 v[26:27], s[12:13], 0, v[10:11]
	v_lshlrev_b64 v[10:11], 12, v[18:19]
	s_add_u32 s12, s11, s10
	v_readlane_b32 s11, v243, 2
	v_or_b32_e32 v10, v10, v0
	s_addc_u32 s13, s11, 0
	v_readlane_b32 s11, v243, 3
	v_lshl_add_u64 v[28:29], s[12:13], 0, v[10:11]
	v_lshlrev_b64 v[10:11], 11, v[18:19]
	s_add_u32 s10, s11, s10
	v_readlane_b32 s11, v243, 4
	v_readlane_b32 s34, v243, 61
	v_lshl_or_b32 v10, v3, 3, v10
	s_addc_u32 s11, s11, 0
	v_readlane_b32 s35, v243, 62
	v_lshl_add_u64 v[30:31], s[10:11], 0, v[10:11]
	s_mov_b64 s[10:11], 0
	v_lshlrev_b32_e32 v0, 2, v2
	v_lshlrev_b32_e32 v32, 2, v4
	v_lshlrev_b32_e32 v34, 2, v6
	v_lshlrev_b32_e32 v36, 2, v8
	v_readlane_b32 s50, v243, 39
	v_readlane_b32 s51, v243, 40
	v_readlane_b32 s52, v243, 41
	v_readlane_b32 s53, v243, 42
	v_readlane_b32 s54, v243, 43
	v_readlane_b32 s55, v243, 44
	s_cmpk_lg_u32 s92, 0x200
	s_cbranch_scc1 .LBB0_533
	global_load_dwordx4 v[138:141], v[20:21], off
	global_load_dwordx4 v[142:145], v[22:23], off
	global_load_dwordx4 v[246:249], v[24:25], off
	global_load_dwordx4 v[250:253], v[26:27], off
	s_mov_b64 s[64:65], s[8:9]
	s_add_u32 s66, s8, 0x1000
	s_addc_u32 s67, s9, 0
	global_load_dwordx4 v[64:67], v[28:29], off offset:-2048
	global_load_dwordx4 v[68:71], v[28:29], off offset:-1024
	global_load_dwordx4 v[72:75], v[28:29], off
	global_load_dwordx4 v[76:79], v[28:29], off offset:1024
	v_lshl_add_u64 v[28:29], v[28:29], 0, s[34:35]
	global_load_dwordx4 v[80:83], v0, s[64:65]
	global_load_dwordx4 v[84:87], v0, s[64:65] offset:1024
	global_load_dwordx4 v[88:91], v0, s[64:65] offset:2048
	global_load_dwordx4 v[92:95], v0, s[64:65] offset:3072
	global_load_dwordx4 v[96:99], v0, s[66:67]
	global_load_dwordx4 v[100:103], v0, s[66:67] offset:1024
	global_load_dwordx4 v[104:107], v0, s[66:67] offset:2048
	global_load_dwordx4 v[108:111], v0, s[66:67] offset:3072
	s_add_u32 s64, s64, 0x9000
	s_addc_u32 s65, s65, 0
	s_add_u32 s66, s66, 0x9000
	s_addc_u32 s67, s67, 0
	global_load_dwordx4 v[214:217], v[28:29], off offset:-2048
	global_load_dwordx4 v[218:221], v[28:29], off offset:-1024
	global_load_dwordx4 v[222:225], v[28:29], off
	global_load_dwordx4 v[226:229], v[28:29], off offset:1024
	v_lshl_add_u64 v[28:29], v[28:29], 0, s[34:35]
	global_load_dwordx4 v[112:115], v0, s[64:65]
	global_load_dwordx4 v[116:119], v0, s[64:65] offset:1024
	global_load_dwordx4 v[120:123], v0, s[64:65] offset:2048
	global_load_dwordx4 v[126:129], v0, s[64:65] offset:3072
	global_load_dwordx4 v[230:233], v0, s[66:67]
	global_load_dwordx4 v[234:237], v0, s[66:67] offset:1024
	global_load_dwordx4 v[238:241], v0, s[66:67] offset:2048
	global_load_dwordx4 v[134:137], v0, s[66:67] offset:3072
	s_add_u32 s64, s64, 0x9000
	s_addc_u32 s65, s65, 0
	s_add_u32 s66, s66, 0x9000
	s_addc_u32 s67, s67, 0
	s_waitcnt vmcnt(12)
	v_mul_f32_e32 v37, v65, v65
	v_fmac_f32_e32 v37, v64, v64
	v_fmac_f32_e32 v37, v66, v66
	v_fmac_f32_e32 v37, v67, v67
	v_mul_f32_e32 v38, v69, v69
	v_fmac_f32_e32 v38, v68, v68
	v_fmac_f32_e32 v38, v70, v70
	v_fmac_f32_e32 v38, v71, v71
	v_mul_f32_e32 v39, v73, v73
	v_fmac_f32_e32 v39, v72, v72
	v_fmac_f32_e32 v39, v74, v74
	v_fmac_f32_e32 v39, v75, v75
	v_mul_f32_e32 v40, v77, v77
	v_fmac_f32_e32 v40, v76, v76
	v_fmac_f32_e32 v40, v78, v78
	v_fmac_f32_e32 v40, v79, v79
	v_add_f32_e32 v255, v37, v38
	v_add_f32_e32 v255, v255, v39
	v_add_f32_e32 v255, v255, v40
	ds_bpermute_b32 v254, v48, v255
	s_waitcnt lgkmcnt(0)
	v_add_f32_e32 v255, v255, v254
	ds_bpermute_b32 v254, v49, v255
	s_waitcnt lgkmcnt(0)
	v_add_f32_e32 v255, v255, v254
	ds_bpermute_b32 v254, v50, v255
	s_waitcnt lgkmcnt(0)
; DI void phase_norm(const Params& p, char* wsb, int layer, int which, int mrows, bool do_convert, char* lds) {
;     ...
;   for (int row = blockIdx.x * 4 + wid; row < mrows; row += nw) {
;     const float4* xr = (const float4*)(xs + (size_t)row * 1024);
;     float4 v[4];
;     float ss = 0.f;
; #pragma unroll
;     for (int i = 0; i < 4; ++i) { v[i] = xr[lane + 64 * i]; ss += v[i].x * v[i].x + v[i].y * v[i].y + v[i].z * v[i].z + v[i].w * v[i].w; }
; #pragma unroll
;     for (int o = 32; o; o >>= 1) ss += __shfl_xor(ss, o);
;     const float r = rsqrtf(ss * (1.f / 1024.f) + 1e-6f);
;     const int mr = row < TL ? (row >> 11) : 8;
;     const float* sh = mods + (size_t)mr * 9216 + (3 * which) * 1024;
;     const float* sc = sh + 1024;
; #pragma unroll
;     for (int i = 0; i < 4; ++i) {
;       int col = (lane + 64 * i) * 4;
;       float4 gg = *(const float4*)(g + col), s4 = *(const float4*)(sh + col), c4 = *(const float4*)(sc + col);
;       float o0 = v[i].x * r * gg.x * (1.f + c4.x) + s4.x;
;       float o1 = v[i].y * r * gg.y * (1.f + c4.y) + s4.y;
;       float o2 = v[i].z * r * gg.z * (1.f + c4.z) + s4.z;
;       float o3 = v[i].w * r * gg.w * (1.f + c4.w) + s4.w;
;       *(uint2*)(H + (size_t)row * 1024 + col) = make_uint2(pack2(o0, o1), pack2(o2, o3));
;     }
	v_add_f32_e32 v255, v255, v254
	ds_bpermute_b32 v254, v51, v255
	s_waitcnt lgkmcnt(0)
	v_add_f32_e32 v255, v255, v254
	ds_bpermute_b32 v254, v52, v255
	s_waitcnt lgkmcnt(0)
	v_add_f32_e32 v255, v255, v254
	ds_bpermute_b32 v254, v53, v255
	s_waitcnt lgkmcnt(0)
	v_add_f32_e32 v255, v255, v254
	v_fmamk_f32 v255, v255, 0x3a800000, v179
	v_cmp_gt_f32_e32 vcc, s46, v255
	v_mul_f32_e32 v254, 0x4b800000, v255
	s_nop 0
	v_cndmask_b32_e32 v255, v255, v254, vcc
	v_rsq_f32_e32 v255, v255
	s_nop 0
	v_mul_f32_e32 v254, 0x45800000, v255
	v_cndmask_b32_e32 v56, v255, v254, vcc
	s_nop 0
	v_pk_mul_f32 v[64:65], v[64:65], v[56:57] op_sel_hi:[1,0]
	v_pk_mul_f32 v[66:67], v[66:67], v[56:57] op_sel_hi:[1,0]
	v_pk_add_f32 v[96:97], v[96:97], 1.0 op_sel_hi:[1,0]
	v_pk_add_f32 v[98:99], v[98:99], 1.0 op_sel_hi:[1,0]
	v_pk_mul_f32 v[64:65], v[138:139], v[64:65]
	v_pk_mul_f32 v[66:67], v[140:141], v[66:67]
	v_pk_fma_f32 v[64:65], v[96:97], v[64:65], v[80:81]
	v_pk_fma_f32 v[66:67], v[98:99], v[66:67], v[82:83]
	v_cvt_pk_bf16_f32 v58, v64, v65
	v_cvt_pk_bf16_f32 v59, v66, v67
	global_store_dwordx2 v[30:31], v[58:59], off offset:-1024
	v_pk_mul_f32 v[68:69], v[68:69], v[56:57] op_sel_hi:[1,0]
	v_pk_mul_f32 v[70:71], v[70:71], v[56:57] op_sel_hi:[1,0]
	v_pk_add_f32 v[100:101], v[100:101], 1.0 op_sel_hi:[1,0]
	v_pk_add_f32 v[102:103], v[102:103], 1.0 op_sel_hi:[1,0]
	v_pk_mul_f32 v[68:69], v[142:143], v[68:69]
	v_pk_mul_f32 v[70:71], v[144:145], v[70:71]
	v_pk_fma_f32 v[68:69], v[100:101], v[68:69], v[84:85]
	v_pk_fma_f32 v[70:71], v[102:103], v[70:71], v[86:87]
	v_cvt_pk_bf16_f32 v60, v68, v69
	v_cvt_pk_bf16_f32 v61, v70, v71
	global_store_dwordx2 v[30:31], v[60:61], off offset:-512
	v_pk_mul_f32 v[72:73], v[72:73], v[56:57] op_sel_hi:[1,0]
	v_pk_mul_f32 v[74:75], v[74:75], v[56:57] op_sel_hi:[1,0]
	v_pk_add_f32 v[104:105], v[104:105], 1.0 op_sel_hi:[1,0]
	v_pk_add_f32 v[106:107], v[106:107], 1.0 op_sel_hi:[1,0]
	v_pk_mul_f32 v[72:73], v[246:247], v[72:73]
	v_pk_mul_f32 v[74:75], v[248:249], v[74:75]
	v_pk_fma_f32 v[72:73], v[104:105], v[72:73], v[88:89]
	v_pk_fma_f32 v[74:75], v[106:107], v[74:75], v[90:91]
	v_cvt_pk_bf16_f32 v58, v72, v73
	v_cvt_pk_bf16_f32 v59, v74, v75
	global_store_dwordx2 v[30:31], v[58:59], off
	v_pk_mul_f32 v[76:77], v[76:77], v[56:57] op_sel_hi:[1,0]
	v_pk_mul_f32 v[78:79], v[78:79], v[56:57] op_sel_hi:[1,0]
	v_pk_add_f32 v[108:109], v[108:109], 1.0 op_sel_hi:[1,0]
	v_pk_add_f32 v[110:111], v[110:111], 1.0 op_sel_hi:[1,0]
	v_pk_mul_f32 v[76:77], v[250:251], v[76:77]
	v_pk_mul_f32 v[78:79], v[252:253], v[78:79]
	v_pk_fma_f32 v[76:77], v[108:109], v[76:77], v[92:93]
	v_pk_fma_f32 v[78:79], v[110:111], v[78:79], v[94:95]
	v_cvt_pk_bf16_f32 v60, v76, v77
	v_cvt_pk_bf16_f32 v61, v78, v79
	global_store_dwordx2 v[30:31], v[60:61], off offset:512
	v_lshl_add_u64 v[30:31], v[30:31], 0, s[36:37]
	global_load_dwordx4 v[64:67], v[28:29], off offset:-2048
	global_load_dwordx4 v[68:71], v[28:29], off offset:-1024
	global_load_dwordx4 v[72:75], v[28:29], off
	global_load_dwordx4 v[76:79], v[28:29], off offset:1024
	v_lshl_add_u64 v[28:29], v[28:29], 0, s[34:35]
	global_load_dwordx4 v[80:83], v0, s[64:65]
	global_load_dwordx4 v[84:87], v0, s[64:65] offset:1024
	global_load_dwordx4 v[88:91], v0, s[64:65] offset:2048
	global_load_dwordx4 v[92:95], v0, s[64:65] offset:3072
	global_load_dwordx4 v[96:99], v0, s[66:67]
	global_load_dwordx4 v[100:103], v0, s[66:67] offset:1024
	global_load_dwordx4 v[104:107], v0, s[66:67] offset:2048
	global_load_dwordx4 v[108:111], v0, s[66:67] offset:3072
	s_add_u32 s64, s64, 0x9000
	s_addc_u32 s65, s65, 0
	s_add_u32 s66, s66, 0x9000
	s_addc_u32 s67, s67, 0
	s_waitcnt vmcnt(16)
	v_mul_f32_e32 v37, v215, v215
	v_fmac_f32_e32 v37, v214, v214
	v_fmac_f32_e32 v37, v216, v216
	v_fmac_f32_e32 v37, v217, v217
	v_mul_f32_e32 v38, v219, v219
	v_fmac_f32_e32 v38, v218, v218
	v_fmac_f32_e32 v38, v220, v220
	v_fmac_f32_e32 v38, v221, v221
	v_mul_f32_e32 v39, v223, v223
	v_fmac_f32_e32 v39, v222, v222
	v_fmac_f32_e32 v39, v224, v224
	v_fmac_f32_e32 v39, v225, v225
	v_mul_f32_e32 v40, v227, v227
	v_fmac_f32_e32 v40, v226, v226
	v_fmac_f32_e32 v40, v228, v228
	v_fmac_f32_e32 v40, v229, v229
	v_add_f32_e32 v255, v37, v38
	v_add_f32_e32 v255, v255, v39
	v_add_f32_e32 v255, v255, v40
	ds_bpermute_b32 v254, v48, v255
	s_waitcnt lgkmcnt(0)
	v_add_f32_e32 v255, v255, v254
	ds_bpermute_b32 v254, v49, v255
	s_waitcnt lgkmcnt(0)
	v_add_f32_e32 v255, v255, v254
	ds_bpermute_b32 v254, v50, v255
	s_waitcnt lgkmcnt(0)
	v_add_f32_e32 v255, v255, v254
	ds_bpermute_b32 v254, v51, v255
	s_waitcnt lgkmcnt(0)
	v_add_f32_e32 v255, v255, v254
	ds_bpermute_b32 v254, v52, v255
	s_waitcnt lgkmcnt(0)
	v_add_f32_e32 v255, v255, v254
	ds_bpermute_b32 v254, v53, v255
	s_waitcnt lgkmcnt(0)
; DI void phase_norm(const Params& p, char* wsb, int layer, int which, int mrows, bool do_convert, char* lds) {
;     ...
;   for (int row = blockIdx.x * 4 + wid; row < mrows; row += nw) {
;     const float4* xr = (const float4*)(xs + (size_t)row * 1024);
;     float4 v[4];
;     float ss = 0.f;
; #pragma unroll
;     for (int i = 0; i < 4; ++i) { v[i] = xr[lane + 64 * i]; ss += v[i].x * v[i].x + v[i].y * v[i].y + v[i].z * v[i].z + v[i].w * v[i].w; }
; #pragma unroll
;     for (int o = 32; o; o >>= 1) ss += __shfl_xor(ss, o);
;     const float r = rsqrtf(ss * (1.f / 1024.f) + 1e-6f);
;     const int mr = row < TL ? (row >> 11) : 8;
;     const float* sh = mods + (size_t)mr * 9216 + (3 * which) * 1024;
;     const float* sc = sh + 1024;
; #pragma unroll
;     for (int i = 0; i < 4; ++i) {
;       int col = (lane + 64 * i) * 4;
;       float4 gg = *(const float4*)(g + col), s4 = *(const float4*)(sh + col), c4 = *(const float4*)(sc + col);
;       float o0 = v[i].x * r * gg.x * (1.f + c4.x) + s4.x;
;       float o1 = v[i].y * r * gg.y * (1.f + c4.y) + s4.y;
;       float o2 = v[i].z * r * gg.z * (1.f + c4.z) + s4.z;
;       float o3 = v[i].w * r * gg.w * (1.f + c4.w) + s4.w;
;       *(uint2*)(H + (size_t)row * 1024 + col) = make_uint2(pack2(o0, o1), pack2(o2, o3));
;     }
	v_add_f32_e32 v255, v255, v254
	v_fmamk_f32 v255, v255, 0x3a800000, v179
	v_cmp_gt_f32_e32 vcc, s46, v255
	v_mul_f32_e32 v254, 0x4b800000, v255
	s_nop 0
	v_cndmask_b32_e32 v255, v255, v254, vcc
	v_rsq_f32_e32 v255, v255
	s_nop 0
	v_mul_f32_e32 v254, 0x45800000, v255
	v_cndmask_b32_e32 v56, v255, v254, vcc
	s_nop 0
	v_pk_mul_f32 v[214:215], v[214:215], v[56:57] op_sel_hi:[1,0]
	v_pk_mul_f32 v[216:217], v[216:217], v[56:57] op_sel_hi:[1,0]
	v_pk_add_f32 v[230:231], v[230:231], 1.0 op_sel_hi:[1,0]
	v_pk_add_f32 v[232:233], v[232:233], 1.0 op_sel_hi:[1,0]
	v_pk_mul_f32 v[214:215], v[138:139], v[214:215]
	v_pk_mul_f32 v[216:217], v[140:141], v[216:217]
	v_pk_fma_f32 v[214:215], v[230:231], v[214:215], v[112:113]
	v_pk_fma_f32 v[216:217], v[232:233], v[216:217], v[114:115]
	v_cvt_pk_bf16_f32 v58, v214, v215
	v_cvt_pk_bf16_f32 v59, v216, v217
	global_store_dwordx2 v[30:31], v[58:59], off offset:-1024
	v_pk_mul_f32 v[218:219], v[218:219], v[56:57] op_sel_hi:[1,0]
	v_pk_mul_f32 v[220:221], v[220:221], v[56:57] op_sel_hi:[1,0]
	v_pk_add_f32 v[234:235], v[234:235], 1.0 op_sel_hi:[1,0]
	v_pk_add_f32 v[236:237], v[236:237], 1.0 op_sel_hi:[1,0]
	v_pk_mul_f32 v[218:219], v[142:143], v[218:219]
	v_pk_mul_f32 v[220:221], v[144:145], v[220:221]
	v_pk_fma_f32 v[218:219], v[234:235], v[218:219], v[116:117]
	v_pk_fma_f32 v[220:221], v[236:237], v[220:221], v[118:119]
	v_cvt_pk_bf16_f32 v60, v218, v219
	v_cvt_pk_bf16_f32 v61, v220, v221
	global_store_dwordx2 v[30:31], v[60:61], off offset:-512
	v_pk_mul_f32 v[222:223], v[222:223], v[56:57] op_sel_hi:[1,0]
	v_pk_mul_f32 v[224:225], v[224:225], v[56:57] op_sel_hi:[1,0]
	v_pk_add_f32 v[238:239], v[238:239], 1.0 op_sel_hi:[1,0]
	v_pk_add_f32 v[240:241], v[240:241], 1.0 op_sel_hi:[1,0]
	v_pk_mul_f32 v[222:223], v[246:247], v[222:223]
	v_pk_mul_f32 v[224:225], v[248:249], v[224:225]
	v_pk_fma_f32 v[222:223], v[238:239], v[222:223], v[120:121]
	v_pk_fma_f32 v[224:225], v[240:241], v[224:225], v[122:123]
	v_cvt_pk_bf16_f32 v58, v222, v223
	v_cvt_pk_bf16_f32 v59, v224, v225
	global_store_dwordx2 v[30:31], v[58:59], off
	v_pk_mul_f32 v[226:227], v[226:227], v[56:57] op_sel_hi:[1,0]
	v_pk_mul_f32 v[228:229], v[228:229], v[56:57] op_sel_hi:[1,0]
	v_pk_add_f32 v[134:135], v[134:135], 1.0 op_sel_hi:[1,0]
	v_pk_add_f32 v[136:137], v[136:137], 1.0 op_sel_hi:[1,0]
	v_pk_mul_f32 v[226:227], v[250:251], v[226:227]
	v_pk_mul_f32 v[228:229], v[252:253], v[228:229]
	v_pk_fma_f32 v[226:227], v[134:135], v[226:227], v[126:127]
	v_pk_fma_f32 v[228:229], v[136:137], v[228:229], v[128:129]
	v_cvt_pk_bf16_f32 v60, v226, v227
	v_cvt_pk_bf16_f32 v61, v228, v229
	global_store_dwordx2 v[30:31], v[60:61], off offset:512
	v_lshl_add_u64 v[30:31], v[30:31], 0, s[36:37]
	global_load_dwordx4 v[214:217], v[28:29], off offset:-2048
	global_load_dwordx4 v[218:221], v[28:29], off offset:-1024
	global_load_dwordx4 v[222:225], v[28:29], off
	global_load_dwordx4 v[226:229], v[28:29], off offset:1024
	v_lshl_add_u64 v[28:29], v[28:29], 0, s[34:35]
	global_load_dwordx4 v[112:115], v0, s[64:65]
	global_load_dwordx4 v[116:119], v0, s[64:65] offset:1024
	global_load_dwordx4 v[120:123], v0, s[64:65] offset:2048
	global_load_dwordx4 v[126:129], v0, s[64:65] offset:3072
	global_load_dwordx4 v[230:233], v0, s[66:67]
	global_load_dwordx4 v[234:237], v0, s[66:67] offset:1024
	global_load_dwordx4 v[238:241], v0, s[66:67] offset:2048
	global_load_dwordx4 v[134:137], v0, s[66:67] offset:3072
	s_add_u32 s64, s64, 0x9000
	s_addc_u32 s65, s65, 0
	s_add_u32 s66, s66, 0x9000
	s_addc_u32 s67, s67, 0
	s_waitcnt vmcnt(16)
	v_mul_f32_e32 v37, v65, v65
	v_fmac_f32_e32 v37, v64, v64
	v_fmac_f32_e32 v37, v66, v66
	v_fmac_f32_e32 v37, v67, v67
	v_mul_f32_e32 v38, v69, v69
	v_fmac_f32_e32 v38, v68, v68
	v_fmac_f32_e32 v38, v70, v70
	v_fmac_f32_e32 v38, v71, v71
	v_mul_f32_e32 v39, v73, v73
	v_fmac_f32_e32 v39, v72, v72
	v_fmac_f32_e32 v39, v74, v74
	v_fmac_f32_e32 v39, v75, v75
	v_mul_f32_e32 v40, v77, v77
	v_fmac_f32_e32 v40, v76, v76
	v_fmac_f32_e32 v40, v78, v78
	v_fmac_f32_e32 v40, v79, v79
	v_add_f32_e32 v255, v37, v38
	v_add_f32_e32 v255, v255, v39
	v_add_f32_e32 v255, v255, v40
	ds_bpermute_b32 v254, v48, v255
	s_waitcnt lgkmcnt(0)
	v_add_f32_e32 v255, v255, v254
	ds_bpermute_b32 v254, v49, v255
	s_waitcnt lgkmcnt(0)
	v_add_f32_e32 v255, v255, v254
	ds_bpermute_b32 v254, v50, v255
	s_waitcnt lgkmcnt(0)
	v_add_f32_e32 v255, v255, v254
	ds_bpermute_b32 v254, v51, v255
	s_waitcnt lgkmcnt(0)
	v_add_f32_e32 v255, v255, v254
	ds_bpermute_b32 v254, v52, v255
	s_waitcnt lgkmcnt(0)
	v_add_f32_e32 v255, v255, v254
	ds_bpermute_b32 v254, v53, v255
	s_waitcnt lgkmcnt(0)
; DI void phase_norm(const Params& p, char* wsb, int layer, int which, int mrows, bool do_convert, char* lds) {
;     ...
;   for (int row = blockIdx.x * 4 + wid; row < mrows; row += nw) {
;     const float4* xr = (const float4*)(xs + (size_t)row * 1024);
;     float4 v[4];
;     float ss = 0.f;
; #pragma unroll
;     for (int i = 0; i < 4; ++i) { v[i] = xr[lane + 64 * i]; ss += v[i].x * v[i].x + v[i].y * v[i].y + v[i].z * v[i].z + v[i].w * v[i].w; }
; #pragma unroll
;     for (int o = 32; o; o >>= 1) ss += __shfl_xor(ss, o);
;     const float r = rsqrtf(ss * (1.f / 1024.f) + 1e-6f);
;     const int mr = row < TL ? (row >> 11) : 8;
;     const float* sh = mods + (size_t)mr * 9216 + (3 * which) * 1024;
;     const float* sc = sh + 1024;
; #pragma unroll
;     for (int i = 0; i < 4; ++i) {
;       int col = (lane + 64 * i) * 4;
;       float4 gg = *(const float4*)(g + col), s4 = *(const float4*)(sh + col), c4 = *(const float4*)(sc + col);
;       float o0 = v[i].x * r * gg.x * (1.f + c4.x) + s4.x;
;       float o1 = v[i].y * r * gg.y * (1.f + c4.y) + s4.y;
;       float o2 = v[i].z * r * gg.z * (1.f + c4.z) + s4.z;
;       float o3 = v[i].w * r * gg.w * (1.f + c4.w) + s4.w;
;       *(uint2*)(H + (size_t)row * 1024 + col) = make_uint2(pack2(o0, o1), pack2(o2, o3));
;     }
	v_add_f32_e32 v255, v255, v254
	v_fmamk_f32 v255, v255, 0x3a800000, v179
	v_cmp_gt_f32_e32 vcc, s46, v255
	v_mul_f32_e32 v254, 0x4b800000, v255
	s_nop 0
	v_cndmask_b32_e32 v255, v255, v254, vcc
	v_rsq_f32_e32 v255, v255
	s_nop 0
	v_mul_f32_e32 v254, 0x45800000, v255
	v_cndmask_b32_e32 v56, v255, v254, vcc
	s_nop 0
	v_pk_mul_f32 v[64:65], v[64:65], v[56:57] op_sel_hi:[1,0]
	v_pk_mul_f32 v[66:67], v[66:67], v[56:57] op_sel_hi:[1,0]
	v_pk_add_f32 v[96:97], v[96:97], 1.0 op_sel_hi:[1,0]
	v_pk_add_f32 v[98:99], v[98:99], 1.0 op_sel_hi:[1,0]
	v_pk_mul_f32 v[64:65], v[138:139], v[64:65]
	v_pk_mul_f32 v[66:67], v[140:141], v[66:67]
	v_pk_fma_f32 v[64:65], v[96:97], v[64:65], v[80:81]
	v_pk_fma_f32 v[66:67], v[98:99], v[66:67], v[82:83]
	v_cvt_pk_bf16_f32 v58, v64, v65
	v_cvt_pk_bf16_f32 v59, v66, v67
	global_store_dwordx2 v[30:31], v[58:59], off offset:-1024
	v_pk_mul_f32 v[68:69], v[68:69], v[56:57] op_sel_hi:[1,0]
	v_pk_mul_f32 v[70:71], v[70:71], v[56:57] op_sel_hi:[1,0]
	v_pk_add_f32 v[100:101], v[100:101], 1.0 op_sel_hi:[1,0]
	v_pk_add_f32 v[102:103], v[102:103], 1.0 op_sel_hi:[1,0]
	v_pk_mul_f32 v[68:69], v[142:143], v[68:69]
	v_pk_mul_f32 v[70:71], v[144:145], v[70:71]
	v_pk_fma_f32 v[68:69], v[100:101], v[68:69], v[84:85]
	v_pk_fma_f32 v[70:71], v[102:103], v[70:71], v[86:87]
	v_cvt_pk_bf16_f32 v60, v68, v69
	v_cvt_pk_bf16_f32 v61, v70, v71
	global_store_dwordx2 v[30:31], v[60:61], off offset:-512
	v_pk_mul_f32 v[72:73], v[72:73], v[56:57] op_sel_hi:[1,0]
	v_pk_mul_f32 v[74:75], v[74:75], v[56:57] op_sel_hi:[1,0]
	v_pk_add_f32 v[104:105], v[104:105], 1.0 op_sel_hi:[1,0]
	v_pk_add_f32 v[106:107], v[106:107], 1.0 op_sel_hi:[1,0]
	v_pk_mul_f32 v[72:73], v[246:247], v[72:73]
	v_pk_mul_f32 v[74:75], v[248:249], v[74:75]
	v_pk_fma_f32 v[72:73], v[104:105], v[72:73], v[88:89]
	v_pk_fma_f32 v[74:75], v[106:107], v[74:75], v[90:91]
	v_cvt_pk_bf16_f32 v58, v72, v73
	v_cvt_pk_bf16_f32 v59, v74, v75
	global_store_dwordx2 v[30:31], v[58:59], off
	v_pk_mul_f32 v[76:77], v[76:77], v[56:57] op_sel_hi:[1,0]
	v_pk_mul_f32 v[78:79], v[78:79], v[56:57] op_sel_hi:[1,0]
	v_pk_add_f32 v[108:109], v[108:109], 1.0 op_sel_hi:[1,0]
	v_pk_add_f32 v[110:111], v[110:111], 1.0 op_sel_hi:[1,0]
	v_pk_mul_f32 v[76:77], v[250:251], v[76:77]
	v_pk_mul_f32 v[78:79], v[252:253], v[78:79]
	v_pk_fma_f32 v[76:77], v[108:109], v[76:77], v[92:93]
	v_pk_fma_f32 v[78:79], v[110:111], v[78:79], v[94:95]
	v_cvt_pk_bf16_f32 v60, v76, v77
	v_cvt_pk_bf16_f32 v61, v78, v79
	global_store_dwordx2 v[30:31], v[60:61], off offset:512
	v_lshl_add_u64 v[30:31], v[30:31], 0, s[36:37]
	global_load_dwordx4 v[64:67], v[28:29], off offset:-2048
	global_load_dwordx4 v[68:71], v[28:29], off offset:-1024
	global_load_dwordx4 v[72:75], v[28:29], off
	global_load_dwordx4 v[76:79], v[28:29], off offset:1024
	v_lshl_add_u64 v[28:29], v[28:29], 0, s[34:35]
	global_load_dwordx4 v[80:83], v0, s[64:65]
	global_load_dwordx4 v[84:87], v0, s[64:65] offset:1024
	global_load_dwordx4 v[88:91], v0, s[64:65] offset:2048
	global_load_dwordx4 v[92:95], v0, s[64:65] offset:3072
	global_load_dwordx4 v[96:99], v0, s[66:67]
	global_load_dwordx4 v[100:103], v0, s[66:67] offset:1024
	global_load_dwordx4 v[104:107], v0, s[66:67] offset:2048
	global_load_dwordx4 v[108:111], v0, s[66:67] offset:3072
	s_add_u32 s64, s64, 0x9000
	s_addc_u32 s65, s65, 0
	s_add_u32 s66, s66, 0x9000
	s_addc_u32 s67, s67, 0
	s_waitcnt vmcnt(16)
	v_mul_f32_e32 v37, v215, v215
	v_fmac_f32_e32 v37, v214, v214
	v_fmac_f32_e32 v37, v216, v216
	v_fmac_f32_e32 v37, v217, v217
	v_mul_f32_e32 v38, v219, v219
	v_fmac_f32_e32 v38, v218, v218
	v_fmac_f32_e32 v38, v220, v220
	v_fmac_f32_e32 v38, v221, v221
	v_mul_f32_e32 v39, v223, v223
	v_fmac_f32_e32 v39, v222, v222
	v_fmac_f32_e32 v39, v224, v224
	v_fmac_f32_e32 v39, v225, v225
	v_mul_f32_e32 v40, v227, v227
	v_fmac_f32_e32 v40, v226, v226
	v_fmac_f32_e32 v40, v228, v228
	v_fmac_f32_e32 v40, v229, v229
	v_add_f32_e32 v255, v37, v38
	v_add_f32_e32 v255, v255, v39
	v_add_f32_e32 v255, v255, v40
	ds_bpermute_b32 v254, v48, v255
	s_waitcnt lgkmcnt(0)
	v_add_f32_e32 v255, v255, v254
	ds_bpermute_b32 v254, v49, v255
	s_waitcnt lgkmcnt(0)
	v_add_f32_e32 v255, v255, v254
	ds_bpermute_b32 v254, v50, v255
	s_waitcnt lgkmcnt(0)
	v_add_f32_e32 v255, v255, v254
	ds_bpermute_b32 v254, v51, v255
	s_waitcnt lgkmcnt(0)
	v_add_f32_e32 v255, v255, v254
	ds_bpermute_b32 v254, v52, v255
	s_waitcnt lgkmcnt(0)
	v_add_f32_e32 v255, v255, v254
	ds_bpermute_b32 v254, v53, v255
	s_waitcnt lgkmcnt(0)
; DI void phase_norm(const Params& p, char* wsb, int layer, int which, int mrows, bool do_convert, char* lds) {
;     ...
;   for (int row = blockIdx.x * 4 + wid; row < mrows; row += nw) {
;     const float4* xr = (const float4*)(xs + (size_t)row * 1024);
;     float4 v[4];
;     float ss = 0.f;
; #pragma unroll
;     for (int i = 0; i < 4; ++i) { v[i] = xr[lane + 64 * i]; ss += v[i].x * v[i].x + v[i].y * v[i].y + v[i].z * v[i].z + v[i].w * v[i].w; }
; #pragma unroll
;     for (int o = 32; o; o >>= 1) ss += __shfl_xor(ss, o);
;     const float r = rsqrtf(ss * (1.f / 1024.f) + 1e-6f);
;     const int mr = row < TL ? (row >> 11) : 8;
;     const float* sh = mods + (size_t)mr * 9216 + (3 * which) * 1024;
;     const float* sc = sh + 1024;
; #pragma unroll
;     for (int i = 0; i < 4; ++i) {
;       int col = (lane + 64 * i) * 4;
;       float4 gg = *(const float4*)(g + col), s4 = *(const float4*)(sh + col), c4 = *(const float4*)(sc + col);
;       float o0 = v[i].x * r * gg.x * (1.f + c4.x) + s4.x;
;       float o1 = v[i].y * r * gg.y * (1.f + c4.y) + s4.y;
;       float o2 = v[i].z * r * gg.z * (1.f + c4.z) + s4.z;
;       float o3 = v[i].w * r * gg.w * (1.f + c4.w) + s4.w;
;       *(uint2*)(H + (size_t)row * 1024 + col) = make_uint2(pack2(o0, o1), pack2(o2, o3));
;     }
	v_add_f32_e32 v255, v255, v254
	v_fmamk_f32 v255, v255, 0x3a800000, v179
	v_cmp_gt_f32_e32 vcc, s46, v255
	v_mul_f32_e32 v254, 0x4b800000, v255
	s_nop 0
	v_cndmask_b32_e32 v255, v255, v254, vcc
	v_rsq_f32_e32 v255, v255
	s_nop 0
	v_mul_f32_e32 v254, 0x45800000, v255
	v_cndmask_b32_e32 v56, v255, v254, vcc
	s_nop 0
	v_pk_mul_f32 v[214:215], v[214:215], v[56:57] op_sel_hi:[1,0]
	v_pk_mul_f32 v[216:217], v[216:217], v[56:57] op_sel_hi:[1,0]
	v_pk_add_f32 v[230:231], v[230:231], 1.0 op_sel_hi:[1,0]
	v_pk_add_f32 v[232:233], v[232:233], 1.0 op_sel_hi:[1,0]
	v_pk_mul_f32 v[214:215], v[138:139], v[214:215]
	v_pk_mul_f32 v[216:217], v[140:141], v[216:217]
	v_pk_fma_f32 v[214:215], v[230:231], v[214:215], v[112:113]
	v_pk_fma_f32 v[216:217], v[232:233], v[216:217], v[114:115]
	v_cvt_pk_bf16_f32 v58, v214, v215
	v_cvt_pk_bf16_f32 v59, v216, v217
	global_store_dwordx2 v[30:31], v[58:59], off offset:-1024
	v_pk_mul_f32 v[218:219], v[218:219], v[56:57] op_sel_hi:[1,0]
	v_pk_mul_f32 v[220:221], v[220:221], v[56:57] op_sel_hi:[1,0]
	v_pk_add_f32 v[234:235], v[234:235], 1.0 op_sel_hi:[1,0]
	v_pk_add_f32 v[236:237], v[236:237], 1.0 op_sel_hi:[1,0]
	v_pk_mul_f32 v[218:219], v[142:143], v[218:219]
	v_pk_mul_f32 v[220:221], v[144:145], v[220:221]
	v_pk_fma_f32 v[218:219], v[234:235], v[218:219], v[116:117]
	v_pk_fma_f32 v[220:221], v[236:237], v[220:221], v[118:119]
	v_cvt_pk_bf16_f32 v60, v218, v219
	v_cvt_pk_bf16_f32 v61, v220, v221
	global_store_dwordx2 v[30:31], v[60:61], off offset:-512
	v_pk_mul_f32 v[222:223], v[222:223], v[56:57] op_sel_hi:[1,0]
	v_pk_mul_f32 v[224:225], v[224:225], v[56:57] op_sel_hi:[1,0]
	v_pk_add_f32 v[238:239], v[238:239], 1.0 op_sel_hi:[1,0]
	v_pk_add_f32 v[240:241], v[240:241], 1.0 op_sel_hi:[1,0]
	v_pk_mul_f32 v[222:223], v[246:247], v[222:223]
	v_pk_mul_f32 v[224:225], v[248:249], v[224:225]
	v_pk_fma_f32 v[222:223], v[238:239], v[222:223], v[120:121]
	v_pk_fma_f32 v[224:225], v[240:241], v[224:225], v[122:123]
	v_cvt_pk_bf16_f32 v58, v222, v223
	v_cvt_pk_bf16_f32 v59, v224, v225
	global_store_dwordx2 v[30:31], v[58:59], off
	v_pk_mul_f32 v[226:227], v[226:227], v[56:57] op_sel_hi:[1,0]
	v_pk_mul_f32 v[228:229], v[228:229], v[56:57] op_sel_hi:[1,0]
	v_pk_add_f32 v[134:135], v[134:135], 1.0 op_sel_hi:[1,0]
	v_pk_add_f32 v[136:137], v[136:137], 1.0 op_sel_hi:[1,0]
	v_pk_mul_f32 v[226:227], v[250:251], v[226:227]
	v_pk_mul_f32 v[228:229], v[252:253], v[228:229]
	v_pk_fma_f32 v[226:227], v[134:135], v[226:227], v[126:127]
	v_pk_fma_f32 v[228:229], v[136:137], v[228:229], v[128:129]
	v_cvt_pk_bf16_f32 v60, v226, v227
	v_cvt_pk_bf16_f32 v61, v228, v229
	global_store_dwordx2 v[30:31], v[60:61], off offset:512
	v_lshl_add_u64 v[30:31], v[30:31], 0, s[36:37]
	global_load_dwordx4 v[214:217], v[28:29], off offset:-2048
	global_load_dwordx4 v[218:221], v[28:29], off offset:-1024
	global_load_dwordx4 v[222:225], v[28:29], off
	global_load_dwordx4 v[226:229], v[28:29], off offset:1024
	v_lshl_add_u64 v[28:29], v[28:29], 0, s[34:35]
	global_load_dwordx4 v[112:115], v0, s[64:65]
	global_load_dwordx4 v[116:119], v0, s[64:65] offset:1024
	global_load_dwordx4 v[120:123], v0, s[64:65] offset:2048
	global_load_dwordx4 v[126:129], v0, s[64:65] offset:3072
	global_load_dwordx4 v[230:233], v0, s[66:67]
	global_load_dwordx4 v[234:237], v0, s[66:67] offset:1024
	global_load_dwordx4 v[238:241], v0, s[66:67] offset:2048
	global_load_dwordx4 v[134:137], v0, s[66:67] offset:3072
	s_add_u32 s64, s64, 0x9000
	s_addc_u32 s65, s65, 0
	s_add_u32 s66, s66, 0x9000
	s_addc_u32 s67, s67, 0
	s_waitcnt vmcnt(16)
	v_mul_f32_e32 v37, v65, v65
	v_fmac_f32_e32 v37, v64, v64
	v_fmac_f32_e32 v37, v66, v66
	v_fmac_f32_e32 v37, v67, v67
	v_mul_f32_e32 v38, v69, v69
	v_fmac_f32_e32 v38, v68, v68
	v_fmac_f32_e32 v38, v70, v70
	v_fmac_f32_e32 v38, v71, v71
	v_mul_f32_e32 v39, v73, v73
	v_fmac_f32_e32 v39, v72, v72
	v_fmac_f32_e32 v39, v74, v74
	v_fmac_f32_e32 v39, v75, v75
	v_mul_f32_e32 v40, v77, v77
	v_fmac_f32_e32 v40, v76, v76
	v_fmac_f32_e32 v40, v78, v78
	v_fmac_f32_e32 v40, v79, v79
	v_add_f32_e32 v255, v37, v38
	v_add_f32_e32 v255, v255, v39
	v_add_f32_e32 v255, v255, v40
	ds_bpermute_b32 v254, v48, v255
	s_waitcnt lgkmcnt(0)
	v_add_f32_e32 v255, v255, v254
	ds_bpermute_b32 v254, v49, v255
	s_waitcnt lgkmcnt(0)
	v_add_f32_e32 v255, v255, v254
	ds_bpermute_b32 v254, v50, v255
	s_waitcnt lgkmcnt(0)
	v_add_f32_e32 v255, v255, v254
	ds_bpermute_b32 v254, v51, v255
	s_waitcnt lgkmcnt(0)
	v_add_f32_e32 v255, v255, v254
	ds_bpermute_b32 v254, v52, v255
	s_waitcnt lgkmcnt(0)
	v_add_f32_e32 v255, v255, v254
	ds_bpermute_b32 v254, v53, v255
	s_waitcnt lgkmcnt(0)
; DI void phase_norm(const Params& p, char* wsb, int layer, int which, int mrows, bool do_convert, char* lds) {
;     ...
;   for (int row = blockIdx.x * 4 + wid; row < mrows; row += nw) {
;     const float4* xr = (const float4*)(xs + (size_t)row * 1024);
;     float4 v[4];
;     float ss = 0.f;
; #pragma unroll
;     for (int i = 0; i < 4; ++i) { v[i] = xr[lane + 64 * i]; ss += v[i].x * v[i].x + v[i].y * v[i].y + v[i].z * v[i].z + v[i].w * v[i].w; }
; #pragma unroll
;     for (int o = 32; o; o >>= 1) ss += __shfl_xor(ss, o);
;     const float r = rsqrtf(ss * (1.f / 1024.f) + 1e-6f);
;     const int mr = row < TL ? (row >> 11) : 8;
;     const float* sh = mods + (size_t)mr * 9216 + (3 * which) * 1024;
;     const float* sc = sh + 1024;
; #pragma unroll
;     for (int i = 0; i < 4; ++i) {
;       int col = (lane + 64 * i) * 4;
;       float4 gg = *(const float4*)(g + col), s4 = *(const float4*)(sh + col), c4 = *(const float4*)(sc + col);
;       float o0 = v[i].x * r * gg.x * (1.f + c4.x) + s4.x;
;       float o1 = v[i].y * r * gg.y * (1.f + c4.y) + s4.y;
;       float o2 = v[i].z * r * gg.z * (1.f + c4.z) + s4.z;
;       float o3 = v[i].w * r * gg.w * (1.f + c4.w) + s4.w;
;       *(uint2*)(H + (size_t)row * 1024 + col) = make_uint2(pack2(o0, o1), pack2(o2, o3));
;     }
	v_add_f32_e32 v255, v255, v254
	v_fmamk_f32 v255, v255, 0x3a800000, v179
	v_cmp_gt_f32_e32 vcc, s46, v255
	v_mul_f32_e32 v254, 0x4b800000, v255
	s_nop 0
	v_cndmask_b32_e32 v255, v255, v254, vcc
	v_rsq_f32_e32 v255, v255
	s_nop 0
	v_mul_f32_e32 v254, 0x45800000, v255
	v_cndmask_b32_e32 v56, v255, v254, vcc
	s_nop 0
	v_pk_mul_f32 v[64:65], v[64:65], v[56:57] op_sel_hi:[1,0]
	v_pk_mul_f32 v[66:67], v[66:67], v[56:57] op_sel_hi:[1,0]
	v_pk_add_f32 v[96:97], v[96:97], 1.0 op_sel_hi:[1,0]
	v_pk_add_f32 v[98:99], v[98:99], 1.0 op_sel_hi:[1,0]
	v_pk_mul_f32 v[64:65], v[138:139], v[64:65]
	v_pk_mul_f32 v[66:67], v[140:141], v[66:67]
	v_pk_fma_f32 v[64:65], v[96:97], v[64:65], v[80:81]
	v_pk_fma_f32 v[66:67], v[98:99], v[66:67], v[82:83]
	v_cvt_pk_bf16_f32 v58, v64, v65
	v_cvt_pk_bf16_f32 v59, v66, v67
	global_store_dwordx2 v[30:31], v[58:59], off offset:-1024
	v_pk_mul_f32 v[68:69], v[68:69], v[56:57] op_sel_hi:[1,0]
	v_pk_mul_f32 v[70:71], v[70:71], v[56:57] op_sel_hi:[1,0]
	v_pk_add_f32 v[100:101], v[100:101], 1.0 op_sel_hi:[1,0]
	v_pk_add_f32 v[102:103], v[102:103], 1.0 op_sel_hi:[1,0]
	v_pk_mul_f32 v[68:69], v[142:143], v[68:69]
	v_pk_mul_f32 v[70:71], v[144:145], v[70:71]
	v_pk_fma_f32 v[68:69], v[100:101], v[68:69], v[84:85]
	v_pk_fma_f32 v[70:71], v[102:103], v[70:71], v[86:87]
	v_cvt_pk_bf16_f32 v60, v68, v69
	v_cvt_pk_bf16_f32 v61, v70, v71
	global_store_dwordx2 v[30:31], v[60:61], off offset:-512
	v_pk_mul_f32 v[72:73], v[72:73], v[56:57] op_sel_hi:[1,0]
	v_pk_mul_f32 v[74:75], v[74:75], v[56:57] op_sel_hi:[1,0]
	v_pk_add_f32 v[104:105], v[104:105], 1.0 op_sel_hi:[1,0]
	v_pk_add_f32 v[106:107], v[106:107], 1.0 op_sel_hi:[1,0]
	v_pk_mul_f32 v[72:73], v[246:247], v[72:73]
	v_pk_mul_f32 v[74:75], v[248:249], v[74:75]
	v_pk_fma_f32 v[72:73], v[104:105], v[72:73], v[88:89]
	v_pk_fma_f32 v[74:75], v[106:107], v[74:75], v[90:91]
	v_cvt_pk_bf16_f32 v58, v72, v73
	v_cvt_pk_bf16_f32 v59, v74, v75
	global_store_dwordx2 v[30:31], v[58:59], off
	v_pk_mul_f32 v[76:77], v[76:77], v[56:57] op_sel_hi:[1,0]
	v_pk_mul_f32 v[78:79], v[78:79], v[56:57] op_sel_hi:[1,0]
	v_pk_add_f32 v[108:109], v[108:109], 1.0 op_sel_hi:[1,0]
	v_pk_add_f32 v[110:111], v[110:111], 1.0 op_sel_hi:[1,0]
	v_pk_mul_f32 v[76:77], v[250:251], v[76:77]
	v_pk_mul_f32 v[78:79], v[252:253], v[78:79]
	v_pk_fma_f32 v[76:77], v[108:109], v[76:77], v[92:93]
	v_pk_fma_f32 v[78:79], v[110:111], v[78:79], v[94:95]
	v_cvt_pk_bf16_f32 v60, v76, v77
	v_cvt_pk_bf16_f32 v61, v78, v79
	global_store_dwordx2 v[30:31], v[60:61], off offset:512
	v_lshl_add_u64 v[30:31], v[30:31], 0, s[36:37]
	global_load_dwordx4 v[64:67], v[28:29], off offset:-2048
	global_load_dwordx4 v[68:71], v[28:29], off offset:-1024
	global_load_dwordx4 v[72:75], v[28:29], off
	global_load_dwordx4 v[76:79], v[28:29], off offset:1024
	v_lshl_add_u64 v[28:29], v[28:29], 0, s[34:35]
	global_load_dwordx4 v[80:83], v0, s[64:65]
	global_load_dwordx4 v[84:87], v0, s[64:65] offset:1024
	global_load_dwordx4 v[88:91], v0, s[64:65] offset:2048
	global_load_dwordx4 v[92:95], v0, s[64:65] offset:3072
	global_load_dwordx4 v[96:99], v0, s[66:67]
	global_load_dwordx4 v[100:103], v0, s[66:67] offset:1024
	global_load_dwordx4 v[104:107], v0, s[66:67] offset:2048
	global_load_dwordx4 v[108:111], v0, s[66:67] offset:3072
	s_add_u32 s64, s64, 0x9000
	s_addc_u32 s65, s65, 0
	s_add_u32 s66, s66, 0x9000
	s_addc_u32 s67, s67, 0
	s_waitcnt vmcnt(16)
	v_mul_f32_e32 v37, v215, v215
	v_fmac_f32_e32 v37, v214, v214
	v_fmac_f32_e32 v37, v216, v216
	v_fmac_f32_e32 v37, v217, v217
	v_mul_f32_e32 v38, v219, v219
	v_fmac_f32_e32 v38, v218, v218
	v_fmac_f32_e32 v38, v220, v220
	v_fmac_f32_e32 v38, v221, v221
	v_mul_f32_e32 v39, v223, v223
	v_fmac_f32_e32 v39, v222, v222
	v_fmac_f32_e32 v39, v224, v224
	v_fmac_f32_e32 v39, v225, v225
	v_mul_f32_e32 v40, v227, v227
	v_fmac_f32_e32 v40, v226, v226
	v_fmac_f32_e32 v40, v228, v228
	v_fmac_f32_e32 v40, v229, v229
	v_add_f32_e32 v255, v37, v38
	v_add_f32_e32 v255, v255, v39
	v_add_f32_e32 v255, v255, v40
	ds_bpermute_b32 v254, v48, v255
	s_waitcnt lgkmcnt(0)
	v_add_f32_e32 v255, v255, v254
	ds_bpermute_b32 v254, v49, v255
	s_waitcnt lgkmcnt(0)
	v_add_f32_e32 v255, v255, v254
	ds_bpermute_b32 v254, v50, v255
	s_waitcnt lgkmcnt(0)
	v_add_f32_e32 v255, v255, v254
	ds_bpermute_b32 v254, v51, v255
	s_waitcnt lgkmcnt(0)
	v_add_f32_e32 v255, v255, v254
	ds_bpermute_b32 v254, v52, v255
	s_waitcnt lgkmcnt(0)
	v_add_f32_e32 v255, v255, v254
	ds_bpermute_b32 v254, v53, v255
	s_waitcnt lgkmcnt(0)
; DI void phase_norm(const Params& p, char* wsb, int layer, int which, int mrows, bool do_convert, char* lds) {
;     ...
;   for (int row = blockIdx.x * 4 + wid; row < mrows; row += nw) {
;     const float4* xr = (const float4*)(xs + (size_t)row * 1024);
;     float4 v[4];
;     float ss = 0.f;
; #pragma unroll
;     for (int i = 0; i < 4; ++i) { v[i] = xr[lane + 64 * i]; ss += v[i].x * v[i].x + v[i].y * v[i].y + v[i].z * v[i].z + v[i].w * v[i].w; }
; #pragma unroll
;     for (int o = 32; o; o >>= 1) ss += __shfl_xor(ss, o);
;     const float r = rsqrtf(ss * (1.f / 1024.f) + 1e-6f);
;     const int mr = row < TL ? (row >> 11) : 8;
;     const float* sh = mods + (size_t)mr * 9216 + (3 * which) * 1024;
;     const float* sc = sh + 1024;
; #pragma unroll
;     for (int i = 0; i < 4; ++i) {
;       int col = (lane + 64 * i) * 4;
;       float4 gg = *(const float4*)(g + col), s4 = *(const float4*)(sh + col), c4 = *(const float4*)(sc + col);
;       float o0 = v[i].x * r * gg.x * (1.f + c4.x) + s4.x;
;       float o1 = v[i].y * r * gg.y * (1.f + c4.y) + s4.y;
;       float o2 = v[i].z * r * gg.z * (1.f + c4.z) + s4.z;
;       float o3 = v[i].w * r * gg.w * (1.f + c4.w) + s4.w;
;       *(uint2*)(H + (size_t)row * 1024 + col) = make_uint2(pack2(o0, o1), pack2(o2, o3));
;     }
	v_add_f32_e32 v255, v255, v254
	v_fmamk_f32 v255, v255, 0x3a800000, v179
	v_cmp_gt_f32_e32 vcc, s46, v255
	v_mul_f32_e32 v254, 0x4b800000, v255
	s_nop 0
	v_cndmask_b32_e32 v255, v255, v254, vcc
	v_rsq_f32_e32 v255, v255
	s_nop 0
	v_mul_f32_e32 v254, 0x45800000, v255
	v_cndmask_b32_e32 v56, v255, v254, vcc
	s_nop 0
	v_pk_mul_f32 v[214:215], v[214:215], v[56:57] op_sel_hi:[1,0]
	v_pk_mul_f32 v[216:217], v[216:217], v[56:57] op_sel_hi:[1,0]
	v_pk_add_f32 v[230:231], v[230:231], 1.0 op_sel_hi:[1,0]
	v_pk_add_f32 v[232:233], v[232:233], 1.0 op_sel_hi:[1,0]
	v_pk_mul_f32 v[214:215], v[138:139], v[214:215]
	v_pk_mul_f32 v[216:217], v[140:141], v[216:217]
	v_pk_fma_f32 v[214:215], v[230:231], v[214:215], v[112:113]
	v_pk_fma_f32 v[216:217], v[232:233], v[216:217], v[114:115]
	v_cvt_pk_bf16_f32 v58, v214, v215
	v_cvt_pk_bf16_f32 v59, v216, v217
	global_store_dwordx2 v[30:31], v[58:59], off offset:-1024
	v_pk_mul_f32 v[218:219], v[218:219], v[56:57] op_sel_hi:[1,0]
	v_pk_mul_f32 v[220:221], v[220:221], v[56:57] op_sel_hi:[1,0]
	v_pk_add_f32 v[234:235], v[234:235], 1.0 op_sel_hi:[1,0]
	v_pk_add_f32 v[236:237], v[236:237], 1.0 op_sel_hi:[1,0]
	v_pk_mul_f32 v[218:219], v[142:143], v[218:219]
	v_pk_mul_f32 v[220:221], v[144:145], v[220:221]
	v_pk_fma_f32 v[218:219], v[234:235], v[218:219], v[116:117]
	v_pk_fma_f32 v[220:221], v[236:237], v[220:221], v[118:119]
	v_cvt_pk_bf16_f32 v60, v218, v219
	v_cvt_pk_bf16_f32 v61, v220, v221
	global_store_dwordx2 v[30:31], v[60:61], off offset:-512
	v_pk_mul_f32 v[222:223], v[222:223], v[56:57] op_sel_hi:[1,0]
	v_pk_mul_f32 v[224:225], v[224:225], v[56:57] op_sel_hi:[1,0]
	v_pk_add_f32 v[238:239], v[238:239], 1.0 op_sel_hi:[1,0]
	v_pk_add_f32 v[240:241], v[240:241], 1.0 op_sel_hi:[1,0]
	v_pk_mul_f32 v[222:223], v[246:247], v[222:223]
	v_pk_mul_f32 v[224:225], v[248:249], v[224:225]
	v_pk_fma_f32 v[222:223], v[238:239], v[222:223], v[120:121]
	v_pk_fma_f32 v[224:225], v[240:241], v[224:225], v[122:123]
	v_cvt_pk_bf16_f32 v58, v222, v223
	v_cvt_pk_bf16_f32 v59, v224, v225
	global_store_dwordx2 v[30:31], v[58:59], off
	v_pk_mul_f32 v[226:227], v[226:227], v[56:57] op_sel_hi:[1,0]
	v_pk_mul_f32 v[228:229], v[228:229], v[56:57] op_sel_hi:[1,0]
	v_pk_add_f32 v[134:135], v[134:135], 1.0 op_sel_hi:[1,0]
	v_pk_add_f32 v[136:137], v[136:137], 1.0 op_sel_hi:[1,0]
	v_pk_mul_f32 v[226:227], v[250:251], v[226:227]
	v_pk_mul_f32 v[228:229], v[252:253], v[228:229]
	v_pk_fma_f32 v[226:227], v[134:135], v[226:227], v[126:127]
	v_pk_fma_f32 v[228:229], v[136:137], v[228:229], v[128:129]
	v_cvt_pk_bf16_f32 v60, v226, v227
	v_cvt_pk_bf16_f32 v61, v228, v229
	global_store_dwordx2 v[30:31], v[60:61], off offset:512
	v_lshl_add_u64 v[30:31], v[30:31], 0, s[36:37]
	global_load_dwordx4 v[214:217], v[28:29], off offset:-2048
	global_load_dwordx4 v[218:221], v[28:29], off offset:-1024
	global_load_dwordx4 v[222:225], v[28:29], off
	global_load_dwordx4 v[226:229], v[28:29], off offset:1024
	v_lshl_add_u64 v[28:29], v[28:29], 0, s[34:35]
	global_load_dwordx4 v[112:115], v0, s[64:65]
	global_load_dwordx4 v[116:119], v0, s[64:65] offset:1024
	global_load_dwordx4 v[120:123], v0, s[64:65] offset:2048
	global_load_dwordx4 v[126:129], v0, s[64:65] offset:3072
	global_load_dwordx4 v[230:233], v0, s[66:67]
	global_load_dwordx4 v[234:237], v0, s[66:67] offset:1024
	global_load_dwordx4 v[238:241], v0, s[66:67] offset:2048
	global_load_dwordx4 v[134:137], v0, s[66:67] offset:3072
	s_add_u32 s64, s64, 0x9000
	s_addc_u32 s65, s65, 0
	s_add_u32 s66, s66, 0x9000
	s_addc_u32 s67, s67, 0
	s_waitcnt vmcnt(16)
	v_mul_f32_e32 v37, v65, v65
	v_fmac_f32_e32 v37, v64, v64
	v_fmac_f32_e32 v37, v66, v66
	v_fmac_f32_e32 v37, v67, v67
	v_mul_f32_e32 v38, v69, v69
	v_fmac_f32_e32 v38, v68, v68
	v_fmac_f32_e32 v38, v70, v70
	v_fmac_f32_e32 v38, v71, v71
	v_mul_f32_e32 v39, v73, v73
	v_fmac_f32_e32 v39, v72, v72
	v_fmac_f32_e32 v39, v74, v74
	v_fmac_f32_e32 v39, v75, v75
	v_mul_f32_e32 v40, v77, v77
	v_fmac_f32_e32 v40, v76, v76
	v_fmac_f32_e32 v40, v78, v78
	v_fmac_f32_e32 v40, v79, v79
	v_add_f32_e32 v255, v37, v38
	v_add_f32_e32 v255, v255, v39
	v_add_f32_e32 v255, v255, v40
	ds_bpermute_b32 v254, v48, v255
	s_waitcnt lgkmcnt(0)
	v_add_f32_e32 v255, v255, v254
	ds_bpermute_b32 v254, v49, v255
	s_waitcnt lgkmcnt(0)
	v_add_f32_e32 v255, v255, v254
	ds_bpermute_b32 v254, v50, v255
	s_waitcnt lgkmcnt(0)
	v_add_f32_e32 v255, v255, v254
	ds_bpermute_b32 v254, v51, v255
	s_waitcnt lgkmcnt(0)
	v_add_f32_e32 v255, v255, v254
	ds_bpermute_b32 v254, v52, v255
	s_waitcnt lgkmcnt(0)
	v_add_f32_e32 v255, v255, v254
	ds_bpermute_b32 v254, v53, v255
	s_waitcnt lgkmcnt(0)
; DI void phase_norm(const Params& p, char* wsb, int layer, int which, int mrows, bool do_convert, char* lds) {
;     ...
;   for (int row = blockIdx.x * 4 + wid; row < mrows; row += nw) {
;     const float4* xr = (const float4*)(xs + (size_t)row * 1024);
;     float4 v[4];
;     float ss = 0.f;
; #pragma unroll
;     for (int i = 0; i < 4; ++i) { v[i] = xr[lane + 64 * i]; ss += v[i].x * v[i].x + v[i].y * v[i].y + v[i].z * v[i].z + v[i].w * v[i].w; }
; #pragma unroll
;     for (int o = 32; o; o >>= 1) ss += __shfl_xor(ss, o);
;     const float r = rsqrtf(ss * (1.f / 1024.f) + 1e-6f);
;     const int mr = row < TL ? (row >> 11) : 8;
;     const float* sh = mods + (size_t)mr * 9216 + (3 * which) * 1024;
;     const float* sc = sh + 1024;
; #pragma unroll
;     for (int i = 0; i < 4; ++i) {
;       int col = (lane + 64 * i) * 4;
;       float4 gg = *(const float4*)(g + col), s4 = *(const float4*)(sh + col), c4 = *(const float4*)(sc + col);
;       float o0 = v[i].x * r * gg.x * (1.f + c4.x) + s4.x;
;       float o1 = v[i].y * r * gg.y * (1.f + c4.y) + s4.y;
;       float o2 = v[i].z * r * gg.z * (1.f + c4.z) + s4.z;
;       float o3 = v[i].w * r * gg.w * (1.f + c4.w) + s4.w;
;       *(uint2*)(H + (size_t)row * 1024 + col) = make_uint2(pack2(o0, o1), pack2(o2, o3));
;     }
	v_add_f32_e32 v255, v255, v254
	v_fmamk_f32 v255, v255, 0x3a800000, v179
	v_cmp_gt_f32_e32 vcc, s46, v255
	v_mul_f32_e32 v254, 0x4b800000, v255
	s_nop 0
	v_cndmask_b32_e32 v255, v255, v254, vcc
	v_rsq_f32_e32 v255, v255
	s_nop 0
	v_mul_f32_e32 v254, 0x45800000, v255
	v_cndmask_b32_e32 v56, v255, v254, vcc
	s_nop 0
	v_pk_mul_f32 v[64:65], v[64:65], v[56:57] op_sel_hi:[1,0]
	v_pk_mul_f32 v[66:67], v[66:67], v[56:57] op_sel_hi:[1,0]
	v_pk_add_f32 v[96:97], v[96:97], 1.0 op_sel_hi:[1,0]
	v_pk_add_f32 v[98:99], v[98:99], 1.0 op_sel_hi:[1,0]
	v_pk_mul_f32 v[64:65], v[138:139], v[64:65]
	v_pk_mul_f32 v[66:67], v[140:141], v[66:67]
	v_pk_fma_f32 v[64:65], v[96:97], v[64:65], v[80:81]
	v_pk_fma_f32 v[66:67], v[98:99], v[66:67], v[82:83]
	v_cvt_pk_bf16_f32 v58, v64, v65
	v_cvt_pk_bf16_f32 v59, v66, v67
	global_store_dwordx2 v[30:31], v[58:59], off offset:-1024
	v_pk_mul_f32 v[68:69], v[68:69], v[56:57] op_sel_hi:[1,0]
	v_pk_mul_f32 v[70:71], v[70:71], v[56:57] op_sel_hi:[1,0]
	v_pk_add_f32 v[100:101], v[100:101], 1.0 op_sel_hi:[1,0]
	v_pk_add_f32 v[102:103], v[102:103], 1.0 op_sel_hi:[1,0]
	v_pk_mul_f32 v[68:69], v[142:143], v[68:69]
	v_pk_mul_f32 v[70:71], v[144:145], v[70:71]
	v_pk_fma_f32 v[68:69], v[100:101], v[68:69], v[84:85]
	v_pk_fma_f32 v[70:71], v[102:103], v[70:71], v[86:87]
	v_cvt_pk_bf16_f32 v60, v68, v69
	v_cvt_pk_bf16_f32 v61, v70, v71
	global_store_dwordx2 v[30:31], v[60:61], off offset:-512
	v_pk_mul_f32 v[72:73], v[72:73], v[56:57] op_sel_hi:[1,0]
	v_pk_mul_f32 v[74:75], v[74:75], v[56:57] op_sel_hi:[1,0]
	v_pk_add_f32 v[104:105], v[104:105], 1.0 op_sel_hi:[1,0]
	v_pk_add_f32 v[106:107], v[106:107], 1.0 op_sel_hi:[1,0]
	v_pk_mul_f32 v[72:73], v[246:247], v[72:73]
	v_pk_mul_f32 v[74:75], v[248:249], v[74:75]
	v_pk_fma_f32 v[72:73], v[104:105], v[72:73], v[88:89]
	v_pk_fma_f32 v[74:75], v[106:107], v[74:75], v[90:91]
	v_cvt_pk_bf16_f32 v58, v72, v73
	v_cvt_pk_bf16_f32 v59, v74, v75
	global_store_dwordx2 v[30:31], v[58:59], off
	v_pk_mul_f32 v[76:77], v[76:77], v[56:57] op_sel_hi:[1,0]
	v_pk_mul_f32 v[78:79], v[78:79], v[56:57] op_sel_hi:[1,0]
	v_pk_add_f32 v[108:109], v[108:109], 1.0 op_sel_hi:[1,0]
	v_pk_add_f32 v[110:111], v[110:111], 1.0 op_sel_hi:[1,0]
	v_pk_mul_f32 v[76:77], v[250:251], v[76:77]
	v_pk_mul_f32 v[78:79], v[252:253], v[78:79]
	v_pk_fma_f32 v[76:77], v[108:109], v[76:77], v[92:93]
	v_pk_fma_f32 v[78:79], v[110:111], v[78:79], v[94:95]
	v_cvt_pk_bf16_f32 v60, v76, v77
	v_cvt_pk_bf16_f32 v61, v78, v79
	global_store_dwordx2 v[30:31], v[60:61], off offset:512
	v_lshl_add_u64 v[30:31], v[30:31], 0, s[36:37]
	global_load_dwordx4 v[64:67], v[28:29], off offset:-2048
	global_load_dwordx4 v[68:71], v[28:29], off offset:-1024
	global_load_dwordx4 v[72:75], v[28:29], off
	global_load_dwordx4 v[76:79], v[28:29], off offset:1024
	v_lshl_add_u64 v[28:29], v[28:29], 0, s[34:35]
	global_load_dwordx4 v[80:83], v0, s[64:65]
	global_load_dwordx4 v[84:87], v0, s[64:65] offset:1024
	global_load_dwordx4 v[88:91], v0, s[64:65] offset:2048
	global_load_dwordx4 v[92:95], v0, s[64:65] offset:3072
	global_load_dwordx4 v[96:99], v0, s[66:67]
	global_load_dwordx4 v[100:103], v0, s[66:67] offset:1024
	global_load_dwordx4 v[104:107], v0, s[66:67] offset:2048
	global_load_dwordx4 v[108:111], v0, s[66:67] offset:3072
	s_add_u32 s64, s64, 0x9000
	s_addc_u32 s65, s65, 0
	s_add_u32 s66, s66, 0x9000
	s_addc_u32 s67, s67, 0
	s_waitcnt vmcnt(16)
	v_mul_f32_e32 v37, v215, v215
	v_fmac_f32_e32 v37, v214, v214
	v_fmac_f32_e32 v37, v216, v216
	v_fmac_f32_e32 v37, v217, v217
	v_mul_f32_e32 v38, v219, v219
	v_fmac_f32_e32 v38, v218, v218
	v_fmac_f32_e32 v38, v220, v220
	v_fmac_f32_e32 v38, v221, v221
	v_mul_f32_e32 v39, v223, v223
	v_fmac_f32_e32 v39, v222, v222
	v_fmac_f32_e32 v39, v224, v224
	v_fmac_f32_e32 v39, v225, v225
	v_mul_f32_e32 v40, v227, v227
	v_fmac_f32_e32 v40, v226, v226
	v_fmac_f32_e32 v40, v228, v228
	v_fmac_f32_e32 v40, v229, v229
	v_add_f32_e32 v255, v37, v38
	v_add_f32_e32 v255, v255, v39
	v_add_f32_e32 v255, v255, v40
	ds_bpermute_b32 v254, v48, v255
	s_waitcnt lgkmcnt(0)
	v_add_f32_e32 v255, v255, v254
	ds_bpermute_b32 v254, v49, v255
	s_waitcnt lgkmcnt(0)
	v_add_f32_e32 v255, v255, v254
	ds_bpermute_b32 v254, v50, v255
	s_waitcnt lgkmcnt(0)
	v_add_f32_e32 v255, v255, v254
	ds_bpermute_b32 v254, v51, v255
	s_waitcnt lgkmcnt(0)
	v_add_f32_e32 v255, v255, v254
	ds_bpermute_b32 v254, v52, v255
	s_waitcnt lgkmcnt(0)
	v_add_f32_e32 v255, v255, v254
	ds_bpermute_b32 v254, v53, v255
	s_waitcnt lgkmcnt(0)
; DI void phase_norm(const Params& p, char* wsb, int layer, int which, int mrows, bool do_convert, char* lds) {
;     ...
;   for (int row = blockIdx.x * 4 + wid; row < mrows; row += nw) {
;     const float4* xr = (const float4*)(xs + (size_t)row * 1024);
;     float4 v[4];
;     float ss = 0.f;
; #pragma unroll
;     for (int i = 0; i < 4; ++i) { v[i] = xr[lane + 64 * i]; ss += v[i].x * v[i].x + v[i].y * v[i].y + v[i].z * v[i].z + v[i].w * v[i].w; }
; #pragma unroll
;     for (int o = 32; o; o >>= 1) ss += __shfl_xor(ss, o);
;     const float r = rsqrtf(ss * (1.f / 1024.f) + 1e-6f);
;     const int mr = row < TL ? (row >> 11) : 8;
;     const float* sh = mods + (size_t)mr * 9216 + (3 * which) * 1024;
;     const float* sc = sh + 1024;
; #pragma unroll
;     for (int i = 0; i < 4; ++i) {
;       int col = (lane + 64 * i) * 4;
;       float4 gg = *(const float4*)(g + col), s4 = *(const float4*)(sh + col), c4 = *(const float4*)(sc + col);
;       float o0 = v[i].x * r * gg.x * (1.f + c4.x) + s4.x;
;       float o1 = v[i].y * r * gg.y * (1.f + c4.y) + s4.y;
;       float o2 = v[i].z * r * gg.z * (1.f + c4.z) + s4.z;
;       float o3 = v[i].w * r * gg.w * (1.f + c4.w) + s4.w;
;       *(uint2*)(H + (size_t)row * 1024 + col) = make_uint2(pack2(o0, o1), pack2(o2, o3));
;     }
	v_add_f32_e32 v255, v255, v254
	v_fmamk_f32 v255, v255, 0x3a800000, v179
	v_cmp_gt_f32_e32 vcc, s46, v255
	v_mul_f32_e32 v254, 0x4b800000, v255
	s_nop 0
	v_cndmask_b32_e32 v255, v255, v254, vcc
	v_rsq_f32_e32 v255, v255
	s_nop 0
	v_mul_f32_e32 v254, 0x45800000, v255
	v_cndmask_b32_e32 v56, v255, v254, vcc
	s_nop 0
	v_pk_mul_f32 v[214:215], v[214:215], v[56:57] op_sel_hi:[1,0]
	v_pk_mul_f32 v[216:217], v[216:217], v[56:57] op_sel_hi:[1,0]
	v_pk_add_f32 v[230:231], v[230:231], 1.0 op_sel_hi:[1,0]
	v_pk_add_f32 v[232:233], v[232:233], 1.0 op_sel_hi:[1,0]
	v_pk_mul_f32 v[214:215], v[138:139], v[214:215]
	v_pk_mul_f32 v[216:217], v[140:141], v[216:217]
	v_pk_fma_f32 v[214:215], v[230:231], v[214:215], v[112:113]
	v_pk_fma_f32 v[216:217], v[232:233], v[216:217], v[114:115]
	v_cvt_pk_bf16_f32 v58, v214, v215
	v_cvt_pk_bf16_f32 v59, v216, v217
	global_store_dwordx2 v[30:31], v[58:59], off offset:-1024
	v_pk_mul_f32 v[218:219], v[218:219], v[56:57] op_sel_hi:[1,0]
	v_pk_mul_f32 v[220:221], v[220:221], v[56:57] op_sel_hi:[1,0]
	v_pk_add_f32 v[234:235], v[234:235], 1.0 op_sel_hi:[1,0]
	v_pk_add_f32 v[236:237], v[236:237], 1.0 op_sel_hi:[1,0]
	v_pk_mul_f32 v[218:219], v[142:143], v[218:219]
	v_pk_mul_f32 v[220:221], v[144:145], v[220:221]
	v_pk_fma_f32 v[218:219], v[234:235], v[218:219], v[116:117]
	v_pk_fma_f32 v[220:221], v[236:237], v[220:221], v[118:119]
	v_cvt_pk_bf16_f32 v60, v218, v219
	v_cvt_pk_bf16_f32 v61, v220, v221
	global_store_dwordx2 v[30:31], v[60:61], off offset:-512
	v_pk_mul_f32 v[222:223], v[222:223], v[56:57] op_sel_hi:[1,0]
	v_pk_mul_f32 v[224:225], v[224:225], v[56:57] op_sel_hi:[1,0]
	v_pk_add_f32 v[238:239], v[238:239], 1.0 op_sel_hi:[1,0]
	v_pk_add_f32 v[240:241], v[240:241], 1.0 op_sel_hi:[1,0]
	v_pk_mul_f32 v[222:223], v[246:247], v[222:223]
	v_pk_mul_f32 v[224:225], v[248:249], v[224:225]
	v_pk_fma_f32 v[222:223], v[238:239], v[222:223], v[120:121]
	v_pk_fma_f32 v[224:225], v[240:241], v[224:225], v[122:123]
	v_cvt_pk_bf16_f32 v58, v222, v223
	v_cvt_pk_bf16_f32 v59, v224, v225
	global_store_dwordx2 v[30:31], v[58:59], off
	v_pk_mul_f32 v[226:227], v[226:227], v[56:57] op_sel_hi:[1,0]
	v_pk_mul_f32 v[228:229], v[228:229], v[56:57] op_sel_hi:[1,0]
	v_pk_add_f32 v[134:135], v[134:135], 1.0 op_sel_hi:[1,0]
	v_pk_add_f32 v[136:137], v[136:137], 1.0 op_sel_hi:[1,0]
	v_pk_mul_f32 v[226:227], v[250:251], v[226:227]
	v_pk_mul_f32 v[228:229], v[252:253], v[228:229]
	v_pk_fma_f32 v[226:227], v[134:135], v[226:227], v[126:127]
	v_pk_fma_f32 v[228:229], v[136:137], v[228:229], v[128:129]
	v_cvt_pk_bf16_f32 v60, v226, v227
	v_cvt_pk_bf16_f32 v61, v228, v229
	global_store_dwordx2 v[30:31], v[60:61], off offset:512
	v_lshl_add_u64 v[30:31], v[30:31], 0, s[36:37]
	s_waitcnt vmcnt(4)
	v_mul_f32_e32 v37, v65, v65
	v_fmac_f32_e32 v37, v64, v64
	v_fmac_f32_e32 v37, v66, v66
	v_fmac_f32_e32 v37, v67, v67
	v_mul_f32_e32 v38, v69, v69
	v_fmac_f32_e32 v38, v68, v68
	v_fmac_f32_e32 v38, v70, v70
	v_fmac_f32_e32 v38, v71, v71
	v_mul_f32_e32 v39, v73, v73
	v_fmac_f32_e32 v39, v72, v72
	v_fmac_f32_e32 v39, v74, v74
	v_fmac_f32_e32 v39, v75, v75
	v_mul_f32_e32 v40, v77, v77
	v_fmac_f32_e32 v40, v76, v76
	v_fmac_f32_e32 v40, v78, v78
	v_fmac_f32_e32 v40, v79, v79
	v_add_f32_e32 v255, v37, v38
	v_add_f32_e32 v255, v255, v39
	v_add_f32_e32 v255, v255, v40
	ds_bpermute_b32 v254, v48, v255
	s_waitcnt lgkmcnt(0)
	v_add_f32_e32 v255, v255, v254
	ds_bpermute_b32 v254, v49, v255
	s_waitcnt lgkmcnt(0)
	v_add_f32_e32 v255, v255, v254
	ds_bpermute_b32 v254, v50, v255
	s_waitcnt lgkmcnt(0)
	v_add_f32_e32 v255, v255, v254
	ds_bpermute_b32 v254, v51, v255
	s_waitcnt lgkmcnt(0)
	v_add_f32_e32 v255, v255, v254
	ds_bpermute_b32 v254, v52, v255
	s_waitcnt lgkmcnt(0)
	v_add_f32_e32 v255, v255, v254
	ds_bpermute_b32 v254, v53, v255
	s_waitcnt lgkmcnt(0)
	v_add_f32_e32 v255, v255, v254
	v_fmamk_f32 v255, v255, 0x3a800000, v179
	v_cmp_gt_f32_e32 vcc, s46, v255
	v_mul_f32_e32 v254, 0x4b800000, v255
	s_nop 0
	v_cndmask_b32_e32 v255, v255, v254, vcc
	v_rsq_f32_e32 v255, v255
	s_nop 0
	v_mul_f32_e32 v254, 0x45800000, v255
	v_cndmask_b32_e32 v56, v255, v254, vcc
	s_nop 0
	v_pk_mul_f32 v[64:65], v[64:65], v[56:57] op_sel_hi:[1,0]
	v_pk_mul_f32 v[66:67], v[66:67], v[56:57] op_sel_hi:[1,0]
	v_pk_add_f32 v[96:97], v[96:97], 1.0 op_sel_hi:[1,0]
	v_pk_add_f32 v[98:99], v[98:99], 1.0 op_sel_hi:[1,0]
	v_pk_mul_f32 v[64:65], v[138:139], v[64:65]
	v_pk_mul_f32 v[66:67], v[140:141], v[66:67]
	v_pk_fma_f32 v[64:65], v[96:97], v[64:65], v[80:81]
	v_pk_fma_f32 v[66:67], v[98:99], v[66:67], v[82:83]
	v_cvt_pk_bf16_f32 v58, v64, v65
	v_cvt_pk_bf16_f32 v59, v66, v67
	global_store_dwordx2 v[30:31], v[58:59], off offset:-1024
	v_pk_mul_f32 v[68:69], v[68:69], v[56:57] op_sel_hi:[1,0]
	v_pk_mul_f32 v[70:71], v[70:71], v[56:57] op_sel_hi:[1,0]
	v_pk_add_f32 v[100:101], v[100:101], 1.0 op_sel_hi:[1,0]
	v_pk_add_f32 v[102:103], v[102:103], 1.0 op_sel_hi:[1,0]
	v_pk_mul_f32 v[68:69], v[142:143], v[68:69]
	v_pk_mul_f32 v[70:71], v[144:145], v[70:71]
	v_pk_fma_f32 v[68:69], v[100:101], v[68:69], v[84:85]
	v_pk_fma_f32 v[70:71], v[102:103], v[70:71], v[86:87]
	v_cvt_pk_bf16_f32 v60, v68, v69
	v_cvt_pk_bf16_f32 v61, v70, v71
	global_store_dwordx2 v[30:31], v[60:61], off offset:-512
	v_pk_mul_f32 v[72:73], v[72:73], v[56:57] op_sel_hi:[1,0]
	v_pk_mul_f32 v[74:75], v[74:75], v[56:57] op_sel_hi:[1,0]
	v_pk_add_f32 v[104:105], v[104:105], 1.0 op_sel_hi:[1,0]
	v_pk_add_f32 v[106:107], v[106:107], 1.0 op_sel_hi:[1,0]
	v_pk_mul_f32 v[72:73], v[246:247], v[72:73]
	v_pk_mul_f32 v[74:75], v[248:249], v[74:75]
	v_pk_fma_f32 v[72:73], v[104:105], v[72:73], v[88:89]
	v_pk_fma_f32 v[74:75], v[106:107], v[74:75], v[90:91]
	v_cvt_pk_bf16_f32 v58, v72, v73
	v_cvt_pk_bf16_f32 v59, v74, v75
	global_store_dwordx2 v[30:31], v[58:59], off
	v_pk_mul_f32 v[76:77], v[76:77], v[56:57] op_sel_hi:[1,0]
	v_pk_mul_f32 v[78:79], v[78:79], v[56:57] op_sel_hi:[1,0]
	v_pk_add_f32 v[108:109], v[108:109], 1.0 op_sel_hi:[1,0]
	v_pk_add_f32 v[110:111], v[110:111], 1.0 op_sel_hi:[1,0]
	v_pk_mul_f32 v[76:77], v[250:251], v[76:77]
	v_pk_mul_f32 v[78:79], v[252:253], v[78:79]
	v_pk_fma_f32 v[76:77], v[108:109], v[76:77], v[92:93]
	v_pk_fma_f32 v[78:79], v[110:111], v[78:79], v[94:95]
	v_cvt_pk_bf16_f32 v60, v76, v77
	v_cvt_pk_bf16_f32 v61, v78, v79
	global_store_dwordx2 v[30:31], v[60:61], off offset:512
	v_lshl_add_u64 v[30:31], v[30:31], 0, s[36:37]
; DI void phase_norm(const Params& p, char* wsb, int layer, int which, int mrows, bool do_convert, char* lds) {
;     ...
;   for (int row = blockIdx.x * 4 + wid; row < mrows; row += nw) {
;     const float4* xr = (const float4*)(xs + (size_t)row * 1024);
;     float4 v[4];
;     float ss = 0.f;
; #pragma unroll
;     for (int i = 0; i < 4; ++i) { v[i] = xr[lane + 64 * i]; ss += v[i].x * v[i].x + v[i].y * v[i].y + v[i].z * v[i].z + v[i].w * v[i].w; }
; #pragma unroll
;     for (int o = 32; o; o >>= 1) ss += __shfl_xor(ss, o);
;     const float r = rsqrtf(ss * (1.f / 1024.f) + 1e-6f);
;     const int mr = row < TL ? (row >> 11) : 8;
;     const float* sh = mods + (size_t)mr * 9216 + (3 * which) * 1024;
;     const float* sc = sh + 1024;
; #pragma unroll
;     for (int i = 0; i < 4; ++i) {
;       int col = (lane + 64 * i) * 4;
;       float4 gg = *(const float4*)(g + col), s4 = *(const float4*)(sh + col), c4 = *(const float4*)(sc + col);
;       float o0 = v[i].x * r * gg.x * (1.f + c4.x) + s4.x;
;       float o1 = v[i].y * r * gg.y * (1.f + c4.y) + s4.y;
;       float o2 = v[i].z * r * gg.z * (1.f + c4.z) + s4.z;
;       float o3 = v[i].w * r * gg.w * (1.f + c4.w) + s4.w;
;       *(uint2*)(H + (size_t)row * 1024 + col) = make_uint2(pack2(o0, o1), pack2(o2, o3));
;     }
.Lnrm1_done:
	s_branch .LBB0_534
.LBB0_533:
	v_min_i32_e32 v2, 0x4000, v18
	v_ashrrev_i32_e32 v2, 11, v2
	v_mul_hi_i32_i24_e32 v3, 0x9000, v2
	v_mul_i32_i24_e32 v2, 0x9000, v2
	v_lshl_add_u64 v[2:3], s[8:9], 0, v[2:3]
	v_lshl_add_u64 v[42:43], v[2:3], 0, s[56:57]
	v_lshl_add_u64 v[38:39], v[2:3], 0, v[0:1]
	v_lshl_add_u64 v[2:3], v[42:43], 0, v[0:1]
	global_load_dwordx4 v[54:57], v[28:29], off offset:-2048
	global_load_dwordx4 v[14:17], v[20:21], off
	global_load_dwordx4 v[10:13], v[38:39], off
	s_nop 0
	global_load_dwordx4 v[2:5], v[2:3], off
	v_mov_b32_e32 v33, v1
	global_load_dwordx4 v[6:9], v[28:29], off offset:-1024
	v_lshl_add_u64 v[44:45], v[42:43], 0, v[32:33]
	v_mov_b32_e32 v35, v1
	v_mov_b32_e32 v37, v1
	v_add_u32_e32 v18, s94, v18
	s_waitcnt vmcnt(4)
	v_mov_b32_e32 v58, v55
	v_mov_b32_e32 v40, v54
	s_waitcnt vmcnt(1)
	v_pk_add_f32 v[62:63], v[2:3], 1.0 op_sel_hi:[1,0]
	v_mov_b32_e32 v2, v56
	s_waitcnt vmcnt(0)
	v_mov_b32_e32 v59, v7
	v_mov_b32_e32 v41, v6
	v_pk_mul_f32 v[58:59], v[58:59], v[58:59]
	v_mov_b32_e32 v3, v8
	v_pk_fma_f32 v[40:41], v[40:41], v[40:41], v[58:59]
	v_pk_add_f32 v[46:47], v[4:5], 1.0 op_sel_hi:[1,0]
	v_mov_b32_e32 v4, v57
	v_mov_b32_e32 v5, v9
	v_pk_fma_f32 v[2:3], v[2:3], v[2:3], v[40:41]
	global_load_dwordx4 v[58:61], v[28:29], off
	v_pk_fma_f32 v[64:65], v[4:5], v[4:5], v[2:3]
	global_load_dwordx4 v[2:5], v[28:29], off offset:1024
	v_add_f32_e32 v19, v64, v65
	v_lshl_add_u64 v[40:41], v[42:43], 0, v[34:35]
	v_lshl_add_u64 v[42:43], v[42:43], 0, v[36:37]
	v_lshl_add_u64 v[28:29], v[28:29], 0, s[34:35]
	s_waitcnt vmcnt(1)
	v_mov_b32_e32 v72, v59
	v_mov_b32_e32 v70, v58
	s_waitcnt vmcnt(0)
	v_mov_b32_e32 v73, v3
	v_mov_b32_e32 v71, v2
	v_pk_mul_f32 v[72:73], v[72:73], v[72:73]
	v_mov_b32_e32 v66, v60
	v_mov_b32_e32 v67, v4
	v_pk_fma_f32 v[70:71], v[70:71], v[70:71], v[72:73]
	v_mov_b32_e32 v68, v61
	v_mov_b32_e32 v69, v5
	v_pk_fma_f32 v[66:67], v[66:67], v[66:67], v[70:71]
	s_nop 0
	v_pk_fma_f32 v[66:67], v[68:69], v[68:69], v[66:67]
	s_nop 0
	v_add_f32_e32 v19, v19, v66
	v_add_f32_e32 v19, v19, v67
	ds_bpermute_b32 v33, v48, v19
	s_waitcnt lgkmcnt(0)
	v_add_f32_e32 v19, v19, v33
	ds_bpermute_b32 v33, v49, v19
	s_waitcnt lgkmcnt(0)
	v_add_f32_e32 v19, v19, v33
	ds_bpermute_b32 v33, v50, v19
	s_waitcnt lgkmcnt(0)
	v_add_f32_e32 v19, v19, v33
	ds_bpermute_b32 v33, v51, v19
	s_waitcnt lgkmcnt(0)
	v_add_f32_e32 v19, v19, v33
	ds_bpermute_b32 v33, v52, v19
	s_waitcnt lgkmcnt(0)
	v_add_f32_e32 v19, v19, v33
	ds_bpermute_b32 v33, v53, v19
	s_waitcnt lgkmcnt(0)
	v_add_f32_e32 v19, v19, v33
	v_fmamk_f32 v19, v19, 0x3a800000, v179
	v_cmp_gt_f32_e32 vcc, s46, v19
	v_mul_f32_e32 v33, 0x4b800000, v19
	s_nop 0
	v_cndmask_b32_e32 v19, v19, v33, vcc
	v_rsq_f32_e32 v19, v19
	s_nop 0
	v_mul_f32_e32 v33, 0x45800000, v19
	v_cndmask_b32_e32 v64, v19, v33, vcc
	v_pk_mul_f32 v[54:55], v[54:55], v[64:65] op_sel_hi:[1,0]
	v_pk_mul_f32 v[6:7], v[6:7], v[64:65] op_sel_hi:[1,0]
	v_pk_mul_f32 v[14:15], v[14:15], v[54:55]
	v_pk_mul_f32 v[8:9], v[8:9], v[64:65] op_sel_hi:[1,0]
	v_pk_fma_f32 v[10:11], v[62:63], v[14:15], v[10:11]
	v_pk_mul_f32 v[14:15], v[56:57], v[64:65] op_sel_hi:[1,0]
	v_cvt_pk_bf16_f32 v10, v10, v11
	v_pk_mul_f32 v[14:15], v[16:17], v[14:15]
	v_pk_mul_f32 v[2:3], v[2:3], v[64:65] op_sel_hi:[1,0]
	v_pk_fma_f32 v[12:13], v[46:47], v[14:15], v[12:13]
	v_pk_mul_f32 v[4:5], v[4:5], v[64:65] op_sel_hi:[1,0]
	v_cvt_pk_bf16_f32 v11, v12, v13
	global_store_dwordx2 v[30:31], v[10:11], off offset:-1024
	global_load_dwordx4 v[10:13], v[22:23], off
	s_nop 0
	global_load_dwordx4 v[14:17], v[38:39], off offset:1024
	s_nop 0
	global_load_dwordx4 v[44:47], v[44:45], off
	v_cmp_lt_i32_e32 vcc, s40, v18
	s_or_b64 s[10:11], vcc, s[10:11]
	s_waitcnt vmcnt(2)
	v_pk_mul_f32 v[6:7], v[6:7], v[10:11]
	v_pk_mul_f32 v[8:9], v[8:9], v[12:13]
	s_waitcnt vmcnt(0)
	v_pk_add_f32 v[10:11], v[44:45], 1.0 op_sel_hi:[1,0]
	s_nop 0
	v_pk_fma_f32 v[6:7], v[6:7], v[10:11], v[14:15]
	v_pk_add_f32 v[10:11], v[46:47], 1.0 op_sel_hi:[1,0]
	v_cvt_pk_bf16_f32 v6, v6, v7
	v_pk_fma_f32 v[8:9], v[8:9], v[10:11], v[16:17]
	s_nop 0
	v_cvt_pk_bf16_f32 v7, v8, v9
	global_store_dwordx2 v[30:31], v[6:7], off offset:-512
	global_load_dwordx4 v[6:9], v[24:25], off
	s_nop 0
	global_load_dwordx4 v[10:13], v[38:39], off offset:2048
	global_load_dwordx4 v[14:17], v[40:41], off
	v_pk_mul_f32 v[40:41], v[58:59], v[64:65] op_sel_hi:[1,0]
	s_waitcnt vmcnt(0)
	v_pk_add_f32 v[14:15], v[14:15], 1.0 op_sel_hi:[1,0]
	v_pk_mul_f32 v[6:7], v[40:41], v[6:7]
	s_nop 0
	v_pk_fma_f32 v[6:7], v[6:7], v[14:15], v[10:11]
	v_pk_mul_f32 v[10:11], v[60:61], v[64:65] op_sel_hi:[1,0]
	v_cvt_pk_bf16_f32 v6, v6, v7
	v_pk_mul_f32 v[8:9], v[10:11], v[8:9]
	v_pk_add_f32 v[10:11], v[16:17], 1.0 op_sel_hi:[1,0]
	s_nop 0
	v_pk_fma_f32 v[8:9], v[8:9], v[10:11], v[12:13]
	s_nop 0
	v_cvt_pk_bf16_f32 v7, v8, v9
	global_store_dwordx2 v[30:31], v[6:7], off
	global_load_dwordx4 v[6:9], v[26:27], off
	s_nop 0
	global_load_dwordx4 v[10:13], v[38:39], off offset:3072
	global_load_dwordx4 v[14:17], v[42:43], off
	s_waitcnt vmcnt(2)
	v_pk_mul_f32 v[2:3], v[2:3], v[6:7]
	v_pk_mul_f32 v[4:5], v[4:5], v[8:9]
	s_waitcnt vmcnt(0)
	v_pk_add_f32 v[6:7], v[14:15], 1.0 op_sel_hi:[1,0]
	s_nop 0
	v_pk_fma_f32 v[2:3], v[2:3], v[6:7], v[10:11]
	v_pk_add_f32 v[6:7], v[16:17], 1.0 op_sel_hi:[1,0]
	v_cvt_pk_bf16_f32 v2, v2, v3
	v_pk_fma_f32 v[4:5], v[4:5], v[6:7], v[12:13]
	s_nop 0
	v_cvt_pk_bf16_f32 v3, v4, v5
	global_store_dwordx2 v[30:31], v[2:3], off offset:512
	v_lshl_add_u64 v[30:31], v[30:31], 0, s[36:37]
	s_andn2_b64 exec, exec, s[10:11]
	s_cbranch_execnz .LBB0_533

; #define MFMA(a, b, c) __builtin_amdgcn_mfma_f32_32x32x16_bf16((a), (b), (c), 0, 0, 0)
; template <int NB1>
; DI void hyena_item(const Params& p, char* wsb, int layer, int c, char* lds) {
;     ...
;       auto d1_range = [&](const int lo, const int hi, const int jmask) {
; #pragma unroll 1
;         for (int d1o = lo; d1o < hi; d1o += 2) {
; #pragma unroll
;           for (int dk = 0; dk < 4; ++dk) {
;             const int d1 = d1o + (dk >> 1), ks = dk & 1;
;             const unsigned* rp = Rd + (-16 * d1 + 8 * ks);
;             unsigned w[5];
; #pragma unroll
;             for (int q = 0; q < 5; ++q) w[q] = rp[q];
;             union { s16x8 v; unsigned u[4]; } af;
; #pragma unroll
;             for (int q = 0; q < 4; ++q) af.u[q] = __builtin_amdgcn_alignbit(w[q + 1], w[q], sh);
; #pragma unroll
;             for (int j = 0; j < TPW; ++j) {
;               if (!((jmask >> (j & 1)) & 1)) continue;
;               const bool ok = (unsigned)(tt1[j] - d1) < (unsigned)NB1;
;               const int addr = ok ? ub[j] - d1 * 80 + ks * 32 : zaddr;
;               const s16x8 bf = *(const s16x8*)(lds + addr);
;               acc[j] = MFMA(af.v, bf, acc[j]);
;             }
;           }
;         }
;       };
;       if (NB1 == 64) { d1_range(-64, -32, 1); d1_range(-32, 32, 3); d1_range(32, 64, 2); }
.LBB0_867:
	v_add_u32_e32 v30, v147, v20
	v_add_u32_e32 v31, v147, v19
	v_add_u32_e32 v246, 1, v21
	v_cmp_gt_u32_e32 vcc, 64, v246
	v_cmp_gt_u32_e64 s[8:9], 64, v21
	v_add_u32_e32 v213, 0x1400, v30
	v_add_u32_e32 v214, 0x1400, v31
	v_add_u32_e32 v215, 0x1420, v30
	v_add_u32_e32 v216, 0x1420, v31
	v_add_u32_e32 v217, 0x13b0, v30
	v_add_u32_e32 v218, 0x13b0, v31
	v_add_u32_e32 v219, 0x13d0, v30
	v_add_u32_e32 v220, 0x13d0, v31
	v_cndmask_b32_e32 v213, v212, v213, vcc
	v_cndmask_b32_e32 v214, v212, v214, vcc
	v_cndmask_b32_e32 v215, v212, v215, vcc
	v_cndmask_b32_e32 v216, v212, v216, vcc
	v_cndmask_b32_e64 v217, v212, v217, s[8:9]
	v_cndmask_b32_e64 v218, v212, v218, s[8:9]
	v_cndmask_b32_e64 v219, v212, v219, s[8:9]
	v_cndmask_b32_e64 v220, v212, v220, s[8:9]
	v_add_u32_e32 v20, 0xffffff60, v20
	v_add_u32_e32 v19, 0xffffff60, v19
	v_add_u32_e32 v21, -2, v21
	s_add_i32 s6, s6, 2
	ds_read2_b32 v[22:23], v18 offset0:16 offset1:17
	ds_read2_b32 v[26:27], v18 offset0:17 offset1:18
	ds_read2_b32 v[24:25], v18 offset0:19 offset1:20
	ds_read2_b32 v[222:223], v18 offset0:24 offset1:25
	ds_read2_b32 v[226:227], v18 offset0:25 offset1:26
	ds_read2_b32 v[224:225], v18 offset0:27 offset1:28
	ds_read_b128 v[230:233], v213
	ds_read_b128 v[234:237], v214
	ds_read_b128 v[238:241], v215
	ds_read_b128 v[170:173], v216
	s_waitcnt lgkmcnt(4)
	v_alignbit_b32 v22, v26, v22, v66
	v_alignbit_b32 v25, v25, v24, v69
	v_alignbit_b32 v24, v24, v27, v68
	v_alignbit_b32 v23, v27, v23, v67
	v_alignbit_b32 v222, v226, v222, v66
	v_alignbit_b32 v225, v225, v224, v69
	v_alignbit_b32 v224, v224, v227, v68
	v_alignbit_b32 v223, v227, v223, v67
	s_waitcnt lgkmcnt(3)
	v_mfma_f32_32x32x16_bf16 v[34:49], v[22:25], v[230:233], v[34:49]
	s_waitcnt lgkmcnt(2)
	v_mfma_f32_32x32x16_bf16 v[2:17], v[22:25], v[234:237], v[2:17]
	s_waitcnt lgkmcnt(1)
	v_mfma_f32_32x32x16_bf16 v[34:49], v[222:225], v[238:241], v[34:49]
	s_waitcnt lgkmcnt(0)
	v_mfma_f32_32x32x16_bf16 v[2:17], v[222:225], v[170:173], v[2:17]
	ds_read2_b32 v[22:23], v18 offset1:1
	ds_read2_b32 v[26:27], v18 offset0:1 offset1:2
	ds_read2_b32 v[24:25], v18 offset0:3 offset1:4
	ds_read2_b32 v[222:223], v18 offset0:8 offset1:9
	ds_read2_b32 v[226:227], v18 offset0:9 offset1:10
	ds_read2_b32 v[224:225], v18 offset0:11 offset1:12
	ds_read_b128 v[230:233], v217
	ds_read_b128 v[234:237], v218
	ds_read_b128 v[238:241], v219
	ds_read_b128 v[170:173], v220
	s_waitcnt lgkmcnt(4)
	v_alignbit_b32 v22, v26, v22, v66
	v_alignbit_b32 v25, v25, v24, v69
	v_alignbit_b32 v24, v24, v27, v68
	v_alignbit_b32 v23, v27, v23, v67
	v_alignbit_b32 v222, v226, v222, v66
	v_alignbit_b32 v225, v225, v224, v69
	v_alignbit_b32 v224, v224, v227, v68
	v_alignbit_b32 v223, v227, v223, v67
	s_waitcnt lgkmcnt(3)
	v_mfma_f32_32x32x16_bf16 v[34:49], v[22:25], v[230:233], v[34:49]
	s_waitcnt lgkmcnt(2)
	v_mfma_f32_32x32x16_bf16 v[2:17], v[22:25], v[234:237], v[2:17]
	s_waitcnt lgkmcnt(1)
	v_mfma_f32_32x32x16_bf16 v[34:49], v[222:225], v[238:241], v[34:49]
	s_waitcnt lgkmcnt(0)
	v_mfma_f32_32x32x16_bf16 v[2:17], v[222:225], v[170:173], v[2:17]
	v_add_u32_e32 v18, 0xffffff80, v18
	s_cmp_lt_u32 s6, 0xffffffde
	s_cbranch_scc1 .LBB0_867
	v_mov_b32_e32 v18, 0
	s_movk_i32 s40, 0xffde
	v_mov_b32_e32 v123, v165
	v_mov_b32_e32 v125, v160
	v_mov_b32_e32 v127, v159
	v_mov_b32_e32 v134, v164
	v_mov_b32_e32 v135, v163
	v_mov_b32_e32 v136, v162
	v_mov_b32_e32 v19, v18
	v_mov_b32_e32 v20, v18
	v_mov_b32_e32 v21, v18
	v_mov_b32_e32 v22, v18
	v_mov_b32_e32 v23, v18
	v_mov_b32_e32 v24, v18
	v_mov_b32_e32 v25, v18
	v_mov_b32_e32 v26, v18
	v_mov_b32_e32 v27, v18
	v_mov_b32_e32 v28, v18
	v_mov_b32_e32 v29, v18
	v_mov_b32_e32 v30, v18
	v_mov_b32_e32 v31, v18
	v_mov_b32_e32 v32, v18
	v_mov_b32_e32 v33, v18
	v_mov_b32_e32 v50, v18
	v_mov_b32_e32 v51, v18
	v_mov_b32_e32 v52, v18
	v_mov_b32_e32 v53, v18
	v_mov_b32_e32 v54, v18
	v_mov_b32_e32 v55, v18
	v_mov_b32_e32 v56, v18
	v_mov_b32_e32 v57, v18
	v_mov_b32_e32 v58, v18
	v_mov_b32_e32 v59, v18
	v_mov_b32_e32 v60, v18
	v_mov_b32_e32 v61, v18
	v_mov_b32_e32 v62, v18
	v_mov_b32_e32 v63, v18
	v_mov_b32_e32 v64, v18
	v_mov_b32_e32 v65, v18
.LBB0_869:
	v_add_u32_e32 v174, v146, v134
	v_add_u32_e32 v246, 32, v174
	v_cmp_gt_u32_e32 vcc, 64, v246
	v_add_u32_e32 v137, v147, v127
	v_add_u32_e32 v175, v146, v135
	v_add_co_u32_e64 v246, s[6:7], 64, v175
	v_add_u32_e32 v138, v147, v125
	v_add_u32_e32 v139, v146, v136
	v_add_u32_e32 v246, 0x80, v139
	v_cmp_gt_u32_e64 s[8:9], 64, v246
	v_add_u32_e32 v213, 0xa00, v137
	v_add_u32_e32 v214, 0x1400, v137
	v_add_u32_e32 v215, 0xa00, v138
	v_add_u32_e32 v216, 0x2800, v137
	v_add_u32_e32 v217, 0xa20, v137
	v_add_u32_e32 v218, 0x1420, v137
	v_add_u32_e32 v219, 0xa20, v138
	v_add_u32_e32 v220, 0x2820, v137
	v_cndmask_b32_e32 v213, v212, v213, vcc
	v_cndmask_b32_e64 v214, v212, v214, s[6:7]
	v_cndmask_b32_e32 v215, v212, v215, vcc
	v_cndmask_b32_e64 v216, v212, v216, s[8:9]
	v_cndmask_b32_e32 v217, v212, v217, vcc
	v_cndmask_b32_e64 v218, v212, v218, s[6:7]
	v_cndmask_b32_e32 v219, v212, v219, vcc
	v_cndmask_b32_e64 v220, v212, v220, s[8:9]
	v_add_u32_e32 v246, 0x7f, v139
	v_cmp_gt_u32_e64 s[6:7], 64, v246
	v_add_u32_e32 v246, 31, v174
	v_cmp_gt_u32_e32 vcc, 64, v246
	v_add_u32_e32 v246, 63, v175
	v_cmp_gt_u32_e64 s[8:9], 64, v246
	v_add_u32_e32 v221, 0x9b0, v137
	v_add_u32_e32 v222, 0x13b0, v137
	v_add_u32_e32 v223, 0x9b0, v138
	v_add_u32_e32 v224, 0x27b0, v137
	v_add_u32_e32 v225, 0x9d0, v137
	v_add_u32_e32 v226, 0x13d0, v137
	v_add_u32_e32 v227, 0x9d0, v138
	v_add_u32_e32 v228, 0x27d0, v137
	v_cndmask_b32_e32 v221, v212, v221, vcc
	v_cndmask_b32_e64 v222, v212, v222, s[8:9]
	v_cndmask_b32_e32 v223, v212, v223, vcc
	v_cndmask_b32_e64 v224, v212, v224, s[6:7]
	v_cndmask_b32_e32 v225, v212, v225, vcc
	v_cndmask_b32_e64 v226, v212, v226, s[8:9]
	v_cndmask_b32_e32 v227, v212, v227, vcc
	v_cndmask_b32_e64 v228, v212, v228, s[6:7]
	s_add_i32 s40, s40, 2
	v_add_u32_e32 v135, -2, v135
	v_add_u32_e32 v136, -2, v136
	v_add_u32_e32 v134, -2, v134
	v_add_u32_e32 v127, 0xffffff60, v127
	v_add_u32_e32 v125, 0xffffff60, v125
	ds_read2_b32 v[70:71], v123 offset0:16 offset1:17
	ds_read2_b32 v[140:141], v123 offset0:17 offset1:18
	ds_read2_b32 v[72:73], v123 offset0:19 offset1:20
	ds_read_b128 v[230:233], v213
	ds_read_b128 v[234:237], v214
	ds_read_b128 v[238:241], v215
	ds_read_b128 v[170:173], v216
	s_waitcnt lgkmcnt(4)
; #define MFMA(a, b, c) __builtin_amdgcn_mfma_f32_32x32x16_bf16((a), (b), (c), 0, 0, 0)
; DI float bf2f(u16 v) { return __uint_as_float(((unsigned)v) << 16); }
; template <int NB1>
; DI void hyena_item(const Params& p, char* wsb, int layer, int c, char* lds) {
;     ...
;       auto d1_range = [&](const int lo, const int hi, const int jmask) {
; #pragma unroll 1
;         for (int d1o = lo; d1o < hi; d1o += 2) {
; #pragma unroll
;           for (int dk = 0; dk < 4; ++dk) {
;             const int d1 = d1o + (dk >> 1), ks = dk & 1;
;             const unsigned* rp = Rd + (-16 * d1 + 8 * ks);
;             unsigned w[5];
; #pragma unroll
;             for (int q = 0; q < 5; ++q) w[q] = rp[q];
;             union { s16x8 v; unsigned u[4]; } af;
; #pragma unroll
;             for (int q = 0; q < 4; ++q) af.u[q] = __builtin_amdgcn_alignbit(w[q + 1], w[q], sh);
; #pragma unroll
;             for (int j = 0; j < TPW; ++j) {
;               if (!((jmask >> (j & 1)) & 1)) continue;
;               const bool ok = (unsigned)(tt1[j] - d1) < (unsigned)NB1;
;               const int addr = ok ? ub[j] - d1 * 80 + ks * 32 : zaddr;
;               const s16x8 bf = *(const s16x8*)(lds + addr);
;               acc[j] = MFMA(af.v, bf, acc[j]);
;             }
;           }
;         }
;       };
;       if (NB1 == 64) { d1_range(-64, -32, 1); d1_range(-32, 32, 3); d1_range(32, 64, 2); }
;       else d1_range(-NB1, NB1, 3);
; #pragma unroll
;       for (int j = 0; j < TPW; ++j) {
;         const u16* zr = zbase + ((size_t)(tb[j] * 1536 + xcol)) * L;
; #pragma unroll
;         for (int g4 = 0; g4 < 4; ++g4) {
;           const int t0 = 8 * g4 + 4 * h, t = 32 * tt1[j] + t0;
;           const int uidx = (tb[j] * NB1 + tt1[j]) * 40 + t0;
;           const uint2 uu = *(const uint2*)(U + uidx);
;           const uint2 zz = *(const uint2*)(zr + t);
;           const float zm1 = t > 0 ? bf2f(zr[t - 1]) : 0.f;
;           const float zp4 = t + 4 < L ? bf2f(zr[t + 4]) : 0.f;
	v_alignbit_b32 v70, v140, v70, v66
	v_alignbit_b32 v73, v73, v72, v69
	v_alignbit_b32 v72, v72, v141, v68
	v_alignbit_b32 v71, v141, v71, v67
	s_nop 1
	s_waitcnt lgkmcnt(3)
	v_mfma_f32_32x32x16_bf16 v[34:49], v[70:73], v[230:233], v[34:49]
	s_waitcnt lgkmcnt(2)
	v_mfma_f32_32x32x16_bf16 v[50:65], v[70:73], v[234:237], v[50:65]
	s_waitcnt lgkmcnt(1)
	v_mfma_f32_32x32x16_bf16 v[2:17], v[70:73], v[238:241], v[2:17]
	s_waitcnt lgkmcnt(0)
	v_mfma_f32_32x32x16_bf16 v[18:33], v[70:73], v[170:173], v[18:33]
	ds_read2_b32 v[70:71], v123 offset0:24 offset1:25
	ds_read2_b32 v[140:141], v123 offset0:25 offset1:26
	ds_read2_b32 v[72:73], v123 offset0:27 offset1:28
	ds_read_b128 v[230:233], v217
	ds_read_b128 v[234:237], v218
	ds_read_b128 v[238:241], v219
	ds_read_b128 v[170:173], v220
	s_waitcnt lgkmcnt(4)
	v_alignbit_b32 v70, v140, v70, v66
	v_alignbit_b32 v73, v73, v72, v69
	v_alignbit_b32 v72, v72, v141, v68
	v_alignbit_b32 v71, v141, v71, v67
	s_nop 1
	s_waitcnt lgkmcnt(3)
	v_mfma_f32_32x32x16_bf16 v[34:49], v[70:73], v[230:233], v[34:49]
	s_waitcnt lgkmcnt(2)
	v_mfma_f32_32x32x16_bf16 v[50:65], v[70:73], v[234:237], v[50:65]
	s_waitcnt lgkmcnt(1)
	v_mfma_f32_32x32x16_bf16 v[2:17], v[70:73], v[238:241], v[2:17]
	s_waitcnt lgkmcnt(0)
	v_mfma_f32_32x32x16_bf16 v[18:33], v[70:73], v[170:173], v[18:33]
	ds_read2_b32 v[70:71], v123 offset1:1
	ds_read2_b32 v[140:141], v123 offset0:1 offset1:2
	ds_read2_b32 v[72:73], v123 offset0:3 offset1:4
	ds_read_b128 v[230:233], v221
	ds_read_b128 v[234:237], v222
	ds_read_b128 v[238:241], v223
	ds_read_b128 v[170:173], v224
	s_waitcnt lgkmcnt(4)
	v_alignbit_b32 v70, v140, v70, v66
	v_alignbit_b32 v73, v73, v72, v69
	v_alignbit_b32 v72, v72, v141, v68
	v_alignbit_b32 v71, v141, v71, v67
	s_nop 1
	s_waitcnt lgkmcnt(3)
	v_mfma_f32_32x32x16_bf16 v[34:49], v[70:73], v[230:233], v[34:49]
	s_waitcnt lgkmcnt(2)
	v_mfma_f32_32x32x16_bf16 v[50:65], v[70:73], v[234:237], v[50:65]
	s_waitcnt lgkmcnt(1)
	v_mfma_f32_32x32x16_bf16 v[2:17], v[70:73], v[238:241], v[2:17]
	s_waitcnt lgkmcnt(0)
	v_mfma_f32_32x32x16_bf16 v[18:33], v[70:73], v[170:173], v[18:33]
	ds_read2_b32 v[70:71], v123 offset0:8 offset1:9
	ds_read2_b32 v[140:141], v123 offset0:9 offset1:10
	ds_read2_b32 v[72:73], v123 offset0:11 offset1:12
	ds_read_b128 v[230:233], v225
	ds_read_b128 v[234:237], v226
	ds_read_b128 v[238:241], v227
	ds_read_b128 v[170:173], v228
	s_waitcnt lgkmcnt(4)
	v_alignbit_b32 v70, v140, v70, v66
	v_alignbit_b32 v73, v73, v72, v69
	v_alignbit_b32 v72, v72, v141, v68
	v_alignbit_b32 v71, v141, v71, v67
	s_nop 1
	s_waitcnt lgkmcnt(3)
	v_mfma_f32_32x32x16_bf16 v[34:49], v[70:73], v[230:233], v[34:49]
	s_waitcnt lgkmcnt(2)
	v_mfma_f32_32x32x16_bf16 v[50:65], v[70:73], v[234:237], v[50:65]
	s_waitcnt lgkmcnt(1)
	v_mfma_f32_32x32x16_bf16 v[2:17], v[70:73], v[238:241], v[2:17]
	s_waitcnt lgkmcnt(0)
	v_mfma_f32_32x32x16_bf16 v[18:33], v[70:73], v[170:173], v[18:33]
	v_add_u32_e32 v123, 0xffffff80, v123
	s_cmp_lt_i32 s40, 30
	s_cbranch_scc1 .LBB0_869
	s_mov_b32 s8, 30
	v_mov_b32_e32 v70, v169
	v_mov_b32_e32 v71, v168
	v_mov_b32_e32 v72, v167
	v_mov_b32_e32 v73, v166
.LBB0_871:
	v_cmp_gt_u32_e32 vcc, 64, v72
	v_add_u32_e32 v246, 1, v73
	v_cmp_gt_u32_e64 s[6:7], 64, v246
	v_add_u32_e32 v213, 0x50, v71
	v_add_u32_e32 v214, 0x1450, v71
	v_add_u32_e32 v215, 0x70, v71
	v_add_u32_e32 v216, 0x1470, v71
	v_cndmask_b32_e32 v213, v212, v213, vcc
	v_cndmask_b32_e64 v214, v212, v214, s[6:7]
	v_cndmask_b32_e32 v215, v212, v215, vcc
	v_cndmask_b32_e64 v216, v212, v216, s[6:7]
	v_cmp_gt_u32_e32 vcc, 64, v73
	v_add_u32_e32 v246, -1, v72
	v_cmp_gt_u32_e64 s[6:7], 64, v246
	v_add_u32_e32 v218, 0x1400, v71
	v_add_u32_e32 v219, 32, v71
	v_add_u32_e32 v220, 0x1420, v71
	v_cndmask_b32_e64 v217, v212, v71, s[6:7]
	v_cndmask_b32_e32 v218, v212, v218, vcc
	v_cndmask_b32_e64 v219, v212, v219, s[6:7]
	v_cndmask_b32_e32 v220, v212, v220, vcc
	v_add_u32_e32 v73, -2, v73
	v_add_u32_e32 v72, -2, v72
	s_add_i32 s8, s8, 2
	ds_read2_b32 v[134:135], v70 offset0:16 offset1:17
	ds_read2_b32 v[138:139], v70 offset0:17 offset1:18
	ds_read2_b32 v[136:137], v70 offset0:19 offset1:20
	ds_read2_b32 v[222:223], v70 offset0:24 offset1:25
	ds_read2_b32 v[226:227], v70 offset0:25 offset1:26
	ds_read2_b32 v[224:225], v70 offset0:27 offset1:28
	ds_read_b128 v[230:233], v213
	ds_read_b128 v[234:237], v214
	ds_read_b128 v[238:241], v215
	ds_read_b128 v[170:173], v216
	s_waitcnt lgkmcnt(4)
	v_alignbit_b32 v134, v138, v134, v66
	v_alignbit_b32 v137, v137, v136, v69
	v_alignbit_b32 v136, v136, v139, v68
	v_alignbit_b32 v135, v139, v135, v67
	v_alignbit_b32 v222, v226, v222, v66
	v_alignbit_b32 v225, v225, v224, v69
	v_alignbit_b32 v224, v224, v227, v68
	v_alignbit_b32 v223, v227, v223, v67
	s_waitcnt lgkmcnt(3)
	v_mfma_f32_32x32x16_bf16 v[50:65], v[134:137], v[230:233], v[50:65]
	s_waitcnt lgkmcnt(2)
	v_mfma_f32_32x32x16_bf16 v[18:33], v[134:137], v[234:237], v[18:33]
	s_waitcnt lgkmcnt(1)
	v_mfma_f32_32x32x16_bf16 v[50:65], v[222:225], v[238:241], v[50:65]
	s_waitcnt lgkmcnt(0)
	v_mfma_f32_32x32x16_bf16 v[18:33], v[222:225], v[170:173], v[18:33]
	ds_read2_b32 v[134:135], v70 offset1:1
	ds_read2_b32 v[138:139], v70 offset0:1 offset1:2
	ds_read2_b32 v[136:137], v70 offset0:3 offset1:4
	ds_read2_b32 v[222:223], v70 offset0:8 offset1:9
	ds_read2_b32 v[226:227], v70 offset0:9 offset1:10
	ds_read2_b32 v[224:225], v70 offset0:11 offset1:12
	ds_read_b128 v[230:233], v217
	ds_read_b128 v[234:237], v218
	ds_read_b128 v[238:241], v219
	ds_read_b128 v[170:173], v220
	s_waitcnt lgkmcnt(4)
	v_alignbit_b32 v134, v138, v134, v66
	v_alignbit_b32 v137, v137, v136, v69
	v_alignbit_b32 v136, v136, v139, v68
	v_alignbit_b32 v135, v139, v135, v67
	v_alignbit_b32 v222, v226, v222, v66
	v_alignbit_b32 v225, v225, v224, v69
	v_alignbit_b32 v224, v224, v227, v68
	v_alignbit_b32 v223, v227, v223, v67
	s_waitcnt lgkmcnt(3)
	v_mfma_f32_32x32x16_bf16 v[50:65], v[134:137], v[230:233], v[50:65]
	s_waitcnt lgkmcnt(2)
	v_mfma_f32_32x32x16_bf16 v[18:33], v[134:137], v[234:237], v[18:33]
	s_waitcnt lgkmcnt(1)
	v_mfma_f32_32x32x16_bf16 v[50:65], v[222:225], v[238:241], v[50:65]
	s_waitcnt lgkmcnt(0)
	v_mfma_f32_32x32x16_bf16 v[18:33], v[222:225], v[170:173], v[18:33]
	v_add_u32_e32 v70, 0xffffff80, v70
	v_add_u32_e32 v71, 0xffffff60, v71
	s_cmp_lt_u32 s8, 62
	s_cbranch_scc1 .LBB0_871
	s_add_i32 s11, s11, s10
	v_add_u32_e32 v70, s11, v149
	v_ashrrev_i32_e32 v71, 31, v70
	v_lshlrev_b64 v[70:71], 12, v[70:71]
	v_lshl_add_u64 v[72:73], s[36:37], 0, v[70:71]
	v_lshl_add_u64 v[140:141], v[74:75], 1, v[72:73]
	global_load_dwordx2 v[136:137], v[140:141], off
	ds_read_b64 v[138:139], v148
	v_mov_b32_e32 v135, 0
	v_lshl_add_u64 v[70:71], v[0:1], 1, v[72:73]
	s_and_saveexec_b64 s[6:7], s[48:49]
	s_cbranch_execz .LBB0_874
	global_load_ushort v123, v[70:71], off offset:-2
	s_waitcnt vmcnt(0)
	v_lshlrev_b32_e32 v135, 16, v123

; DI void phase_norm(const Params& p, char* wsb, int layer, int which, int mrows, bool do_convert, char* lds) {
;     ...
; #pragma unroll 2
;   for (int row = blockIdx.x * 4 + wid; row < mrows; row += nw) {
;     const float4* xr = (const float4*)(xs + (size_t)row * 1024);
;     float4 v[4];
;     float ss = 0.f;
; #pragma unroll
;     for (int i = 0; i < 4; ++i) { v[i] = xr[lane + 64 * i]; ss += v[i].x * v[i].x + v[i].y * v[i].y + v[i].z * v[i].z + v[i].w * v[i].w; }
; #pragma unroll
;     for (int o = 32; o; o >>= 1) ss += __shfl_xor(ss, o);
;     const float r = rsqrtf(ss * (1.f / 1024.f) + 1e-6f);
;     const int mr = row < TL ? (row >> 11) : 8;
;     const float* sh = mods + (size_t)mr * 9216 + (3 * which) * 1024;
;     const float* sc = sh + 1024;
; #pragma unroll
;     for (int i = 0; i < 4; ++i) {
;       int col = (lane + 64 * i) * 4;
;       float4 gg = *(const float4*)(g + col), s4 = *(const float4*)(sh + col), c4 = *(const float4*)(sc + col);
;       float o0 = v[i].x * r * gg.x * (1.f + c4.x) + s4.x;
;       float o1 = v[i].y * r * gg.y * (1.f + c4.y) + s4.y;
;       float o2 = v[i].z * r * gg.z * (1.f + c4.z) + s4.z;
;       float o3 = v[i].w * r * gg.w * (1.f + c4.w) + s4.w;
;       *(uint2*)(H + (size_t)row * 1024 + col) = make_uint2(pack2(o0, o1), pack2(o2, o3));
.LBB0_1153:
	s_or_b64 exec, exec, s[6:7]
	v_readlane_b32 s6, v242, 9
	v_readlane_b32 s7, v242, 10
	s_and_b64 s[6:7], s[6:7], exec
	s_mov_b32 s10, s19
	v_mov_b32_e32 v0, v178
	s_movk_i32 s6, 0x4800
	s_waitcnt lgkmcnt(0)
	s_barrier
	s_cselect_b32 s12, 0x4000, s6
	v_ashrrev_i32_e32 v2, 6, v0
	v_add_u32_e32 v18, s87, v2
	v_cmp_gt_i32_e32 vcc, s12, v18
	s_and_saveexec_b64 s[6:7], vcc
	s_mov_b64 s[36:37], 0x1000
	s_cbranch_execz .LBB0_1156
	v_cmp_lt_i32_e32 vcc, v187, v186
	s_mov_b64 s[54:55], s[26:27]
	v_readlane_b32 s8, v242, 0
	v_cndmask_b32_e32 v4, v185, v187, vcc
	v_cmp_lt_i32_e32 vcc, v188, v186
	v_lshlrev_b32_e32 v48, 2, v4
	s_add_u32 s11, s54, s10
	v_cndmask_b32_e32 v4, v185, v188, vcc
	v_cmp_lt_i32_e32 vcc, v189, v186
	v_readlane_b32 s9, v242, 1
	s_mul_i32 s18, s8, 0xc00
	v_lshlrev_b32_e32 v49, 2, v4
	v_cndmask_b32_e32 v4, v185, v189, vcc
	v_cmp_lt_i32_e32 vcc, v190, v186
	s_addc_u32 s13, s55, 0
	s_lshl_b64 s[8:9], s[18:19], 2
	v_readlane_b32 s64, v243, 37
	v_lshlrev_b32_e32 v50, 2, v4
	v_cndmask_b32_e32 v4, v185, v190, vcc
	v_cmp_lt_i32_e32 vcc, v191, v186
	v_readlane_b32 s65, v243, 38
	s_add_u32 s8, s64, s8
	v_and_b32_e32 v3, 63, v0
	v_lshlrev_b32_e32 v51, 2, v4
	v_cndmask_b32_e32 v4, v185, v191, vcc
	v_cmp_lt_i32_e32 vcc, v192, v186
	s_addc_u32 s9, s65, s9
	v_lshlrev_b32_e32 v2, 2, v3
	v_lshlrev_b32_e32 v52, 2, v4
	v_cndmask_b32_e32 v4, v185, v192, vcc
	s_add_u32 s14, s8, 0x2000
	v_lshlrev_b32_e32 v53, 2, v4
	v_or_b32_e32 v4, 0x100, v2
	s_addc_u32 s15, s9, 0
	v_readlane_b32 s8, v242, 2
	v_lshlrev_b32_e32 v6, 2, v4
	v_mov_b32_e32 v7, v1
	s_add_u32 s8, s11, s8
	v_lshl_add_u64 v[22:23], s[14:15], 0, v[6:7]
	v_or_b32_e32 v6, 0x200, v2
	s_addc_u32 s9, s13, 0
	v_lshlrev_b32_e32 v8, 2, v6
	v_mov_b32_e32 v9, v1
	s_add_u32 s8, s8, 0xa000
	v_lshl_add_u64 v[24:25], s[14:15], 0, v[8:9]
	v_or_b32_e32 v8, 0x300, v2
	s_addc_u32 s9, s9, 0
	v_lshlrev_b32_e32 v0, 4, v3
	v_lshlrev_b32_e32 v10, 2, v8
	v_mov_b32_e32 v11, v1
	v_ashrrev_i32_e32 v19, 31, v18
	v_readlane_b32 s11, v243, 1
	v_lshl_add_u64 v[20:21], s[14:15], 0, v[0:1]
	v_lshl_add_u64 v[26:27], s[14:15], 0, v[10:11]
	v_lshlrev_b64 v[10:11], 12, v[18:19]
	s_add_u32 s14, s11, s10
	v_readlane_b32 s11, v243, 2
	v_or_b32_e32 v10, v10, v0
	s_addc_u32 s15, s11, 0
	v_readlane_b32 s11, v243, 3
	v_lshl_add_u64 v[28:29], s[14:15], 0, v[10:11]
	v_lshlrev_b64 v[10:11], 11, v[18:19]
	s_add_u32 s10, s11, s10
	v_readlane_b32 s11, v243, 4
	v_readlane_b32 s54, v243, 61
	v_lshl_or_b32 v10, v3, 3, v10
	s_addc_u32 s11, s11, 0
	v_readlane_b32 s55, v243, 62
	v_lshl_add_u64 v[30:31], s[10:11], 0, v[10:11]
	s_mov_b64 s[10:11], 0
	v_lshlrev_b32_e32 v0, 2, v2
	v_lshlrev_b32_e32 v32, 2, v4
	v_lshlrev_b32_e32 v34, 2, v6
	v_lshlrev_b32_e32 v36, 2, v8
	s_mov_b64 s[52:53], s[24:25]
	s_mov_b64 s[50:51], s[22:23]
	s_mov_b64 s[48:49], s[20:21]
	v_readlane_b32 s66, v243, 39
	v_readlane_b32 s67, v243, 40
	v_readlane_b32 s68, v243, 41
	v_readlane_b32 s69, v243, 42
	v_readlane_b32 s70, v243, 43
	v_readlane_b32 s71, v243, 44
	s_cmpk_lg_u32 s92, 0x200
	s_cbranch_scc1 .LBB0_1155
	global_load_dwordx4 v[138:141], v[20:21], off
	global_load_dwordx4 v[142:145], v[22:23], off
	global_load_dwordx4 v[246:249], v[24:25], off
	global_load_dwordx4 v[250:253], v[26:27], off
	s_mov_b64 s[64:65], s[8:9]
	s_add_u32 s66, s8, 0x1000
	s_addc_u32 s67, s9, 0
	s_cmp_gt_u32 s12, 0x4000
	s_cselect_b32 s68, 9, 8
	global_load_dwordx4 v[64:67], v[28:29], off offset:-2048
	global_load_dwordx4 v[68:71], v[28:29], off offset:-1024
	global_load_dwordx4 v[72:75], v[28:29], off
	global_load_dwordx4 v[76:79], v[28:29], off offset:1024
	v_lshl_add_u64 v[28:29], v[28:29], 0, s[54:55]
	global_load_dwordx4 v[80:83], v0, s[64:65]
	global_load_dwordx4 v[84:87], v0, s[64:65] offset:1024
	global_load_dwordx4 v[88:91], v0, s[64:65] offset:2048
	global_load_dwordx4 v[92:95], v0, s[64:65] offset:3072
	global_load_dwordx4 v[96:99], v0, s[66:67]
	global_load_dwordx4 v[100:103], v0, s[66:67] offset:1024
	global_load_dwordx4 v[104:107], v0, s[66:67] offset:2048
	global_load_dwordx4 v[108:111], v0, s[66:67] offset:3072
	s_add_u32 s64, s64, 0x9000
	s_addc_u32 s65, s65, 0
	s_add_u32 s66, s66, 0x9000
	s_addc_u32 s67, s67, 0
	global_load_dwordx4 v[214:217], v[28:29], off offset:-2048
	global_load_dwordx4 v[218:221], v[28:29], off offset:-1024
	global_load_dwordx4 v[222:225], v[28:29], off
	global_load_dwordx4 v[226:229], v[28:29], off offset:1024
	v_lshl_add_u64 v[28:29], v[28:29], 0, s[54:55]
	global_load_dwordx4 v[112:115], v0, s[64:65]
	global_load_dwordx4 v[116:119], v0, s[64:65] offset:1024
	global_load_dwordx4 v[120:123], v0, s[64:65] offset:2048
	global_load_dwordx4 v[126:129], v0, s[64:65] offset:3072
	global_load_dwordx4 v[230:233], v0, s[66:67]
	global_load_dwordx4 v[234:237], v0, s[66:67] offset:1024
	global_load_dwordx4 v[238:241], v0, s[66:67] offset:2048
	global_load_dwordx4 v[134:137], v0, s[66:67] offset:3072
	s_add_u32 s64, s64, 0x9000
	s_addc_u32 s65, s65, 0
	s_add_u32 s66, s66, 0x9000
	s_addc_u32 s67, s67, 0
	s_waitcnt vmcnt(12)
	v_mul_f32_e32 v37, v65, v65
	v_fmac_f32_e32 v37, v64, v64
	v_fmac_f32_e32 v37, v66, v66
	v_fmac_f32_e32 v37, v67, v67
	v_mul_f32_e32 v38, v69, v69
	v_fmac_f32_e32 v38, v68, v68
	v_fmac_f32_e32 v38, v70, v70
	v_fmac_f32_e32 v38, v71, v71
	v_mul_f32_e32 v39, v73, v73
	v_fmac_f32_e32 v39, v72, v72
	v_fmac_f32_e32 v39, v74, v74
	v_fmac_f32_e32 v39, v75, v75
	v_mul_f32_e32 v40, v77, v77
	v_fmac_f32_e32 v40, v76, v76
	v_fmac_f32_e32 v40, v78, v78
	v_fmac_f32_e32 v40, v79, v79
	v_add_f32_e32 v255, v37, v38
	v_add_f32_e32 v255, v255, v39
	v_add_f32_e32 v255, v255, v40
	ds_bpermute_b32 v254, v48, v255
	s_waitcnt lgkmcnt(0)
; DI void phase_norm(const Params& p, char* wsb, int layer, int which, int mrows, bool do_convert, char* lds) {
;     ...
;     for (int i = 0; i < 4; ++i) { v[i] = xr[lane + 64 * i]; ss += v[i].x * v[i].x + v[i].y * v[i].y + v[i].z * v[i].z + v[i].w * v[i].w; }
; #pragma unroll
;     for (int o = 32; o; o >>= 1) ss += __shfl_xor(ss, o);
;     const float r = rsqrtf(ss * (1.f / 1024.f) + 1e-6f);
;     const int mr = row < TL ? (row >> 11) : 8;
;     const float* sh = mods + (size_t)mr * 9216 + (3 * which) * 1024;
;     const float* sc = sh + 1024;
; #pragma unroll
;     for (int i = 0; i < 4; ++i) {
;       int col = (lane + 64 * i) * 4;
;       float4 gg = *(const float4*)(g + col), s4 = *(const float4*)(sh + col), c4 = *(const float4*)(sc + col);
;       float o0 = v[i].x * r * gg.x * (1.f + c4.x) + s4.x;
;       float o1 = v[i].y * r * gg.y * (1.f + c4.y) + s4.y;
;       float o2 = v[i].z * r * gg.z * (1.f + c4.z) + s4.z;
;       float o3 = v[i].w * r * gg.w * (1.f + c4.w) + s4.w;
;       *(uint2*)(H + (size_t)row * 1024 + col) = make_uint2(pack2(o0, o1), pack2(o2, o3));
	v_add_f32_e32 v255, v255, v254
	ds_bpermute_b32 v254, v49, v255
	s_waitcnt lgkmcnt(0)
	v_add_f32_e32 v255, v255, v254
	ds_bpermute_b32 v254, v50, v255
	s_waitcnt lgkmcnt(0)
	v_add_f32_e32 v255, v255, v254
	ds_bpermute_b32 v254, v51, v255
	s_waitcnt lgkmcnt(0)
	v_add_f32_e32 v255, v255, v254
	ds_bpermute_b32 v254, v52, v255
	s_waitcnt lgkmcnt(0)
	v_add_f32_e32 v255, v255, v254
	ds_bpermute_b32 v254, v53, v255
	s_waitcnt lgkmcnt(0)
	v_add_f32_e32 v255, v255, v254
	v_fmamk_f32 v255, v255, 0x3a800000, v179
	v_cmp_gt_f32_e32 vcc, s46, v255
	v_mul_f32_e32 v254, 0x4b800000, v255
	s_nop 0
	v_cndmask_b32_e32 v255, v255, v254, vcc
	v_rsq_f32_e32 v255, v255
	s_nop 0
	v_mul_f32_e32 v254, 0x45800000, v255
	v_cndmask_b32_e32 v56, v255, v254, vcc
	s_nop 0
	v_pk_mul_f32 v[64:65], v[64:65], v[56:57] op_sel_hi:[1,0]
	v_pk_mul_f32 v[66:67], v[66:67], v[56:57] op_sel_hi:[1,0]
	v_pk_add_f32 v[96:97], v[96:97], 1.0 op_sel_hi:[1,0]
	v_pk_add_f32 v[98:99], v[98:99], 1.0 op_sel_hi:[1,0]
	v_pk_mul_f32 v[64:65], v[138:139], v[64:65]
	v_pk_mul_f32 v[66:67], v[140:141], v[66:67]
	v_pk_fma_f32 v[64:65], v[96:97], v[64:65], v[80:81]
	v_pk_fma_f32 v[66:67], v[98:99], v[66:67], v[82:83]
	v_cvt_pk_bf16_f32 v58, v64, v65
	v_cvt_pk_bf16_f32 v59, v66, v67
	global_store_dwordx2 v[30:31], v[58:59], off offset:-1024
	v_pk_mul_f32 v[68:69], v[68:69], v[56:57] op_sel_hi:[1,0]
	v_pk_mul_f32 v[70:71], v[70:71], v[56:57] op_sel_hi:[1,0]
	v_pk_add_f32 v[100:101], v[100:101], 1.0 op_sel_hi:[1,0]
	v_pk_add_f32 v[102:103], v[102:103], 1.0 op_sel_hi:[1,0]
	v_pk_mul_f32 v[68:69], v[142:143], v[68:69]
	v_pk_mul_f32 v[70:71], v[144:145], v[70:71]
	v_pk_fma_f32 v[68:69], v[100:101], v[68:69], v[84:85]
	v_pk_fma_f32 v[70:71], v[102:103], v[70:71], v[86:87]
	v_cvt_pk_bf16_f32 v60, v68, v69
	v_cvt_pk_bf16_f32 v61, v70, v71
	global_store_dwordx2 v[30:31], v[60:61], off offset:-512
	v_pk_mul_f32 v[72:73], v[72:73], v[56:57] op_sel_hi:[1,0]
	v_pk_mul_f32 v[74:75], v[74:75], v[56:57] op_sel_hi:[1,0]
	v_pk_add_f32 v[104:105], v[104:105], 1.0 op_sel_hi:[1,0]
	v_pk_add_f32 v[106:107], v[106:107], 1.0 op_sel_hi:[1,0]
	v_pk_mul_f32 v[72:73], v[246:247], v[72:73]
	v_pk_mul_f32 v[74:75], v[248:249], v[74:75]
	v_pk_fma_f32 v[72:73], v[104:105], v[72:73], v[88:89]
	v_pk_fma_f32 v[74:75], v[106:107], v[74:75], v[90:91]
	v_cvt_pk_bf16_f32 v58, v72, v73
	v_cvt_pk_bf16_f32 v59, v74, v75
	global_store_dwordx2 v[30:31], v[58:59], off
	v_pk_mul_f32 v[76:77], v[76:77], v[56:57] op_sel_hi:[1,0]
	v_pk_mul_f32 v[78:79], v[78:79], v[56:57] op_sel_hi:[1,0]
	v_pk_add_f32 v[108:109], v[108:109], 1.0 op_sel_hi:[1,0]
	v_pk_add_f32 v[110:111], v[110:111], 1.0 op_sel_hi:[1,0]
	v_pk_mul_f32 v[76:77], v[250:251], v[76:77]
	v_pk_mul_f32 v[78:79], v[252:253], v[78:79]
	v_pk_fma_f32 v[76:77], v[108:109], v[76:77], v[92:93]
	v_pk_fma_f32 v[78:79], v[110:111], v[78:79], v[94:95]
	v_cvt_pk_bf16_f32 v60, v76, v77
	v_cvt_pk_bf16_f32 v61, v78, v79
	global_store_dwordx2 v[30:31], v[60:61], off offset:512
	v_lshl_add_u64 v[30:31], v[30:31], 0, s[16:17]
	global_load_dwordx4 v[64:67], v[28:29], off offset:-2048
	global_load_dwordx4 v[68:71], v[28:29], off offset:-1024
	global_load_dwordx4 v[72:75], v[28:29], off
	global_load_dwordx4 v[76:79], v[28:29], off offset:1024
	v_lshl_add_u64 v[28:29], v[28:29], 0, s[54:55]
	global_load_dwordx4 v[80:83], v0, s[64:65]
	global_load_dwordx4 v[84:87], v0, s[64:65] offset:1024
	global_load_dwordx4 v[88:91], v0, s[64:65] offset:2048
	global_load_dwordx4 v[92:95], v0, s[64:65] offset:3072
	global_load_dwordx4 v[96:99], v0, s[66:67]
	global_load_dwordx4 v[100:103], v0, s[66:67] offset:1024
	global_load_dwordx4 v[104:107], v0, s[66:67] offset:2048
	global_load_dwordx4 v[108:111], v0, s[66:67] offset:3072
	s_add_u32 s64, s64, 0x9000
	s_addc_u32 s65, s65, 0
	s_add_u32 s66, s66, 0x9000
	s_addc_u32 s67, s67, 0
	s_waitcnt vmcnt(16)
	v_mul_f32_e32 v37, v215, v215
	v_fmac_f32_e32 v37, v214, v214
	v_fmac_f32_e32 v37, v216, v216
	v_fmac_f32_e32 v37, v217, v217
	v_mul_f32_e32 v38, v219, v219
	v_fmac_f32_e32 v38, v218, v218
	v_fmac_f32_e32 v38, v220, v220
	v_fmac_f32_e32 v38, v221, v221
	v_mul_f32_e32 v39, v223, v223
	v_fmac_f32_e32 v39, v222, v222
	v_fmac_f32_e32 v39, v224, v224
	v_fmac_f32_e32 v39, v225, v225
	v_mul_f32_e32 v40, v227, v227
	v_fmac_f32_e32 v40, v226, v226
	v_fmac_f32_e32 v40, v228, v228
	v_fmac_f32_e32 v40, v229, v229
	v_add_f32_e32 v255, v37, v38
	v_add_f32_e32 v255, v255, v39
	v_add_f32_e32 v255, v255, v40
	ds_bpermute_b32 v254, v48, v255
	s_waitcnt lgkmcnt(0)
	v_add_f32_e32 v255, v255, v254
	ds_bpermute_b32 v254, v49, v255
	s_waitcnt lgkmcnt(0)
	v_add_f32_e32 v255, v255, v254
	ds_bpermute_b32 v254, v50, v255
	s_waitcnt lgkmcnt(0)
	v_add_f32_e32 v255, v255, v254
	ds_bpermute_b32 v254, v51, v255
	s_waitcnt lgkmcnt(0)
	v_add_f32_e32 v255, v255, v254
	ds_bpermute_b32 v254, v52, v255
	s_waitcnt lgkmcnt(0)
	v_add_f32_e32 v255, v255, v254
	ds_bpermute_b32 v254, v53, v255
	s_waitcnt lgkmcnt(0)
; DI void phase_norm(const Params& p, char* wsb, int layer, int which, int mrows, bool do_convert, char* lds) {
;     ...
;     for (int i = 0; i < 4; ++i) { v[i] = xr[lane + 64 * i]; ss += v[i].x * v[i].x + v[i].y * v[i].y + v[i].z * v[i].z + v[i].w * v[i].w; }
; #pragma unroll
;     for (int o = 32; o; o >>= 1) ss += __shfl_xor(ss, o);
;     const float r = rsqrtf(ss * (1.f / 1024.f) + 1e-6f);
;     const int mr = row < TL ? (row >> 11) : 8;
;     const float* sh = mods + (size_t)mr * 9216 + (3 * which) * 1024;
;     const float* sc = sh + 1024;
; #pragma unroll
;     for (int i = 0; i < 4; ++i) {
;       int col = (lane + 64 * i) * 4;
;       float4 gg = *(const float4*)(g + col), s4 = *(const float4*)(sh + col), c4 = *(const float4*)(sc + col);
;       float o0 = v[i].x * r * gg.x * (1.f + c4.x) + s4.x;
;       float o1 = v[i].y * r * gg.y * (1.f + c4.y) + s4.y;
;       float o2 = v[i].z * r * gg.z * (1.f + c4.z) + s4.z;
;       float o3 = v[i].w * r * gg.w * (1.f + c4.w) + s4.w;
;       *(uint2*)(H + (size_t)row * 1024 + col) = make_uint2(pack2(o0, o1), pack2(o2, o3));
	v_add_f32_e32 v255, v255, v254
	v_fmamk_f32 v255, v255, 0x3a800000, v179
	v_cmp_gt_f32_e32 vcc, s46, v255
	v_mul_f32_e32 v254, 0x4b800000, v255
	s_nop 0
	v_cndmask_b32_e32 v255, v255, v254, vcc
	v_rsq_f32_e32 v255, v255
	s_nop 0
	v_mul_f32_e32 v254, 0x45800000, v255
	v_cndmask_b32_e32 v56, v255, v254, vcc
	s_nop 0
	v_pk_mul_f32 v[214:215], v[214:215], v[56:57] op_sel_hi:[1,0]
	v_pk_mul_f32 v[216:217], v[216:217], v[56:57] op_sel_hi:[1,0]
	v_pk_add_f32 v[230:231], v[230:231], 1.0 op_sel_hi:[1,0]
	v_pk_add_f32 v[232:233], v[232:233], 1.0 op_sel_hi:[1,0]
	v_pk_mul_f32 v[214:215], v[138:139], v[214:215]
	v_pk_mul_f32 v[216:217], v[140:141], v[216:217]
	v_pk_fma_f32 v[214:215], v[230:231], v[214:215], v[112:113]
	v_pk_fma_f32 v[216:217], v[232:233], v[216:217], v[114:115]
	v_cvt_pk_bf16_f32 v58, v214, v215
	v_cvt_pk_bf16_f32 v59, v216, v217
	global_store_dwordx2 v[30:31], v[58:59], off offset:-1024
	v_pk_mul_f32 v[218:219], v[218:219], v[56:57] op_sel_hi:[1,0]
	v_pk_mul_f32 v[220:221], v[220:221], v[56:57] op_sel_hi:[1,0]
	v_pk_add_f32 v[234:235], v[234:235], 1.0 op_sel_hi:[1,0]
	v_pk_add_f32 v[236:237], v[236:237], 1.0 op_sel_hi:[1,0]
	v_pk_mul_f32 v[218:219], v[142:143], v[218:219]
	v_pk_mul_f32 v[220:221], v[144:145], v[220:221]
	v_pk_fma_f32 v[218:219], v[234:235], v[218:219], v[116:117]
	v_pk_fma_f32 v[220:221], v[236:237], v[220:221], v[118:119]
	v_cvt_pk_bf16_f32 v60, v218, v219
	v_cvt_pk_bf16_f32 v61, v220, v221
	global_store_dwordx2 v[30:31], v[60:61], off offset:-512
	v_pk_mul_f32 v[222:223], v[222:223], v[56:57] op_sel_hi:[1,0]
	v_pk_mul_f32 v[224:225], v[224:225], v[56:57] op_sel_hi:[1,0]
	v_pk_add_f32 v[238:239], v[238:239], 1.0 op_sel_hi:[1,0]
	v_pk_add_f32 v[240:241], v[240:241], 1.0 op_sel_hi:[1,0]
	v_pk_mul_f32 v[222:223], v[246:247], v[222:223]
	v_pk_mul_f32 v[224:225], v[248:249], v[224:225]
	v_pk_fma_f32 v[222:223], v[238:239], v[222:223], v[120:121]
	v_pk_fma_f32 v[224:225], v[240:241], v[224:225], v[122:123]
	v_cvt_pk_bf16_f32 v58, v222, v223
	v_cvt_pk_bf16_f32 v59, v224, v225
	global_store_dwordx2 v[30:31], v[58:59], off
	v_pk_mul_f32 v[226:227], v[226:227], v[56:57] op_sel_hi:[1,0]
	v_pk_mul_f32 v[228:229], v[228:229], v[56:57] op_sel_hi:[1,0]
	v_pk_add_f32 v[134:135], v[134:135], 1.0 op_sel_hi:[1,0]
	v_pk_add_f32 v[136:137], v[136:137], 1.0 op_sel_hi:[1,0]
	v_pk_mul_f32 v[226:227], v[250:251], v[226:227]
	v_pk_mul_f32 v[228:229], v[252:253], v[228:229]
	v_pk_fma_f32 v[226:227], v[134:135], v[226:227], v[126:127]
	v_pk_fma_f32 v[228:229], v[136:137], v[228:229], v[128:129]
	v_cvt_pk_bf16_f32 v60, v226, v227
	v_cvt_pk_bf16_f32 v61, v228, v229
	global_store_dwordx2 v[30:31], v[60:61], off offset:512
	v_lshl_add_u64 v[30:31], v[30:31], 0, s[16:17]
	global_load_dwordx4 v[214:217], v[28:29], off offset:-2048
	global_load_dwordx4 v[218:221], v[28:29], off offset:-1024
	global_load_dwordx4 v[222:225], v[28:29], off
	global_load_dwordx4 v[226:229], v[28:29], off offset:1024
	v_lshl_add_u64 v[28:29], v[28:29], 0, s[54:55]
	global_load_dwordx4 v[112:115], v0, s[64:65]
	global_load_dwordx4 v[116:119], v0, s[64:65] offset:1024
	global_load_dwordx4 v[120:123], v0, s[64:65] offset:2048
	global_load_dwordx4 v[126:129], v0, s[64:65] offset:3072
	global_load_dwordx4 v[230:233], v0, s[66:67]
	global_load_dwordx4 v[234:237], v0, s[66:67] offset:1024
	global_load_dwordx4 v[238:241], v0, s[66:67] offset:2048
	global_load_dwordx4 v[134:137], v0, s[66:67] offset:3072
	s_add_u32 s64, s64, 0x9000
	s_addc_u32 s65, s65, 0
	s_add_u32 s66, s66, 0x9000
	s_addc_u32 s67, s67, 0
	s_waitcnt vmcnt(16)
	v_mul_f32_e32 v37, v65, v65
	v_fmac_f32_e32 v37, v64, v64
	v_fmac_f32_e32 v37, v66, v66
	v_fmac_f32_e32 v37, v67, v67
	v_mul_f32_e32 v38, v69, v69
	v_fmac_f32_e32 v38, v68, v68
	v_fmac_f32_e32 v38, v70, v70
	v_fmac_f32_e32 v38, v71, v71
	v_mul_f32_e32 v39, v73, v73
	v_fmac_f32_e32 v39, v72, v72
	v_fmac_f32_e32 v39, v74, v74
	v_fmac_f32_e32 v39, v75, v75
	v_mul_f32_e32 v40, v77, v77
	v_fmac_f32_e32 v40, v76, v76
	v_fmac_f32_e32 v40, v78, v78
	v_fmac_f32_e32 v40, v79, v79
	v_add_f32_e32 v255, v37, v38
	v_add_f32_e32 v255, v255, v39
	v_add_f32_e32 v255, v255, v40
	ds_bpermute_b32 v254, v48, v255
	s_waitcnt lgkmcnt(0)
	v_add_f32_e32 v255, v255, v254
	ds_bpermute_b32 v254, v49, v255
	s_waitcnt lgkmcnt(0)
	v_add_f32_e32 v255, v255, v254
	ds_bpermute_b32 v254, v50, v255
	s_waitcnt lgkmcnt(0)
	v_add_f32_e32 v255, v255, v254
	ds_bpermute_b32 v254, v51, v255
	s_waitcnt lgkmcnt(0)
	v_add_f32_e32 v255, v255, v254
	ds_bpermute_b32 v254, v52, v255
	s_waitcnt lgkmcnt(0)
	v_add_f32_e32 v255, v255, v254
	ds_bpermute_b32 v254, v53, v255
	s_waitcnt lgkmcnt(0)
; DI void phase_norm(const Params& p, char* wsb, int layer, int which, int mrows, bool do_convert, char* lds) {
;     ...
;     for (int i = 0; i < 4; ++i) { v[i] = xr[lane + 64 * i]; ss += v[i].x * v[i].x + v[i].y * v[i].y + v[i].z * v[i].z + v[i].w * v[i].w; }
; #pragma unroll
;     for (int o = 32; o; o >>= 1) ss += __shfl_xor(ss, o);
;     const float r = rsqrtf(ss * (1.f / 1024.f) + 1e-6f);
;     const int mr = row < TL ? (row >> 11) : 8;
;     const float* sh = mods + (size_t)mr * 9216 + (3 * which) * 1024;
;     const float* sc = sh + 1024;
; #pragma unroll
;     for (int i = 0; i < 4; ++i) {
;       int col = (lane + 64 * i) * 4;
;       float4 gg = *(const float4*)(g + col), s4 = *(const float4*)(sh + col), c4 = *(const float4*)(sc + col);
;       float o0 = v[i].x * r * gg.x * (1.f + c4.x) + s4.x;
;       float o1 = v[i].y * r * gg.y * (1.f + c4.y) + s4.y;
;       float o2 = v[i].z * r * gg.z * (1.f + c4.z) + s4.z;
;       float o3 = v[i].w * r * gg.w * (1.f + c4.w) + s4.w;
;       *(uint2*)(H + (size_t)row * 1024 + col) = make_uint2(pack2(o0, o1), pack2(o2, o3));
	v_add_f32_e32 v255, v255, v254
	v_fmamk_f32 v255, v255, 0x3a800000, v179
	v_cmp_gt_f32_e32 vcc, s46, v255
	v_mul_f32_e32 v254, 0x4b800000, v255
	s_nop 0
	v_cndmask_b32_e32 v255, v255, v254, vcc
	v_rsq_f32_e32 v255, v255
	s_nop 0
	v_mul_f32_e32 v254, 0x45800000, v255
	v_cndmask_b32_e32 v56, v255, v254, vcc
	s_nop 0
	v_pk_mul_f32 v[64:65], v[64:65], v[56:57] op_sel_hi:[1,0]
	v_pk_mul_f32 v[66:67], v[66:67], v[56:57] op_sel_hi:[1,0]
	v_pk_add_f32 v[96:97], v[96:97], 1.0 op_sel_hi:[1,0]
	v_pk_add_f32 v[98:99], v[98:99], 1.0 op_sel_hi:[1,0]
	v_pk_mul_f32 v[64:65], v[138:139], v[64:65]
	v_pk_mul_f32 v[66:67], v[140:141], v[66:67]
	v_pk_fma_f32 v[64:65], v[96:97], v[64:65], v[80:81]
	v_pk_fma_f32 v[66:67], v[98:99], v[66:67], v[82:83]
	v_cvt_pk_bf16_f32 v58, v64, v65
	v_cvt_pk_bf16_f32 v59, v66, v67
	global_store_dwordx2 v[30:31], v[58:59], off offset:-1024
	v_pk_mul_f32 v[68:69], v[68:69], v[56:57] op_sel_hi:[1,0]
	v_pk_mul_f32 v[70:71], v[70:71], v[56:57] op_sel_hi:[1,0]
	v_pk_add_f32 v[100:101], v[100:101], 1.0 op_sel_hi:[1,0]
	v_pk_add_f32 v[102:103], v[102:103], 1.0 op_sel_hi:[1,0]
	v_pk_mul_f32 v[68:69], v[142:143], v[68:69]
	v_pk_mul_f32 v[70:71], v[144:145], v[70:71]
	v_pk_fma_f32 v[68:69], v[100:101], v[68:69], v[84:85]
	v_pk_fma_f32 v[70:71], v[102:103], v[70:71], v[86:87]
	v_cvt_pk_bf16_f32 v60, v68, v69
	v_cvt_pk_bf16_f32 v61, v70, v71
	global_store_dwordx2 v[30:31], v[60:61], off offset:-512
	v_pk_mul_f32 v[72:73], v[72:73], v[56:57] op_sel_hi:[1,0]
	v_pk_mul_f32 v[74:75], v[74:75], v[56:57] op_sel_hi:[1,0]
	v_pk_add_f32 v[104:105], v[104:105], 1.0 op_sel_hi:[1,0]
	v_pk_add_f32 v[106:107], v[106:107], 1.0 op_sel_hi:[1,0]
	v_pk_mul_f32 v[72:73], v[246:247], v[72:73]
	v_pk_mul_f32 v[74:75], v[248:249], v[74:75]
	v_pk_fma_f32 v[72:73], v[104:105], v[72:73], v[88:89]
	v_pk_fma_f32 v[74:75], v[106:107], v[74:75], v[90:91]
	v_cvt_pk_bf16_f32 v58, v72, v73
	v_cvt_pk_bf16_f32 v59, v74, v75
	global_store_dwordx2 v[30:31], v[58:59], off
	v_pk_mul_f32 v[76:77], v[76:77], v[56:57] op_sel_hi:[1,0]
	v_pk_mul_f32 v[78:79], v[78:79], v[56:57] op_sel_hi:[1,0]
	v_pk_add_f32 v[108:109], v[108:109], 1.0 op_sel_hi:[1,0]
	v_pk_add_f32 v[110:111], v[110:111], 1.0 op_sel_hi:[1,0]
	v_pk_mul_f32 v[76:77], v[250:251], v[76:77]
	v_pk_mul_f32 v[78:79], v[252:253], v[78:79]
	v_pk_fma_f32 v[76:77], v[108:109], v[76:77], v[92:93]
	v_pk_fma_f32 v[78:79], v[110:111], v[78:79], v[94:95]
	v_cvt_pk_bf16_f32 v60, v76, v77
	v_cvt_pk_bf16_f32 v61, v78, v79
	global_store_dwordx2 v[30:31], v[60:61], off offset:512
	v_lshl_add_u64 v[30:31], v[30:31], 0, s[16:17]
	global_load_dwordx4 v[64:67], v[28:29], off offset:-2048
	global_load_dwordx4 v[68:71], v[28:29], off offset:-1024
	global_load_dwordx4 v[72:75], v[28:29], off
	global_load_dwordx4 v[76:79], v[28:29], off offset:1024
	v_lshl_add_u64 v[28:29], v[28:29], 0, s[54:55]
	global_load_dwordx4 v[80:83], v0, s[64:65]
	global_load_dwordx4 v[84:87], v0, s[64:65] offset:1024
	global_load_dwordx4 v[88:91], v0, s[64:65] offset:2048
	global_load_dwordx4 v[92:95], v0, s[64:65] offset:3072
	global_load_dwordx4 v[96:99], v0, s[66:67]
	global_load_dwordx4 v[100:103], v0, s[66:67] offset:1024
	global_load_dwordx4 v[104:107], v0, s[66:67] offset:2048
	global_load_dwordx4 v[108:111], v0, s[66:67] offset:3072
	s_add_u32 s64, s64, 0x9000
	s_addc_u32 s65, s65, 0
	s_add_u32 s66, s66, 0x9000
	s_addc_u32 s67, s67, 0
	s_waitcnt vmcnt(16)
	v_mul_f32_e32 v37, v215, v215
	v_fmac_f32_e32 v37, v214, v214
	v_fmac_f32_e32 v37, v216, v216
	v_fmac_f32_e32 v37, v217, v217
	v_mul_f32_e32 v38, v219, v219
	v_fmac_f32_e32 v38, v218, v218
	v_fmac_f32_e32 v38, v220, v220
	v_fmac_f32_e32 v38, v221, v221
	v_mul_f32_e32 v39, v223, v223
	v_fmac_f32_e32 v39, v222, v222
	v_fmac_f32_e32 v39, v224, v224
	v_fmac_f32_e32 v39, v225, v225
	v_mul_f32_e32 v40, v227, v227
	v_fmac_f32_e32 v40, v226, v226
	v_fmac_f32_e32 v40, v228, v228
	v_fmac_f32_e32 v40, v229, v229
	v_add_f32_e32 v255, v37, v38
	v_add_f32_e32 v255, v255, v39
	v_add_f32_e32 v255, v255, v40
	ds_bpermute_b32 v254, v48, v255
	s_waitcnt lgkmcnt(0)
	v_add_f32_e32 v255, v255, v254
	ds_bpermute_b32 v254, v49, v255
	s_waitcnt lgkmcnt(0)
	v_add_f32_e32 v255, v255, v254
	ds_bpermute_b32 v254, v50, v255
	s_waitcnt lgkmcnt(0)
	v_add_f32_e32 v255, v255, v254
	ds_bpermute_b32 v254, v51, v255
	s_waitcnt lgkmcnt(0)
	v_add_f32_e32 v255, v255, v254
	ds_bpermute_b32 v254, v52, v255
	s_waitcnt lgkmcnt(0)
	v_add_f32_e32 v255, v255, v254
	ds_bpermute_b32 v254, v53, v255
	s_waitcnt lgkmcnt(0)
; DI void phase_norm(const Params& p, char* wsb, int layer, int which, int mrows, bool do_convert, char* lds) {
;     ...
;     for (int i = 0; i < 4; ++i) { v[i] = xr[lane + 64 * i]; ss += v[i].x * v[i].x + v[i].y * v[i].y + v[i].z * v[i].z + v[i].w * v[i].w; }
; #pragma unroll
;     for (int o = 32; o; o >>= 1) ss += __shfl_xor(ss, o);
;     const float r = rsqrtf(ss * (1.f / 1024.f) + 1e-6f);
;     const int mr = row < TL ? (row >> 11) : 8;
;     const float* sh = mods + (size_t)mr * 9216 + (3 * which) * 1024;
;     const float* sc = sh + 1024;
; #pragma unroll
;     for (int i = 0; i < 4; ++i) {
;       int col = (lane + 64 * i) * 4;
;       float4 gg = *(const float4*)(g + col), s4 = *(const float4*)(sh + col), c4 = *(const float4*)(sc + col);
;       float o0 = v[i].x * r * gg.x * (1.f + c4.x) + s4.x;
;       float o1 = v[i].y * r * gg.y * (1.f + c4.y) + s4.y;
;       float o2 = v[i].z * r * gg.z * (1.f + c4.z) + s4.z;
;       float o3 = v[i].w * r * gg.w * (1.f + c4.w) + s4.w;
;       *(uint2*)(H + (size_t)row * 1024 + col) = make_uint2(pack2(o0, o1), pack2(o2, o3));
	v_add_f32_e32 v255, v255, v254
	v_fmamk_f32 v255, v255, 0x3a800000, v179
	v_cmp_gt_f32_e32 vcc, s46, v255
	v_mul_f32_e32 v254, 0x4b800000, v255
	s_nop 0
	v_cndmask_b32_e32 v255, v255, v254, vcc
	v_rsq_f32_e32 v255, v255
	s_nop 0
	v_mul_f32_e32 v254, 0x45800000, v255
	v_cndmask_b32_e32 v56, v255, v254, vcc
	s_nop 0
	v_pk_mul_f32 v[214:215], v[214:215], v[56:57] op_sel_hi:[1,0]
	v_pk_mul_f32 v[216:217], v[216:217], v[56:57] op_sel_hi:[1,0]
	v_pk_add_f32 v[230:231], v[230:231], 1.0 op_sel_hi:[1,0]
	v_pk_add_f32 v[232:233], v[232:233], 1.0 op_sel_hi:[1,0]
	v_pk_mul_f32 v[214:215], v[138:139], v[214:215]
	v_pk_mul_f32 v[216:217], v[140:141], v[216:217]
	v_pk_fma_f32 v[214:215], v[230:231], v[214:215], v[112:113]
	v_pk_fma_f32 v[216:217], v[232:233], v[216:217], v[114:115]
	v_cvt_pk_bf16_f32 v58, v214, v215
	v_cvt_pk_bf16_f32 v59, v216, v217
	global_store_dwordx2 v[30:31], v[58:59], off offset:-1024
	v_pk_mul_f32 v[218:219], v[218:219], v[56:57] op_sel_hi:[1,0]
	v_pk_mul_f32 v[220:221], v[220:221], v[56:57] op_sel_hi:[1,0]
	v_pk_add_f32 v[234:235], v[234:235], 1.0 op_sel_hi:[1,0]
	v_pk_add_f32 v[236:237], v[236:237], 1.0 op_sel_hi:[1,0]
	v_pk_mul_f32 v[218:219], v[142:143], v[218:219]
	v_pk_mul_f32 v[220:221], v[144:145], v[220:221]
	v_pk_fma_f32 v[218:219], v[234:235], v[218:219], v[116:117]
	v_pk_fma_f32 v[220:221], v[236:237], v[220:221], v[118:119]
	v_cvt_pk_bf16_f32 v60, v218, v219
	v_cvt_pk_bf16_f32 v61, v220, v221
	global_store_dwordx2 v[30:31], v[60:61], off offset:-512
	v_pk_mul_f32 v[222:223], v[222:223], v[56:57] op_sel_hi:[1,0]
	v_pk_mul_f32 v[224:225], v[224:225], v[56:57] op_sel_hi:[1,0]
	v_pk_add_f32 v[238:239], v[238:239], 1.0 op_sel_hi:[1,0]
	v_pk_add_f32 v[240:241], v[240:241], 1.0 op_sel_hi:[1,0]
	v_pk_mul_f32 v[222:223], v[246:247], v[222:223]
	v_pk_mul_f32 v[224:225], v[248:249], v[224:225]
	v_pk_fma_f32 v[222:223], v[238:239], v[222:223], v[120:121]
	v_pk_fma_f32 v[224:225], v[240:241], v[224:225], v[122:123]
	v_cvt_pk_bf16_f32 v58, v222, v223
	v_cvt_pk_bf16_f32 v59, v224, v225
	global_store_dwordx2 v[30:31], v[58:59], off
	v_pk_mul_f32 v[226:227], v[226:227], v[56:57] op_sel_hi:[1,0]
	v_pk_mul_f32 v[228:229], v[228:229], v[56:57] op_sel_hi:[1,0]
	v_pk_add_f32 v[134:135], v[134:135], 1.0 op_sel_hi:[1,0]
	v_pk_add_f32 v[136:137], v[136:137], 1.0 op_sel_hi:[1,0]
	v_pk_mul_f32 v[226:227], v[250:251], v[226:227]
	v_pk_mul_f32 v[228:229], v[252:253], v[228:229]
	v_pk_fma_f32 v[226:227], v[134:135], v[226:227], v[126:127]
	v_pk_fma_f32 v[228:229], v[136:137], v[228:229], v[128:129]
	v_cvt_pk_bf16_f32 v60, v226, v227
	v_cvt_pk_bf16_f32 v61, v228, v229
	global_store_dwordx2 v[30:31], v[60:61], off offset:512
	v_lshl_add_u64 v[30:31], v[30:31], 0, s[16:17]
	global_load_dwordx4 v[214:217], v[28:29], off offset:-2048
	global_load_dwordx4 v[218:221], v[28:29], off offset:-1024
	global_load_dwordx4 v[222:225], v[28:29], off
	global_load_dwordx4 v[226:229], v[28:29], off offset:1024
	v_lshl_add_u64 v[28:29], v[28:29], 0, s[54:55]
	global_load_dwordx4 v[112:115], v0, s[64:65]
	global_load_dwordx4 v[116:119], v0, s[64:65] offset:1024
	global_load_dwordx4 v[120:123], v0, s[64:65] offset:2048
	global_load_dwordx4 v[126:129], v0, s[64:65] offset:3072
	global_load_dwordx4 v[230:233], v0, s[66:67]
	global_load_dwordx4 v[234:237], v0, s[66:67] offset:1024
	global_load_dwordx4 v[238:241], v0, s[66:67] offset:2048
	global_load_dwordx4 v[134:137], v0, s[66:67] offset:3072
	s_add_u32 s64, s64, 0x9000
	s_addc_u32 s65, s65, 0
	s_add_u32 s66, s66, 0x9000
	s_addc_u32 s67, s67, 0
	s_waitcnt vmcnt(16)
	v_mul_f32_e32 v37, v65, v65
	v_fmac_f32_e32 v37, v64, v64
	v_fmac_f32_e32 v37, v66, v66
	v_fmac_f32_e32 v37, v67, v67
	v_mul_f32_e32 v38, v69, v69
	v_fmac_f32_e32 v38, v68, v68
	v_fmac_f32_e32 v38, v70, v70
	v_fmac_f32_e32 v38, v71, v71
	v_mul_f32_e32 v39, v73, v73
	v_fmac_f32_e32 v39, v72, v72
	v_fmac_f32_e32 v39, v74, v74
	v_fmac_f32_e32 v39, v75, v75
	v_mul_f32_e32 v40, v77, v77
	v_fmac_f32_e32 v40, v76, v76
	v_fmac_f32_e32 v40, v78, v78
	v_fmac_f32_e32 v40, v79, v79
	v_add_f32_e32 v255, v37, v38
	v_add_f32_e32 v255, v255, v39
	v_add_f32_e32 v255, v255, v40
	ds_bpermute_b32 v254, v48, v255
	s_waitcnt lgkmcnt(0)
	v_add_f32_e32 v255, v255, v254
	ds_bpermute_b32 v254, v49, v255
	s_waitcnt lgkmcnt(0)
	v_add_f32_e32 v255, v255, v254
	ds_bpermute_b32 v254, v50, v255
	s_waitcnt lgkmcnt(0)
	v_add_f32_e32 v255, v255, v254
	ds_bpermute_b32 v254, v51, v255
	s_waitcnt lgkmcnt(0)
	v_add_f32_e32 v255, v255, v254
	ds_bpermute_b32 v254, v52, v255
	s_waitcnt lgkmcnt(0)
	v_add_f32_e32 v255, v255, v254
	ds_bpermute_b32 v254, v53, v255
	s_waitcnt lgkmcnt(0)
; DI void phase_norm(const Params& p, char* wsb, int layer, int which, int mrows, bool do_convert, char* lds) {
;     ...
;     for (int i = 0; i < 4; ++i) { v[i] = xr[lane + 64 * i]; ss += v[i].x * v[i].x + v[i].y * v[i].y + v[i].z * v[i].z + v[i].w * v[i].w; }
; #pragma unroll
;     for (int o = 32; o; o >>= 1) ss += __shfl_xor(ss, o);
;     const float r = rsqrtf(ss * (1.f / 1024.f) + 1e-6f);
;     const int mr = row < TL ? (row >> 11) : 8;
;     const float* sh = mods + (size_t)mr * 9216 + (3 * which) * 1024;
;     const float* sc = sh + 1024;
; #pragma unroll
;     for (int i = 0; i < 4; ++i) {
;       int col = (lane + 64 * i) * 4;
;       float4 gg = *(const float4*)(g + col), s4 = *(const float4*)(sh + col), c4 = *(const float4*)(sc + col);
;       float o0 = v[i].x * r * gg.x * (1.f + c4.x) + s4.x;
;       float o1 = v[i].y * r * gg.y * (1.f + c4.y) + s4.y;
;       float o2 = v[i].z * r * gg.z * (1.f + c4.z) + s4.z;
;       float o3 = v[i].w * r * gg.w * (1.f + c4.w) + s4.w;
;       *(uint2*)(H + (size_t)row * 1024 + col) = make_uint2(pack2(o0, o1), pack2(o2, o3));
	v_add_f32_e32 v255, v255, v254
	v_fmamk_f32 v255, v255, 0x3a800000, v179
	v_cmp_gt_f32_e32 vcc, s46, v255
	v_mul_f32_e32 v254, 0x4b800000, v255
	s_nop 0
	v_cndmask_b32_e32 v255, v255, v254, vcc
	v_rsq_f32_e32 v255, v255
	s_nop 0
	v_mul_f32_e32 v254, 0x45800000, v255
	v_cndmask_b32_e32 v56, v255, v254, vcc
	s_nop 0
	v_pk_mul_f32 v[64:65], v[64:65], v[56:57] op_sel_hi:[1,0]
	v_pk_mul_f32 v[66:67], v[66:67], v[56:57] op_sel_hi:[1,0]
	v_pk_add_f32 v[96:97], v[96:97], 1.0 op_sel_hi:[1,0]
	v_pk_add_f32 v[98:99], v[98:99], 1.0 op_sel_hi:[1,0]
	v_pk_mul_f32 v[64:65], v[138:139], v[64:65]
	v_pk_mul_f32 v[66:67], v[140:141], v[66:67]
	v_pk_fma_f32 v[64:65], v[96:97], v[64:65], v[80:81]
	v_pk_fma_f32 v[66:67], v[98:99], v[66:67], v[82:83]
	v_cvt_pk_bf16_f32 v58, v64, v65
	v_cvt_pk_bf16_f32 v59, v66, v67
	global_store_dwordx2 v[30:31], v[58:59], off offset:-1024
	v_pk_mul_f32 v[68:69], v[68:69], v[56:57] op_sel_hi:[1,0]
	v_pk_mul_f32 v[70:71], v[70:71], v[56:57] op_sel_hi:[1,0]
	v_pk_add_f32 v[100:101], v[100:101], 1.0 op_sel_hi:[1,0]
	v_pk_add_f32 v[102:103], v[102:103], 1.0 op_sel_hi:[1,0]
	v_pk_mul_f32 v[68:69], v[142:143], v[68:69]
	v_pk_mul_f32 v[70:71], v[144:145], v[70:71]
	v_pk_fma_f32 v[68:69], v[100:101], v[68:69], v[84:85]
	v_pk_fma_f32 v[70:71], v[102:103], v[70:71], v[86:87]
	v_cvt_pk_bf16_f32 v60, v68, v69
	v_cvt_pk_bf16_f32 v61, v70, v71
	global_store_dwordx2 v[30:31], v[60:61], off offset:-512
	v_pk_mul_f32 v[72:73], v[72:73], v[56:57] op_sel_hi:[1,0]
	v_pk_mul_f32 v[74:75], v[74:75], v[56:57] op_sel_hi:[1,0]
	v_pk_add_f32 v[104:105], v[104:105], 1.0 op_sel_hi:[1,0]
	v_pk_add_f32 v[106:107], v[106:107], 1.0 op_sel_hi:[1,0]
	v_pk_mul_f32 v[72:73], v[246:247], v[72:73]
	v_pk_mul_f32 v[74:75], v[248:249], v[74:75]
	v_pk_fma_f32 v[72:73], v[104:105], v[72:73], v[88:89]
	v_pk_fma_f32 v[74:75], v[106:107], v[74:75], v[90:91]
	v_cvt_pk_bf16_f32 v58, v72, v73
	v_cvt_pk_bf16_f32 v59, v74, v75
	global_store_dwordx2 v[30:31], v[58:59], off
	v_pk_mul_f32 v[76:77], v[76:77], v[56:57] op_sel_hi:[1,0]
	v_pk_mul_f32 v[78:79], v[78:79], v[56:57] op_sel_hi:[1,0]
	v_pk_add_f32 v[108:109], v[108:109], 1.0 op_sel_hi:[1,0]
	v_pk_add_f32 v[110:111], v[110:111], 1.0 op_sel_hi:[1,0]
	v_pk_mul_f32 v[76:77], v[250:251], v[76:77]
	v_pk_mul_f32 v[78:79], v[252:253], v[78:79]
	v_pk_fma_f32 v[76:77], v[108:109], v[76:77], v[92:93]
	v_pk_fma_f32 v[78:79], v[110:111], v[78:79], v[94:95]
	v_cvt_pk_bf16_f32 v60, v76, v77
	v_cvt_pk_bf16_f32 v61, v78, v79
	global_store_dwordx2 v[30:31], v[60:61], off offset:512
	v_lshl_add_u64 v[30:31], v[30:31], 0, s[16:17]
	global_load_dwordx4 v[64:67], v[28:29], off offset:-2048
	global_load_dwordx4 v[68:71], v[28:29], off offset:-1024
	global_load_dwordx4 v[72:75], v[28:29], off
	global_load_dwordx4 v[76:79], v[28:29], off offset:1024
	v_lshl_add_u64 v[28:29], v[28:29], 0, s[54:55]
	global_load_dwordx4 v[80:83], v0, s[64:65]
	global_load_dwordx4 v[84:87], v0, s[64:65] offset:1024
	global_load_dwordx4 v[88:91], v0, s[64:65] offset:2048
	global_load_dwordx4 v[92:95], v0, s[64:65] offset:3072
	global_load_dwordx4 v[96:99], v0, s[66:67]
	global_load_dwordx4 v[100:103], v0, s[66:67] offset:1024
	global_load_dwordx4 v[104:107], v0, s[66:67] offset:2048
	global_load_dwordx4 v[108:111], v0, s[66:67] offset:3072
	s_add_u32 s64, s64, 0x9000
	s_addc_u32 s65, s65, 0
	s_add_u32 s66, s66, 0x9000
	s_addc_u32 s67, s67, 0
	s_waitcnt vmcnt(16)
	v_mul_f32_e32 v37, v215, v215
	v_fmac_f32_e32 v37, v214, v214
	v_fmac_f32_e32 v37, v216, v216
	v_fmac_f32_e32 v37, v217, v217
	v_mul_f32_e32 v38, v219, v219
	v_fmac_f32_e32 v38, v218, v218
	v_fmac_f32_e32 v38, v220, v220
	v_fmac_f32_e32 v38, v221, v221
	v_mul_f32_e32 v39, v223, v223
	v_fmac_f32_e32 v39, v222, v222
	v_fmac_f32_e32 v39, v224, v224
	v_fmac_f32_e32 v39, v225, v225
	v_mul_f32_e32 v40, v227, v227
	v_fmac_f32_e32 v40, v226, v226
	v_fmac_f32_e32 v40, v228, v228
	v_fmac_f32_e32 v40, v229, v229
	v_add_f32_e32 v255, v37, v38
	v_add_f32_e32 v255, v255, v39
	v_add_f32_e32 v255, v255, v40
	ds_bpermute_b32 v254, v48, v255
	s_waitcnt lgkmcnt(0)
	v_add_f32_e32 v255, v255, v254
	ds_bpermute_b32 v254, v49, v255
	s_waitcnt lgkmcnt(0)
	v_add_f32_e32 v255, v255, v254
	ds_bpermute_b32 v254, v50, v255
	s_waitcnt lgkmcnt(0)
	v_add_f32_e32 v255, v255, v254
	ds_bpermute_b32 v254, v51, v255
	s_waitcnt lgkmcnt(0)
	v_add_f32_e32 v255, v255, v254
	ds_bpermute_b32 v254, v52, v255
	s_waitcnt lgkmcnt(0)
	v_add_f32_e32 v255, v255, v254
	ds_bpermute_b32 v254, v53, v255
	s_waitcnt lgkmcnt(0)
; DI void phase_norm(const Params& p, char* wsb, int layer, int which, int mrows, bool do_convert, char* lds) {
;     ...
;     for (int i = 0; i < 4; ++i) { v[i] = xr[lane + 64 * i]; ss += v[i].x * v[i].x + v[i].y * v[i].y + v[i].z * v[i].z + v[i].w * v[i].w; }
; #pragma unroll
;     for (int o = 32; o; o >>= 1) ss += __shfl_xor(ss, o);
;     const float r = rsqrtf(ss * (1.f / 1024.f) + 1e-6f);
;     const int mr = row < TL ? (row >> 11) : 8;
;     const float* sh = mods + (size_t)mr * 9216 + (3 * which) * 1024;
;     const float* sc = sh + 1024;
; #pragma unroll
;     for (int i = 0; i < 4; ++i) {
;       int col = (lane + 64 * i) * 4;
;       float4 gg = *(const float4*)(g + col), s4 = *(const float4*)(sh + col), c4 = *(const float4*)(sc + col);
;       float o0 = v[i].x * r * gg.x * (1.f + c4.x) + s4.x;
;       float o1 = v[i].y * r * gg.y * (1.f + c4.y) + s4.y;
;       float o2 = v[i].z * r * gg.z * (1.f + c4.z) + s4.z;
;       float o3 = v[i].w * r * gg.w * (1.f + c4.w) + s4.w;
;       *(uint2*)(H + (size_t)row * 1024 + col) = make_uint2(pack2(o0, o1), pack2(o2, o3));
	v_add_f32_e32 v255, v255, v254
	v_fmamk_f32 v255, v255, 0x3a800000, v179
	v_cmp_gt_f32_e32 vcc, s46, v255
	v_mul_f32_e32 v254, 0x4b800000, v255
	s_nop 0
	v_cndmask_b32_e32 v255, v255, v254, vcc
	v_rsq_f32_e32 v255, v255
	s_nop 0
	v_mul_f32_e32 v254, 0x45800000, v255
	v_cndmask_b32_e32 v56, v255, v254, vcc
	s_nop 0
	v_pk_mul_f32 v[214:215], v[214:215], v[56:57] op_sel_hi:[1,0]
	v_pk_mul_f32 v[216:217], v[216:217], v[56:57] op_sel_hi:[1,0]
	v_pk_add_f32 v[230:231], v[230:231], 1.0 op_sel_hi:[1,0]
	v_pk_add_f32 v[232:233], v[232:233], 1.0 op_sel_hi:[1,0]
	v_pk_mul_f32 v[214:215], v[138:139], v[214:215]
	v_pk_mul_f32 v[216:217], v[140:141], v[216:217]
	v_pk_fma_f32 v[214:215], v[230:231], v[214:215], v[112:113]
	v_pk_fma_f32 v[216:217], v[232:233], v[216:217], v[114:115]
	v_cvt_pk_bf16_f32 v58, v214, v215
	v_cvt_pk_bf16_f32 v59, v216, v217
	global_store_dwordx2 v[30:31], v[58:59], off offset:-1024
	v_pk_mul_f32 v[218:219], v[218:219], v[56:57] op_sel_hi:[1,0]
	v_pk_mul_f32 v[220:221], v[220:221], v[56:57] op_sel_hi:[1,0]
	v_pk_add_f32 v[234:235], v[234:235], 1.0 op_sel_hi:[1,0]
	v_pk_add_f32 v[236:237], v[236:237], 1.0 op_sel_hi:[1,0]
	v_pk_mul_f32 v[218:219], v[142:143], v[218:219]
	v_pk_mul_f32 v[220:221], v[144:145], v[220:221]
	v_pk_fma_f32 v[218:219], v[234:235], v[218:219], v[116:117]
	v_pk_fma_f32 v[220:221], v[236:237], v[220:221], v[118:119]
	v_cvt_pk_bf16_f32 v60, v218, v219
	v_cvt_pk_bf16_f32 v61, v220, v221
	global_store_dwordx2 v[30:31], v[60:61], off offset:-512
	v_pk_mul_f32 v[222:223], v[222:223], v[56:57] op_sel_hi:[1,0]
	v_pk_mul_f32 v[224:225], v[224:225], v[56:57] op_sel_hi:[1,0]
	v_pk_add_f32 v[238:239], v[238:239], 1.0 op_sel_hi:[1,0]
	v_pk_add_f32 v[240:241], v[240:241], 1.0 op_sel_hi:[1,0]
	v_pk_mul_f32 v[222:223], v[246:247], v[222:223]
	v_pk_mul_f32 v[224:225], v[248:249], v[224:225]
	v_pk_fma_f32 v[222:223], v[238:239], v[222:223], v[120:121]
	v_pk_fma_f32 v[224:225], v[240:241], v[224:225], v[122:123]
	v_cvt_pk_bf16_f32 v58, v222, v223
	v_cvt_pk_bf16_f32 v59, v224, v225
	global_store_dwordx2 v[30:31], v[58:59], off
	v_pk_mul_f32 v[226:227], v[226:227], v[56:57] op_sel_hi:[1,0]
	v_pk_mul_f32 v[228:229], v[228:229], v[56:57] op_sel_hi:[1,0]
	v_pk_add_f32 v[134:135], v[134:135], 1.0 op_sel_hi:[1,0]
	v_pk_add_f32 v[136:137], v[136:137], 1.0 op_sel_hi:[1,0]
	v_pk_mul_f32 v[226:227], v[250:251], v[226:227]
	v_pk_mul_f32 v[228:229], v[252:253], v[228:229]
	v_pk_fma_f32 v[226:227], v[134:135], v[226:227], v[126:127]
	v_pk_fma_f32 v[228:229], v[136:137], v[228:229], v[128:129]
	v_cvt_pk_bf16_f32 v60, v226, v227
	v_cvt_pk_bf16_f32 v61, v228, v229
	global_store_dwordx2 v[30:31], v[60:61], off offset:512
	v_lshl_add_u64 v[30:31], v[30:31], 0, s[16:17]
	global_load_dwordx4 v[214:217], v[28:29], off offset:-2048
	global_load_dwordx4 v[218:221], v[28:29], off offset:-1024
	global_load_dwordx4 v[222:225], v[28:29], off
	global_load_dwordx4 v[226:229], v[28:29], off offset:1024
	v_lshl_add_u64 v[28:29], v[28:29], 0, s[54:55]
	global_load_dwordx4 v[112:115], v0, s[64:65]
	global_load_dwordx4 v[116:119], v0, s[64:65] offset:1024
	global_load_dwordx4 v[120:123], v0, s[64:65] offset:2048
	global_load_dwordx4 v[126:129], v0, s[64:65] offset:3072
	global_load_dwordx4 v[230:233], v0, s[66:67]
	global_load_dwordx4 v[234:237], v0, s[66:67] offset:1024
	global_load_dwordx4 v[238:241], v0, s[66:67] offset:2048
	global_load_dwordx4 v[134:137], v0, s[66:67] offset:3072
	s_add_u32 s64, s64, 0x9000
	s_addc_u32 s65, s65, 0
	s_add_u32 s66, s66, 0x9000
	s_addc_u32 s67, s67, 0
	s_waitcnt vmcnt(16)
	v_mul_f32_e32 v37, v65, v65
	v_fmac_f32_e32 v37, v64, v64
	v_fmac_f32_e32 v37, v66, v66
	v_fmac_f32_e32 v37, v67, v67
	v_mul_f32_e32 v38, v69, v69
	v_fmac_f32_e32 v38, v68, v68
	v_fmac_f32_e32 v38, v70, v70
	v_fmac_f32_e32 v38, v71, v71
	v_mul_f32_e32 v39, v73, v73
	v_fmac_f32_e32 v39, v72, v72
	v_fmac_f32_e32 v39, v74, v74
	v_fmac_f32_e32 v39, v75, v75
	v_mul_f32_e32 v40, v77, v77
	v_fmac_f32_e32 v40, v76, v76
	v_fmac_f32_e32 v40, v78, v78
	v_fmac_f32_e32 v40, v79, v79
	v_add_f32_e32 v255, v37, v38
	v_add_f32_e32 v255, v255, v39
	v_add_f32_e32 v255, v255, v40
	ds_bpermute_b32 v254, v48, v255
	s_waitcnt lgkmcnt(0)
	v_add_f32_e32 v255, v255, v254
	ds_bpermute_b32 v254, v49, v255
	s_waitcnt lgkmcnt(0)
	v_add_f32_e32 v255, v255, v254
	ds_bpermute_b32 v254, v50, v255
	s_waitcnt lgkmcnt(0)
	v_add_f32_e32 v255, v255, v254
	ds_bpermute_b32 v254, v51, v255
	s_waitcnt lgkmcnt(0)
	v_add_f32_e32 v255, v255, v254
	ds_bpermute_b32 v254, v52, v255
	s_waitcnt lgkmcnt(0)
	v_add_f32_e32 v255, v255, v254
	ds_bpermute_b32 v254, v53, v255
	s_waitcnt lgkmcnt(0)
; DI void phase_norm(const Params& p, char* wsb, int layer, int which, int mrows, bool do_convert, char* lds) {
;     ...
;     for (int i = 0; i < 4; ++i) { v[i] = xr[lane + 64 * i]; ss += v[i].x * v[i].x + v[i].y * v[i].y + v[i].z * v[i].z + v[i].w * v[i].w; }
; #pragma unroll
;     for (int o = 32; o; o >>= 1) ss += __shfl_xor(ss, o);
;     const float r = rsqrtf(ss * (1.f / 1024.f) + 1e-6f);
;     const int mr = row < TL ? (row >> 11) : 8;
;     const float* sh = mods + (size_t)mr * 9216 + (3 * which) * 1024;
;     const float* sc = sh + 1024;
; #pragma unroll
;     for (int i = 0; i < 4; ++i) {
;       int col = (lane + 64 * i) * 4;
;       float4 gg = *(const float4*)(g + col), s4 = *(const float4*)(sh + col), c4 = *(const float4*)(sc + col);
;       float o0 = v[i].x * r * gg.x * (1.f + c4.x) + s4.x;
;       float o1 = v[i].y * r * gg.y * (1.f + c4.y) + s4.y;
;       float o2 = v[i].z * r * gg.z * (1.f + c4.z) + s4.z;
;       float o3 = v[i].w * r * gg.w * (1.f + c4.w) + s4.w;
;       *(uint2*)(H + (size_t)row * 1024 + col) = make_uint2(pack2(o0, o1), pack2(o2, o3));
	v_add_f32_e32 v255, v255, v254
	v_fmamk_f32 v255, v255, 0x3a800000, v179
	v_cmp_gt_f32_e32 vcc, s46, v255
	v_mul_f32_e32 v254, 0x4b800000, v255
	s_nop 0
	v_cndmask_b32_e32 v255, v255, v254, vcc
	v_rsq_f32_e32 v255, v255
	s_nop 0
	v_mul_f32_e32 v254, 0x45800000, v255
	v_cndmask_b32_e32 v56, v255, v254, vcc
	s_nop 0
	v_pk_mul_f32 v[64:65], v[64:65], v[56:57] op_sel_hi:[1,0]
	v_pk_mul_f32 v[66:67], v[66:67], v[56:57] op_sel_hi:[1,0]
	v_pk_add_f32 v[96:97], v[96:97], 1.0 op_sel_hi:[1,0]
	v_pk_add_f32 v[98:99], v[98:99], 1.0 op_sel_hi:[1,0]
	v_pk_mul_f32 v[64:65], v[138:139], v[64:65]
	v_pk_mul_f32 v[66:67], v[140:141], v[66:67]
	v_pk_fma_f32 v[64:65], v[96:97], v[64:65], v[80:81]
	v_pk_fma_f32 v[66:67], v[98:99], v[66:67], v[82:83]
	v_cvt_pk_bf16_f32 v58, v64, v65
	v_cvt_pk_bf16_f32 v59, v66, v67
	global_store_dwordx2 v[30:31], v[58:59], off offset:-1024
	v_pk_mul_f32 v[68:69], v[68:69], v[56:57] op_sel_hi:[1,0]
	v_pk_mul_f32 v[70:71], v[70:71], v[56:57] op_sel_hi:[1,0]
	v_pk_add_f32 v[100:101], v[100:101], 1.0 op_sel_hi:[1,0]
	v_pk_add_f32 v[102:103], v[102:103], 1.0 op_sel_hi:[1,0]
	v_pk_mul_f32 v[68:69], v[142:143], v[68:69]
	v_pk_mul_f32 v[70:71], v[144:145], v[70:71]
	v_pk_fma_f32 v[68:69], v[100:101], v[68:69], v[84:85]
	v_pk_fma_f32 v[70:71], v[102:103], v[70:71], v[86:87]
	v_cvt_pk_bf16_f32 v60, v68, v69
	v_cvt_pk_bf16_f32 v61, v70, v71
	global_store_dwordx2 v[30:31], v[60:61], off offset:-512
	v_pk_mul_f32 v[72:73], v[72:73], v[56:57] op_sel_hi:[1,0]
	v_pk_mul_f32 v[74:75], v[74:75], v[56:57] op_sel_hi:[1,0]
	v_pk_add_f32 v[104:105], v[104:105], 1.0 op_sel_hi:[1,0]
	v_pk_add_f32 v[106:107], v[106:107], 1.0 op_sel_hi:[1,0]
	v_pk_mul_f32 v[72:73], v[246:247], v[72:73]
	v_pk_mul_f32 v[74:75], v[248:249], v[74:75]
	v_pk_fma_f32 v[72:73], v[104:105], v[72:73], v[88:89]
	v_pk_fma_f32 v[74:75], v[106:107], v[74:75], v[90:91]
	v_cvt_pk_bf16_f32 v58, v72, v73
	v_cvt_pk_bf16_f32 v59, v74, v75
	global_store_dwordx2 v[30:31], v[58:59], off
	v_pk_mul_f32 v[76:77], v[76:77], v[56:57] op_sel_hi:[1,0]
	v_pk_mul_f32 v[78:79], v[78:79], v[56:57] op_sel_hi:[1,0]
	v_pk_add_f32 v[108:109], v[108:109], 1.0 op_sel_hi:[1,0]
	v_pk_add_f32 v[110:111], v[110:111], 1.0 op_sel_hi:[1,0]
	v_pk_mul_f32 v[76:77], v[250:251], v[76:77]
	v_pk_mul_f32 v[78:79], v[252:253], v[78:79]
	v_pk_fma_f32 v[76:77], v[108:109], v[76:77], v[92:93]
	v_pk_fma_f32 v[78:79], v[110:111], v[78:79], v[94:95]
	v_cvt_pk_bf16_f32 v60, v76, v77
	v_cvt_pk_bf16_f32 v61, v78, v79
	global_store_dwordx2 v[30:31], v[60:61], off offset:512
	v_lshl_add_u64 v[30:31], v[30:31], 0, s[16:17]
	s_cmp_lt_u32 s68, 9
	s_cbranch_scc1 .Lnrm2_nopf
	global_load_dwordx4 v[64:67], v[28:29], off offset:-2048
	global_load_dwordx4 v[68:71], v[28:29], off offset:-1024
	global_load_dwordx4 v[72:75], v[28:29], off
	global_load_dwordx4 v[76:79], v[28:29], off offset:1024
	v_lshl_add_u64 v[28:29], v[28:29], 0, s[54:55]
	global_load_dwordx4 v[80:83], v0, s[64:65]
	global_load_dwordx4 v[84:87], v0, s[64:65] offset:1024
	global_load_dwordx4 v[88:91], v0, s[64:65] offset:2048
	global_load_dwordx4 v[92:95], v0, s[64:65] offset:3072
	global_load_dwordx4 v[96:99], v0, s[66:67]
	global_load_dwordx4 v[100:103], v0, s[66:67] offset:1024
	global_load_dwordx4 v[104:107], v0, s[66:67] offset:2048
	global_load_dwordx4 v[108:111], v0, s[66:67] offset:3072
	s_add_u32 s64, s64, 0x9000
	s_addc_u32 s65, s65, 0
	s_add_u32 s66, s66, 0x9000
	s_addc_u32 s67, s67, 0
	s_waitcnt vmcnt(16)
	s_branch .Lnrm2_c7
.Lnrm2_nopf:
	s_waitcnt vmcnt(4)
.Lnrm2_c7:
	v_mul_f32_e32 v37, v215, v215
	v_fmac_f32_e32 v37, v214, v214
	v_fmac_f32_e32 v37, v216, v216
	v_fmac_f32_e32 v37, v217, v217
	v_mul_f32_e32 v38, v219, v219
	v_fmac_f32_e32 v38, v218, v218
	v_fmac_f32_e32 v38, v220, v220
	v_fmac_f32_e32 v38, v221, v221
	v_mul_f32_e32 v39, v223, v223
	v_fmac_f32_e32 v39, v222, v222
	v_fmac_f32_e32 v39, v224, v224
	v_fmac_f32_e32 v39, v225, v225
	v_mul_f32_e32 v40, v227, v227
	v_fmac_f32_e32 v40, v226, v226
	v_fmac_f32_e32 v40, v228, v228
	v_fmac_f32_e32 v40, v229, v229
	v_add_f32_e32 v255, v37, v38
	v_add_f32_e32 v255, v255, v39
	v_add_f32_e32 v255, v255, v40
	ds_bpermute_b32 v254, v48, v255
	s_waitcnt lgkmcnt(0)
	v_add_f32_e32 v255, v255, v254
	ds_bpermute_b32 v254, v49, v255
	s_waitcnt lgkmcnt(0)
	v_add_f32_e32 v255, v255, v254
	ds_bpermute_b32 v254, v50, v255
	s_waitcnt lgkmcnt(0)
	v_add_f32_e32 v255, v255, v254
	ds_bpermute_b32 v254, v51, v255
	s_waitcnt lgkmcnt(0)
	v_add_f32_e32 v255, v255, v254
	ds_bpermute_b32 v254, v52, v255
	s_waitcnt lgkmcnt(0)
	v_add_f32_e32 v255, v255, v254
	ds_bpermute_b32 v254, v53, v255
	s_waitcnt lgkmcnt(0)
; DI void phase_norm(const Params& p, char* wsb, int layer, int which, int mrows, bool do_convert, char* lds) {
;     ...
;     for (int i = 0; i < 4; ++i) { v[i] = xr[lane + 64 * i]; ss += v[i].x * v[i].x + v[i].y * v[i].y + v[i].z * v[i].z + v[i].w * v[i].w; }
; #pragma unroll
;     for (int o = 32; o; o >>= 1) ss += __shfl_xor(ss, o);
;     const float r = rsqrtf(ss * (1.f / 1024.f) + 1e-6f);
;     const int mr = row < TL ? (row >> 11) : 8;
;     const float* sh = mods + (size_t)mr * 9216 + (3 * which) * 1024;
;     const float* sc = sh + 1024;
; #pragma unroll
;     for (int i = 0; i < 4; ++i) {
;       int col = (lane + 64 * i) * 4;
;       float4 gg = *(const float4*)(g + col), s4 = *(const float4*)(sh + col), c4 = *(const float4*)(sc + col);
;       float o0 = v[i].x * r * gg.x * (1.f + c4.x) + s4.x;
;       float o1 = v[i].y * r * gg.y * (1.f + c4.y) + s4.y;
;       float o2 = v[i].z * r * gg.z * (1.f + c4.z) + s4.z;
;       float o3 = v[i].w * r * gg.w * (1.f + c4.w) + s4.w;
;       *(uint2*)(H + (size_t)row * 1024 + col) = make_uint2(pack2(o0, o1), pack2(o2, o3));
	v_add_f32_e32 v255, v255, v254
	v_fmamk_f32 v255, v255, 0x3a800000, v179
	v_cmp_gt_f32_e32 vcc, s46, v255
	v_mul_f32_e32 v254, 0x4b800000, v255
	s_nop 0
	v_cndmask_b32_e32 v255, v255, v254, vcc
	v_rsq_f32_e32 v255, v255
	s_nop 0
	v_mul_f32_e32 v254, 0x45800000, v255
	v_cndmask_b32_e32 v56, v255, v254, vcc
	s_nop 0
	v_pk_mul_f32 v[214:215], v[214:215], v[56:57] op_sel_hi:[1,0]
	v_pk_mul_f32 v[216:217], v[216:217], v[56:57] op_sel_hi:[1,0]
	v_pk_add_f32 v[230:231], v[230:231], 1.0 op_sel_hi:[1,0]
	v_pk_add_f32 v[232:233], v[232:233], 1.0 op_sel_hi:[1,0]
	v_pk_mul_f32 v[214:215], v[138:139], v[214:215]
	v_pk_mul_f32 v[216:217], v[140:141], v[216:217]
	v_pk_fma_f32 v[214:215], v[230:231], v[214:215], v[112:113]
	v_pk_fma_f32 v[216:217], v[232:233], v[216:217], v[114:115]
	v_cvt_pk_bf16_f32 v58, v214, v215
	v_cvt_pk_bf16_f32 v59, v216, v217
	global_store_dwordx2 v[30:31], v[58:59], off offset:-1024
	v_pk_mul_f32 v[218:219], v[218:219], v[56:57] op_sel_hi:[1,0]
	v_pk_mul_f32 v[220:221], v[220:221], v[56:57] op_sel_hi:[1,0]
	v_pk_add_f32 v[234:235], v[234:235], 1.0 op_sel_hi:[1,0]
	v_pk_add_f32 v[236:237], v[236:237], 1.0 op_sel_hi:[1,0]
	v_pk_mul_f32 v[218:219], v[142:143], v[218:219]
	v_pk_mul_f32 v[220:221], v[144:145], v[220:221]
	v_pk_fma_f32 v[218:219], v[234:235], v[218:219], v[116:117]
	v_pk_fma_f32 v[220:221], v[236:237], v[220:221], v[118:119]
	v_cvt_pk_bf16_f32 v60, v218, v219
	v_cvt_pk_bf16_f32 v61, v220, v221
	global_store_dwordx2 v[30:31], v[60:61], off offset:-512
	v_pk_mul_f32 v[222:223], v[222:223], v[56:57] op_sel_hi:[1,0]
	v_pk_mul_f32 v[224:225], v[224:225], v[56:57] op_sel_hi:[1,0]
	v_pk_add_f32 v[238:239], v[238:239], 1.0 op_sel_hi:[1,0]
	v_pk_add_f32 v[240:241], v[240:241], 1.0 op_sel_hi:[1,0]
	v_pk_mul_f32 v[222:223], v[246:247], v[222:223]
	v_pk_mul_f32 v[224:225], v[248:249], v[224:225]
	v_pk_fma_f32 v[222:223], v[238:239], v[222:223], v[120:121]
	v_pk_fma_f32 v[224:225], v[240:241], v[224:225], v[122:123]
	v_cvt_pk_bf16_f32 v58, v222, v223
	v_cvt_pk_bf16_f32 v59, v224, v225
	global_store_dwordx2 v[30:31], v[58:59], off
	v_pk_mul_f32 v[226:227], v[226:227], v[56:57] op_sel_hi:[1,0]
	v_pk_mul_f32 v[228:229], v[228:229], v[56:57] op_sel_hi:[1,0]
	v_pk_add_f32 v[134:135], v[134:135], 1.0 op_sel_hi:[1,0]
	v_pk_add_f32 v[136:137], v[136:137], 1.0 op_sel_hi:[1,0]
	v_pk_mul_f32 v[226:227], v[250:251], v[226:227]
	v_pk_mul_f32 v[228:229], v[252:253], v[228:229]
	v_pk_fma_f32 v[226:227], v[134:135], v[226:227], v[126:127]
	v_pk_fma_f32 v[228:229], v[136:137], v[228:229], v[128:129]
	v_cvt_pk_bf16_f32 v60, v226, v227
	v_cvt_pk_bf16_f32 v61, v228, v229
	global_store_dwordx2 v[30:31], v[60:61], off offset:512
	v_lshl_add_u64 v[30:31], v[30:31], 0, s[16:17]
	s_cmp_lt_u32 s68, 9
	s_cbranch_scc1 .Lnrm2_done
	s_waitcnt vmcnt(4)
	v_mul_f32_e32 v37, v65, v65
	v_fmac_f32_e32 v37, v64, v64
	v_fmac_f32_e32 v37, v66, v66
	v_fmac_f32_e32 v37, v67, v67
	v_mul_f32_e32 v38, v69, v69
	v_fmac_f32_e32 v38, v68, v68
	v_fmac_f32_e32 v38, v70, v70
	v_fmac_f32_e32 v38, v71, v71
	v_mul_f32_e32 v39, v73, v73
	v_fmac_f32_e32 v39, v72, v72
	v_fmac_f32_e32 v39, v74, v74
	v_fmac_f32_e32 v39, v75, v75
	v_mul_f32_e32 v40, v77, v77
	v_fmac_f32_e32 v40, v76, v76
	v_fmac_f32_e32 v40, v78, v78
	v_fmac_f32_e32 v40, v79, v79
	v_add_f32_e32 v255, v37, v38
	v_add_f32_e32 v255, v255, v39
	v_add_f32_e32 v255, v255, v40
	ds_bpermute_b32 v254, v48, v255
	s_waitcnt lgkmcnt(0)
	v_add_f32_e32 v255, v255, v254
	ds_bpermute_b32 v254, v49, v255
	s_waitcnt lgkmcnt(0)
	v_add_f32_e32 v255, v255, v254
	ds_bpermute_b32 v254, v50, v255
	s_waitcnt lgkmcnt(0)
	v_add_f32_e32 v255, v255, v254
	ds_bpermute_b32 v254, v51, v255
	s_waitcnt lgkmcnt(0)
	v_add_f32_e32 v255, v255, v254
	ds_bpermute_b32 v254, v52, v255
	s_waitcnt lgkmcnt(0)
	v_add_f32_e32 v255, v255, v254
	ds_bpermute_b32 v254, v53, v255
	s_waitcnt lgkmcnt(0)
	v_add_f32_e32 v255, v255, v254
	v_fmamk_f32 v255, v255, 0x3a800000, v179
	v_cmp_gt_f32_e32 vcc, s46, v255
	v_mul_f32_e32 v254, 0x4b800000, v255
	s_nop 0
	v_cndmask_b32_e32 v255, v255, v254, vcc
	v_rsq_f32_e32 v255, v255
	s_nop 0
	v_mul_f32_e32 v254, 0x45800000, v255
	v_cndmask_b32_e32 v56, v255, v254, vcc
	s_nop 0
	v_pk_mul_f32 v[64:65], v[64:65], v[56:57] op_sel_hi:[1,0]
	v_pk_mul_f32 v[66:67], v[66:67], v[56:57] op_sel_hi:[1,0]
	v_pk_add_f32 v[96:97], v[96:97], 1.0 op_sel_hi:[1,0]
	v_pk_add_f32 v[98:99], v[98:99], 1.0 op_sel_hi:[1,0]
	v_pk_mul_f32 v[64:65], v[138:139], v[64:65]
	v_pk_mul_f32 v[66:67], v[140:141], v[66:67]
	v_pk_fma_f32 v[64:65], v[96:97], v[64:65], v[80:81]
	v_pk_fma_f32 v[66:67], v[98:99], v[66:67], v[82:83]
	v_cvt_pk_bf16_f32 v58, v64, v65
	v_cvt_pk_bf16_f32 v59, v66, v67
	global_store_dwordx2 v[30:31], v[58:59], off offset:-1024
	v_pk_mul_f32 v[68:69], v[68:69], v[56:57] op_sel_hi:[1,0]
	v_pk_mul_f32 v[70:71], v[70:71], v[56:57] op_sel_hi:[1,0]
	v_pk_add_f32 v[100:101], v[100:101], 1.0 op_sel_hi:[1,0]
	v_pk_add_f32 v[102:103], v[102:103], 1.0 op_sel_hi:[1,0]
	v_pk_mul_f32 v[68:69], v[142:143], v[68:69]
	v_pk_mul_f32 v[70:71], v[144:145], v[70:71]
	v_pk_fma_f32 v[68:69], v[100:101], v[68:69], v[84:85]
	v_pk_fma_f32 v[70:71], v[102:103], v[70:71], v[86:87]
	v_cvt_pk_bf16_f32 v60, v68, v69
	v_cvt_pk_bf16_f32 v61, v70, v71
	global_store_dwordx2 v[30:31], v[60:61], off offset:-512
	v_pk_mul_f32 v[72:73], v[72:73], v[56:57] op_sel_hi:[1,0]
	v_pk_mul_f32 v[74:75], v[74:75], v[56:57] op_sel_hi:[1,0]
	v_pk_add_f32 v[104:105], v[104:105], 1.0 op_sel_hi:[1,0]
	v_pk_add_f32 v[106:107], v[106:107], 1.0 op_sel_hi:[1,0]
	v_pk_mul_f32 v[72:73], v[246:247], v[72:73]
	v_pk_mul_f32 v[74:75], v[248:249], v[74:75]
	v_pk_fma_f32 v[72:73], v[104:105], v[72:73], v[88:89]
	v_pk_fma_f32 v[74:75], v[106:107], v[74:75], v[90:91]
	v_cvt_pk_bf16_f32 v58, v72, v73
	v_cvt_pk_bf16_f32 v59, v74, v75
	global_store_dwordx2 v[30:31], v[58:59], off
	v_pk_mul_f32 v[76:77], v[76:77], v[56:57] op_sel_hi:[1,0]
	v_pk_mul_f32 v[78:79], v[78:79], v[56:57] op_sel_hi:[1,0]
	v_pk_add_f32 v[108:109], v[108:109], 1.0 op_sel_hi:[1,0]
	v_pk_add_f32 v[110:111], v[110:111], 1.0 op_sel_hi:[1,0]
	v_pk_mul_f32 v[76:77], v[250:251], v[76:77]
	v_pk_mul_f32 v[78:79], v[252:253], v[78:79]
	v_pk_fma_f32 v[76:77], v[108:109], v[76:77], v[92:93]
	v_pk_fma_f32 v[78:79], v[110:111], v[78:79], v[94:95]
	v_cvt_pk_bf16_f32 v60, v76, v77
	v_cvt_pk_bf16_f32 v61, v78, v79
	global_store_dwordx2 v[30:31], v[60:61], off offset:512
	v_lshl_add_u64 v[30:31], v[30:31], 0, s[16:17]
; DI void phase_norm(const Params& p, char* wsb, int layer, int which, int mrows, bool do_convert, char* lds) {
;     ...
;   for (int row = blockIdx.x * 4 + wid; row < mrows; row += nw) {
;     const float4* xr = (const float4*)(xs + (size_t)row * 1024);
;     float4 v[4];
;     float ss = 0.f;
; #pragma unroll
;     for (int i = 0; i < 4; ++i) { v[i] = xr[lane + 64 * i]; ss += v[i].x * v[i].x + v[i].y * v[i].y + v[i].z * v[i].z + v[i].w * v[i].w; }
; #pragma unroll
;     for (int o = 32; o; o >>= 1) ss += __shfl_xor(ss, o);
;     const float r = rsqrtf(ss * (1.f / 1024.f) + 1e-6f);
;     const int mr = row < TL ? (row >> 11) : 8;
;     const float* sh = mods + (size_t)mr * 9216 + (3 * which) * 1024;
;     const float* sc = sh + 1024;
; #pragma unroll
;     for (int i = 0; i < 4; ++i) {
;       int col = (lane + 64 * i) * 4;
;       float4 gg = *(const float4*)(g + col), s4 = *(const float4*)(sh + col), c4 = *(const float4*)(sc + col);
;       float o0 = v[i].x * r * gg.x * (1.f + c4.x) + s4.x;
;       float o1 = v[i].y * r * gg.y * (1.f + c4.y) + s4.y;
;       float o2 = v[i].z * r * gg.z * (1.f + c4.z) + s4.z;
;       float o3 = v[i].w * r * gg.w * (1.f + c4.w) + s4.w;
;       *(uint2*)(H + (size_t)row * 1024 + col) = make_uint2(pack2(o0, o1), pack2(o2, o3));
;     }
;   }
.Lnrm2_done:
	s_branch .LBB0_1156
.LBB0_1155:
	v_min_i32_e32 v2, 0x4000, v18
	v_ashrrev_i32_e32 v2, 11, v2
	v_mul_hi_i32_i24_e32 v3, 0x9000, v2
	v_mul_i32_i24_e32 v2, 0x9000, v2
	v_lshl_add_u64 v[2:3], s[8:9], 0, v[2:3]
	v_lshl_add_u64 v[42:43], v[2:3], 0, s[36:37]
	v_lshl_add_u64 v[38:39], v[2:3], 0, v[0:1]
	v_lshl_add_u64 v[2:3], v[42:43], 0, v[0:1]
	global_load_dwordx4 v[54:57], v[28:29], off offset:-2048
	global_load_dwordx4 v[14:17], v[20:21], off
	global_load_dwordx4 v[10:13], v[38:39], off
	s_nop 0
	global_load_dwordx4 v[2:5], v[2:3], off
	v_mov_b32_e32 v33, v1
	global_load_dwordx4 v[6:9], v[28:29], off offset:-1024
	v_lshl_add_u64 v[44:45], v[42:43], 0, v[32:33]
	v_mov_b32_e32 v35, v1
	v_mov_b32_e32 v37, v1
	v_add_u32_e32 v18, s94, v18
	s_waitcnt vmcnt(4)
	v_mov_b32_e32 v58, v55
	v_mov_b32_e32 v40, v54
	s_waitcnt vmcnt(1)
	v_pk_add_f32 v[62:63], v[2:3], 1.0 op_sel_hi:[1,0]
	v_mov_b32_e32 v2, v56
	s_waitcnt vmcnt(0)
	v_mov_b32_e32 v59, v7
	v_mov_b32_e32 v41, v6
	v_pk_mul_f32 v[58:59], v[58:59], v[58:59]
	v_mov_b32_e32 v3, v8
	v_pk_fma_f32 v[40:41], v[40:41], v[40:41], v[58:59]
	v_pk_add_f32 v[46:47], v[4:5], 1.0 op_sel_hi:[1,0]
	v_mov_b32_e32 v4, v57
	v_mov_b32_e32 v5, v9
	v_pk_fma_f32 v[2:3], v[2:3], v[2:3], v[40:41]
	global_load_dwordx4 v[58:61], v[28:29], off
	v_pk_fma_f32 v[64:65], v[4:5], v[4:5], v[2:3]
	global_load_dwordx4 v[2:5], v[28:29], off offset:1024
	v_add_f32_e32 v19, v64, v65
	v_lshl_add_u64 v[40:41], v[42:43], 0, v[34:35]
	v_lshl_add_u64 v[42:43], v[42:43], 0, v[36:37]
	v_lshl_add_u64 v[28:29], v[28:29], 0, s[54:55]
	s_waitcnt vmcnt(1)
	v_mov_b32_e32 v72, v59
	v_mov_b32_e32 v70, v58
	s_waitcnt vmcnt(0)
	v_mov_b32_e32 v73, v3
	v_mov_b32_e32 v71, v2
	v_pk_mul_f32 v[72:73], v[72:73], v[72:73]
	v_mov_b32_e32 v66, v60
	v_mov_b32_e32 v67, v4
	v_pk_fma_f32 v[70:71], v[70:71], v[70:71], v[72:73]
	v_mov_b32_e32 v68, v61
	v_mov_b32_e32 v69, v5
	v_pk_fma_f32 v[66:67], v[66:67], v[66:67], v[70:71]
	s_nop 0
	v_pk_fma_f32 v[66:67], v[68:69], v[68:69], v[66:67]
	s_nop 0
	v_add_f32_e32 v19, v19, v66
	v_add_f32_e32 v19, v19, v67
	ds_bpermute_b32 v33, v48, v19
	s_waitcnt lgkmcnt(0)
	v_add_f32_e32 v19, v19, v33
	ds_bpermute_b32 v33, v49, v19
	s_waitcnt lgkmcnt(0)
	v_add_f32_e32 v19, v19, v33
	ds_bpermute_b32 v33, v50, v19
	s_waitcnt lgkmcnt(0)
	v_add_f32_e32 v19, v19, v33
	ds_bpermute_b32 v33, v51, v19
	s_waitcnt lgkmcnt(0)
	v_add_f32_e32 v19, v19, v33
	ds_bpermute_b32 v33, v52, v19
	s_waitcnt lgkmcnt(0)
	v_add_f32_e32 v19, v19, v33
	ds_bpermute_b32 v33, v53, v19
	s_waitcnt lgkmcnt(0)
	v_add_f32_e32 v19, v19, v33
	v_fmamk_f32 v19, v19, 0x3a800000, v179
	v_cmp_gt_f32_e32 vcc, s46, v19
	v_mul_f32_e32 v33, 0x4b800000, v19
	s_nop 0
	v_cndmask_b32_e32 v19, v19, v33, vcc
	v_rsq_f32_e32 v19, v19
	s_nop 0
	v_mul_f32_e32 v33, 0x45800000, v19
	v_cndmask_b32_e32 v64, v19, v33, vcc
	v_pk_mul_f32 v[54:55], v[54:55], v[64:65] op_sel_hi:[1,0]
	v_pk_mul_f32 v[6:7], v[6:7], v[64:65] op_sel_hi:[1,0]
	v_pk_mul_f32 v[14:15], v[14:15], v[54:55]
	v_pk_mul_f32 v[8:9], v[8:9], v[64:65] op_sel_hi:[1,0]
	v_pk_fma_f32 v[10:11], v[62:63], v[14:15], v[10:11]
	v_pk_mul_f32 v[14:15], v[56:57], v[64:65] op_sel_hi:[1,0]
	v_cvt_pk_bf16_f32 v10, v10, v11
	v_pk_mul_f32 v[14:15], v[16:17], v[14:15]
	v_pk_mul_f32 v[2:3], v[2:3], v[64:65] op_sel_hi:[1,0]
	v_pk_fma_f32 v[12:13], v[46:47], v[14:15], v[12:13]
	v_pk_mul_f32 v[4:5], v[4:5], v[64:65] op_sel_hi:[1,0]
	v_cvt_pk_bf16_f32 v11, v12, v13
	global_store_dwordx2 v[30:31], v[10:11], off offset:-1024
	global_load_dwordx4 v[10:13], v[22:23], off
	s_nop 0
	global_load_dwordx4 v[14:17], v[38:39], off offset:1024
	s_nop 0
	global_load_dwordx4 v[44:47], v[44:45], off
	v_cmp_le_i32_e32 vcc, s12, v18
	s_or_b64 s[10:11], vcc, s[10:11]
	s_waitcnt vmcnt(2)
	v_pk_mul_f32 v[6:7], v[6:7], v[10:11]
	v_pk_mul_f32 v[8:9], v[8:9], v[12:13]
	s_waitcnt vmcnt(0)
	v_pk_add_f32 v[10:11], v[44:45], 1.0 op_sel_hi:[1,0]
	s_nop 0
	v_pk_fma_f32 v[6:7], v[6:7], v[10:11], v[14:15]
	v_pk_add_f32 v[10:11], v[46:47], 1.0 op_sel_hi:[1,0]
	v_cvt_pk_bf16_f32 v6, v6, v7
	v_pk_fma_f32 v[8:9], v[8:9], v[10:11], v[16:17]
	s_nop 0
	v_cvt_pk_bf16_f32 v7, v8, v9
	global_store_dwordx2 v[30:31], v[6:7], off offset:-512
	global_load_dwordx4 v[6:9], v[24:25], off
	s_nop 0
	global_load_dwordx4 v[10:13], v[38:39], off offset:2048
	global_load_dwordx4 v[14:17], v[40:41], off
	v_pk_mul_f32 v[40:41], v[58:59], v[64:65] op_sel_hi:[1,0]
	s_waitcnt vmcnt(0)
	v_pk_add_f32 v[14:15], v[14:15], 1.0 op_sel_hi:[1,0]
	v_pk_mul_f32 v[6:7], v[40:41], v[6:7]
	s_nop 0
	v_pk_fma_f32 v[6:7], v[6:7], v[14:15], v[10:11]
	v_pk_mul_f32 v[10:11], v[60:61], v[64:65] op_sel_hi:[1,0]
	v_cvt_pk_bf16_f32 v6, v6, v7
	v_pk_mul_f32 v[8:9], v[10:11], v[8:9]
	v_pk_add_f32 v[10:11], v[16:17], 1.0 op_sel_hi:[1,0]
	s_nop 0
	v_pk_fma_f32 v[8:9], v[8:9], v[10:11], v[12:13]
	s_nop 0
	v_cvt_pk_bf16_f32 v7, v8, v9
	global_store_dwordx2 v[30:31], v[6:7], off
	global_load_dwordx4 v[6:9], v[26:27], off
	s_nop 0
	global_load_dwordx4 v[10:13], v[38:39], off offset:3072
	global_load_dwordx4 v[14:17], v[42:43], off
	s_waitcnt vmcnt(2)
	v_pk_mul_f32 v[2:3], v[2:3], v[6:7]
	v_pk_mul_f32 v[4:5], v[4:5], v[8:9]
	s_waitcnt vmcnt(0)
	v_pk_add_f32 v[6:7], v[14:15], 1.0 op_sel_hi:[1,0]
	s_nop 0
	v_pk_fma_f32 v[2:3], v[2:3], v[6:7], v[10:11]
	v_pk_add_f32 v[6:7], v[16:17], 1.0 op_sel_hi:[1,0]
	v_cvt_pk_bf16_f32 v2, v2, v3
	v_pk_fma_f32 v[4:5], v[4:5], v[6:7], v[12:13]
	s_nop 0
	v_cvt_pk_bf16_f32 v3, v4, v5
	global_store_dwordx2 v[30:31], v[2:3], off offset:512
	v_lshl_add_u64 v[30:31], v[30:31], 0, s[16:17]
	s_andn2_b64 exec, exec, s[10:11]
	s_cbranch_execnz .LBB0_1155
